# post_token and MLP-up epilogue: 1/sqrt by v_rsq_f32 instead of the corrected sqrt + division sequences; remaining integer bf16 rounding sequences replaced by v_cvt_pk_bf16_f32
# speedup vs baseline: 1.4584x; 1.0027x over previous
; __device__ __forceinline__ unsigned pk2(float lo, float hi) { return f2bf(lo) | (f2bf(hi) << 16); }
;     __device__ __forceinline__ void operator()(const f32x4 (&acc)[2][2][4][2], const pg8::Unit& u, int wr, int wc, int fr, int fq) const {
;     ...
;                 if constexpr (MODE == 8) rstd = 1.f / sqrtf(rs[row] * (1.f / DM) + EPS);
;     ...
;                     } else if constexpr (MODE == 8) {
;                         const f32x4 b0 = *(const f32x4*)(vec + col), b1 = *(const f32x4*)(vec + col + 4);
;                         float r[8] = {v0[0] * rstd + b0[0], v0[1] * rstd + b0[1], v0[2] * rstd + b0[2], v0[3] * rstd + b0[3], v1[0] * rstd + b1[0], v1[1] * rstd + b1[1], v1[2] * rstd + b1[2], v1[3] * rstd + b1[3]};
; #pragma unroll
;                         for (int i = 0; i < 8; ++i) { const float q = fmaxf(r[i], 0.f); r[i] = q * q; }
;                         u32x4 w; w.x = pk2(r[0], r[1]); w.y = pk2(r[2], r[3]); w.z = pk2(r[4], r[5]); w.w = pk2(r[6], r[7]);
;                         *(u32x4*)(ob + row * HIDN + col) = w;
.LBB0_35:
	v_lshl_add_u32 v144, s9, 8, v148
	v_lshl_or_b32 v146, s8, 8, v150
	v_readlane_b32 s8, v251, 21
	v_ashrrev_i32_e32 v145, 31, v144
	v_readlane_b32 s9, v251, 22
	s_mov_b32 s10, 0xf800000
	s_nop 0
	v_lshl_add_u64 v[138:139], v[144:145], 2, s[8:9]
	global_load_dword v140, v[138:139], off
	s_waitcnt vmcnt(0)
	v_fmamk_f32 v140, v140, 0x3a000000, v205
	v_readlane_b32 s0, v251, 23
	v_readlane_b32 s1, v251, 24
	v_ashrrev_i32_e32 v147, 31, v146
	v_rsq_f32_e32 v152, v140
	v_lshl_add_u64 v[140:141], v[146:147], 2, s[0:1]
	global_load_dwordx4 v[154:157], v[140:141], off offset:16
	global_load_dwordx4 v[184:187], v[140:141], off
	v_lshlrev_b64 v[142:143], 14, v[144:145]
	s_waitcnt vmcnt(1)
	v_fma_f32 v145, v121, v152, v155
	s_waitcnt vmcnt(0)
	v_fma_f32 v124, v124, v152, v184
	v_fma_f32 v125, v125, v152, v185
	v_fma_f32 v126, v126, v152, v186
	v_fmac_f32_e32 v187, v127, v152
	v_fma_f32 v127, v120, v152, v154
	v_fmac_f32_e32 v157, v123, v152
	v_fma_f32 v153, v122, v152, v156
	v_max_f32_e32 v120, 0, v124
	v_max_f32_e32 v122, 0, v125
	v_max_f32_e32 v121, 0, v126
	v_max_f32_e32 v123, 0, v187
	v_max_f32_e32 v124, 0, v127
	v_max_f32_e32 v126, 0, v145
	v_max_f32_e32 v127, 0, v157
	v_max_f32_e32 v125, 0, v153
	v_pk_mul_f32 v[122:123], v[122:123], v[122:123]
	v_pk_mul_f32 v[126:127], v[126:127], v[126:127]
	v_pk_mul_f32 v[124:125], v[124:125], v[124:125]
	v_pk_mul_f32 v[120:121], v[120:121], v[120:121]
	v_cvt_pk_bf16_f32 v120, v120, v122
	v_cvt_pk_bf16_f32 v121, v121, v123
	v_cvt_pk_bf16_f32 v122, v124, v126
	v_cvt_pk_bf16_f32 v123, v125, v127
	v_lshl_add_u64 v[124:125], s[20:21], 0, v[142:143]
	v_lshlrev_b64 v[142:143], 1, v[146:147]
	v_lshl_add_u64 v[124:125], v[124:125], 0, v[142:143]
	global_store_dwordx4 v[124:125], v[120:123], off
	s_nop 1
	v_or_b32_e32 v120, 0x80, v146
	v_ashrrev_i32_e32 v121, 31, v120
	v_lshl_add_u64 v[126:127], v[120:121], 2, s[0:1]
	global_load_dwordx4 v[120:123], v[126:127], off offset:16
	global_load_dwordx4 v[154:157], v[126:127], off
	s_waitcnt vmcnt(1)
	v_fmac_f32_e32 v123, v115, v152
	s_waitcnt vmcnt(0)
	v_fma_f32 v116, v116, v152, v154
	v_fma_f32 v117, v117, v152, v155
	v_fma_f32 v118, v118, v152, v156
	v_fmac_f32_e32 v157, v119, v152
	v_fma_f32 v119, v112, v152, v120
	v_fma_f32 v120, v113, v152, v121
	v_fma_f32 v121, v114, v152, v122
	v_max_f32_e32 v112, 0, v116
	v_max_f32_e32 v114, 0, v117
	v_max_f32_e32 v113, 0, v118
	v_max_f32_e32 v115, 0, v157
	v_max_f32_e32 v116, 0, v119
	v_max_f32_e32 v118, 0, v120
	v_max_f32_e32 v119, 0, v123
	v_max_f32_e32 v117, 0, v121
	v_pk_mul_f32 v[114:115], v[114:115], v[114:115]
	v_pk_mul_f32 v[118:119], v[118:119], v[118:119]
	v_pk_mul_f32 v[112:113], v[112:113], v[112:113]
	v_pk_mul_f32 v[116:117], v[116:117], v[116:117]
	v_cvt_pk_bf16_f32 v112, v112, v114
	v_cvt_pk_bf16_f32 v113, v113, v115
	v_cvt_pk_bf16_f32 v114, v116, v118
	v_cvt_pk_bf16_f32 v115, v117, v119
	global_store_dwordx4 v[124:125], v[112:115], off offset:256
	s_nop 1
	v_or_b32_e32 v112, 16, v144
	v_ashrrev_i32_e32 v113, 31, v112
	v_lshl_add_u64 v[114:115], v[112:113], 2, s[8:9]
	global_load_dword v114, v[114:115], off
	v_lshlrev_b64 v[112:113], 14, v[112:113]
	s_waitcnt vmcnt(0)
	v_fmamk_f32 v114, v114, 0x3a000000, v205
	global_load_dwordx4 v[116:119], v[140:141], off offset:16
	global_load_dwordx4 v[120:123], v[140:141], off
	v_rsq_f32_e32 v114, v114
	s_waitcnt vmcnt(1)
	v_fma_f32 v115, v105, v114, v117
	s_waitcnt vmcnt(0)
	v_fma_f32 v108, v108, v114, v120
	v_fma_f32 v109, v109, v114, v121
	v_fma_f32 v110, v110, v114, v122
	v_fmac_f32_e32 v123, v111, v114
	v_fma_f32 v111, v104, v114, v116
	v_fmac_f32_e32 v119, v107, v114
	v_fma_f32 v116, v106, v114, v118
	v_max_f32_e32 v104, 0, v108
	v_max_f32_e32 v106, 0, v109
	v_max_f32_e32 v105, 0, v110
	v_max_f32_e32 v107, 0, v123
	v_max_f32_e32 v108, 0, v111
	v_max_f32_e32 v110, 0, v115
	v_max_f32_e32 v111, 0, v119
	v_max_f32_e32 v109, 0, v116
	v_pk_mul_f32 v[106:107], v[106:107], v[106:107]
	v_pk_mul_f32 v[110:111], v[110:111], v[110:111]
	v_pk_mul_f32 v[108:109], v[108:109], v[108:109]
	v_pk_mul_f32 v[104:105], v[104:105], v[104:105]
	v_cvt_pk_bf16_f32 v104, v104, v106
	v_cvt_pk_bf16_f32 v105, v105, v107
	v_cvt_pk_bf16_f32 v106, v108, v110
	v_cvt_pk_bf16_f32 v107, v109, v111
	v_lshl_add_u64 v[108:109], s[20:21], 0, v[112:113]
	v_lshl_add_u64 v[108:109], v[108:109], 0, v[142:143]
	global_store_dwordx4 v[108:109], v[104:107], off
	global_load_dwordx4 v[104:107], v[126:127], off offset:16
	s_nop 0
	global_load_dwordx4 v[110:113], v[126:127], off
	s_waitcnt vmcnt(1)
	v_fmac_f32_e32 v107, v99, v114
	s_waitcnt vmcnt(0)
	v_fma_f32 v100, v100, v114, v110
	v_fma_f32 v101, v101, v114, v111
	v_fma_f32 v102, v102, v114, v112
	v_fmac_f32_e32 v113, v103, v114
	v_fma_f32 v103, v96, v114, v104
	v_fma_f32 v104, v97, v114, v105
	v_fma_f32 v105, v98, v114, v106
	v_max_f32_e32 v96, 0, v100
	v_max_f32_e32 v98, 0, v101
	v_max_f32_e32 v97, 0, v102
	v_max_f32_e32 v99, 0, v113
	v_max_f32_e32 v100, 0, v103
	v_max_f32_e32 v102, 0, v104
	v_max_f32_e32 v103, 0, v107
	v_max_f32_e32 v101, 0, v105
	v_pk_mul_f32 v[98:99], v[98:99], v[98:99]
	v_pk_mul_f32 v[102:103], v[102:103], v[102:103]
	v_pk_mul_f32 v[96:97], v[96:97], v[96:97]
	v_pk_mul_f32 v[100:101], v[100:101], v[100:101]
	v_cvt_pk_bf16_f32 v96, v96, v98
	v_cvt_pk_bf16_f32 v97, v97, v99
	v_cvt_pk_bf16_f32 v98, v100, v102
	v_cvt_pk_bf16_f32 v99, v101, v103
	global_store_dwordx4 v[108:109], v[96:99], off offset:256
	s_nop 1
	v_or_b32_e32 v96, 32, v144
	v_ashrrev_i32_e32 v97, 31, v96
	v_lshl_add_u64 v[98:99], v[96:97], 2, s[8:9]
	global_load_dword v98, v[98:99], off
	v_lshlrev_b64 v[96:97], 14, v[96:97]
	s_waitcnt vmcnt(0)
; __device__ __forceinline__ unsigned pk2(float lo, float hi) { return f2bf(lo) | (f2bf(hi) << 16); }
;     __device__ __forceinline__ void operator()(const f32x4 (&acc)[2][2][4][2], const pg8::Unit& u, int wr, int wc, int fr, int fq) const {
;     ...
;                 if constexpr (MODE == 8) rstd = 1.f / sqrtf(rs[row] * (1.f / DM) + EPS);
;     ...
;                     } else if constexpr (MODE == 8) {
;                         const f32x4 b0 = *(const f32x4*)(vec + col), b1 = *(const f32x4*)(vec + col + 4);
;                         float r[8] = {v0[0] * rstd + b0[0], v0[1] * rstd + b0[1], v0[2] * rstd + b0[2], v0[3] * rstd + b0[3], v1[0] * rstd + b1[0], v1[1] * rstd + b1[1], v1[2] * rstd + b1[2], v1[3] * rstd + b1[3]};
; #pragma unroll
;                         for (int i = 0; i < 8; ++i) { const float q = fmaxf(r[i], 0.f); r[i] = q * q; }
;                         u32x4 w; w.x = pk2(r[0], r[1]); w.y = pk2(r[2], r[3]); w.z = pk2(r[4], r[5]); w.w = pk2(r[6], r[7]);
;                         *(u32x4*)(ob + row * HIDN + col) = w;
	v_fmamk_f32 v98, v98, 0x3a000000, v205
	global_load_dwordx4 v[100:103], v[140:141], off offset:16
	global_load_dwordx4 v[104:107], v[140:141], off
	v_rsq_f32_e32 v98, v98
	s_waitcnt vmcnt(1)
	v_fma_f32 v99, v89, v98, v101
	s_waitcnt vmcnt(0)
	v_fma_f32 v92, v92, v98, v104
	v_fma_f32 v93, v93, v98, v105
	v_fma_f32 v94, v94, v98, v106
	v_fmac_f32_e32 v107, v95, v98
	v_fma_f32 v95, v88, v98, v100
	v_fmac_f32_e32 v103, v91, v98
	v_fma_f32 v100, v90, v98, v102
	v_max_f32_e32 v88, 0, v92
	v_max_f32_e32 v90, 0, v93
	v_max_f32_e32 v89, 0, v94
	v_max_f32_e32 v91, 0, v107
	v_max_f32_e32 v92, 0, v95
	v_max_f32_e32 v94, 0, v99
	v_max_f32_e32 v95, 0, v103
	v_max_f32_e32 v93, 0, v100
	v_pk_mul_f32 v[90:91], v[90:91], v[90:91]
	v_pk_mul_f32 v[94:95], v[94:95], v[94:95]
	v_pk_mul_f32 v[92:93], v[92:93], v[92:93]
	v_pk_mul_f32 v[88:89], v[88:89], v[88:89]
	v_cvt_pk_bf16_f32 v88, v88, v90
	v_cvt_pk_bf16_f32 v89, v89, v91
	v_cvt_pk_bf16_f32 v90, v92, v94
	v_cvt_pk_bf16_f32 v91, v93, v95
	v_lshl_add_u64 v[92:93], s[20:21], 0, v[96:97]
	v_lshl_add_u64 v[92:93], v[92:93], 0, v[142:143]
	global_store_dwordx4 v[92:93], v[88:91], off
	global_load_dwordx4 v[88:91], v[126:127], off offset:16
	s_nop 0
	global_load_dwordx4 v[94:97], v[126:127], off
	s_waitcnt vmcnt(1)
	v_fmac_f32_e32 v91, v83, v98
	s_waitcnt vmcnt(0)
	v_fma_f32 v84, v84, v98, v94
	v_fma_f32 v85, v85, v98, v95
	v_fma_f32 v86, v86, v98, v96
	v_fmac_f32_e32 v97, v87, v98
	v_fma_f32 v87, v80, v98, v88
	v_fma_f32 v88, v81, v98, v89
	v_fma_f32 v89, v82, v98, v90
	v_max_f32_e32 v80, 0, v84
	v_max_f32_e32 v82, 0, v85
	v_max_f32_e32 v81, 0, v86
	v_max_f32_e32 v83, 0, v97
	v_max_f32_e32 v84, 0, v87
	v_max_f32_e32 v86, 0, v88
	v_max_f32_e32 v87, 0, v91
	v_max_f32_e32 v85, 0, v89
	v_pk_mul_f32 v[82:83], v[82:83], v[82:83]
	v_pk_mul_f32 v[86:87], v[86:87], v[86:87]
	v_pk_mul_f32 v[80:81], v[80:81], v[80:81]
	v_pk_mul_f32 v[84:85], v[84:85], v[84:85]
	v_cvt_pk_bf16_f32 v80, v80, v82
	v_cvt_pk_bf16_f32 v81, v81, v83
	v_cvt_pk_bf16_f32 v82, v84, v86
	v_cvt_pk_bf16_f32 v83, v85, v87
	global_store_dwordx4 v[92:93], v[80:83], off offset:256
	s_nop 1
	v_or_b32_e32 v80, 48, v144
	v_ashrrev_i32_e32 v81, 31, v80
	v_lshl_add_u64 v[82:83], v[80:81], 2, s[8:9]
	global_load_dword v82, v[82:83], off
	v_lshlrev_b64 v[80:81], 14, v[80:81]
	s_waitcnt vmcnt(0)
	v_fmamk_f32 v82, v82, 0x3a000000, v205
	global_load_dwordx4 v[84:87], v[140:141], off offset:16
	global_load_dwordx4 v[88:91], v[140:141], off
	v_rsq_f32_e32 v82, v82
	s_waitcnt vmcnt(1)
	v_fma_f32 v83, v73, v82, v85
	s_waitcnt vmcnt(0)
	v_fma_f32 v76, v76, v82, v88
	v_fma_f32 v77, v77, v82, v89
	v_fma_f32 v78, v78, v82, v90
	v_fmac_f32_e32 v91, v79, v82
	v_fma_f32 v79, v72, v82, v84
	v_fmac_f32_e32 v87, v75, v82
	v_fma_f32 v84, v74, v82, v86
	v_max_f32_e32 v72, 0, v76
	v_max_f32_e32 v74, 0, v77
	v_max_f32_e32 v73, 0, v78
	v_max_f32_e32 v75, 0, v91
	v_max_f32_e32 v76, 0, v79
	v_max_f32_e32 v78, 0, v83
	v_max_f32_e32 v79, 0, v87
	v_max_f32_e32 v77, 0, v84
	v_pk_mul_f32 v[74:75], v[74:75], v[74:75]
	v_pk_mul_f32 v[78:79], v[78:79], v[78:79]
	v_pk_mul_f32 v[76:77], v[76:77], v[76:77]
	v_pk_mul_f32 v[72:73], v[72:73], v[72:73]
	v_cvt_pk_bf16_f32 v72, v72, v74
	v_cvt_pk_bf16_f32 v73, v73, v75
	v_cvt_pk_bf16_f32 v74, v76, v78
	v_cvt_pk_bf16_f32 v75, v77, v79
	v_lshl_add_u64 v[76:77], s[20:21], 0, v[80:81]
	v_lshl_add_u64 v[76:77], v[76:77], 0, v[142:143]
	global_store_dwordx4 v[76:77], v[72:75], off
	global_load_dwordx4 v[72:75], v[126:127], off offset:16
	s_nop 0
	global_load_dwordx4 v[78:81], v[126:127], off
	s_waitcnt vmcnt(1)
	v_fmac_f32_e32 v75, v67, v82
	s_waitcnt vmcnt(0)
	v_fma_f32 v68, v68, v82, v78
	v_fma_f32 v69, v69, v82, v79
	v_fma_f32 v70, v70, v82, v80
	v_fmac_f32_e32 v81, v71, v82
	v_fma_f32 v71, v64, v82, v72
	v_fma_f32 v72, v65, v82, v73
	v_fma_f32 v73, v66, v82, v74
	v_max_f32_e32 v64, 0, v68
	v_max_f32_e32 v66, 0, v69
	v_max_f32_e32 v65, 0, v70
	v_max_f32_e32 v67, 0, v81
	v_max_f32_e32 v68, 0, v71
	v_max_f32_e32 v70, 0, v72
	v_max_f32_e32 v71, 0, v75
	v_max_f32_e32 v69, 0, v73
	v_pk_mul_f32 v[66:67], v[66:67], v[66:67]
	v_pk_mul_f32 v[70:71], v[70:71], v[70:71]
	v_pk_mul_f32 v[64:65], v[64:65], v[64:65]
	v_pk_mul_f32 v[68:69], v[68:69], v[68:69]
	v_cvt_pk_bf16_f32 v64, v64, v66
	v_cvt_pk_bf16_f32 v65, v65, v67
	v_cvt_pk_bf16_f32 v66, v68, v70
	v_cvt_pk_bf16_f32 v67, v69, v71
	global_store_dwordx4 v[76:77], v[64:67], off offset:256
	global_load_dword v64, v[138:139], off offset:512
	s_waitcnt vmcnt(0)
	v_fmamk_f32 v64, v64, 0x3a000000, v205
	s_mov_b64 s[0:1], 0x200000
	global_load_dwordx4 v[66:69], v[140:141], off offset:16
	global_load_dwordx4 v[70:73], v[140:141], off
	v_rsq_f32_e32 v64, v64
	s_waitcnt vmcnt(1)
	v_fma_f32 v65, v57, v64, v67
	s_waitcnt vmcnt(0)
	v_fma_f32 v60, v60, v64, v70
	v_fma_f32 v61, v61, v64, v71
	v_fma_f32 v62, v62, v64, v72
	v_fmac_f32_e32 v73, v63, v64
	v_fma_f32 v63, v56, v64, v66
	v_fmac_f32_e32 v69, v59, v64
	v_fma_f32 v66, v58, v64, v68
	v_max_f32_e32 v56, 0, v60
	v_max_f32_e32 v58, 0, v61
	v_max_f32_e32 v57, 0, v62
	v_max_f32_e32 v59, 0, v73
	v_max_f32_e32 v60, 0, v63
	v_max_f32_e32 v62, 0, v65
	v_max_f32_e32 v63, 0, v69
	v_max_f32_e32 v61, 0, v66
	v_pk_mul_f32 v[58:59], v[58:59], v[58:59]
	v_pk_mul_f32 v[62:63], v[62:63], v[62:63]
	v_pk_mul_f32 v[60:61], v[60:61], v[60:61]
	v_bfe_u32 v67, v59, 16, 1
	v_bfe_u32 v68, v58, 16, 1
	v_add3_u32 v68, v58, v68, s33
	v_add3_u32 v67, v59, v67, s33
	v_pk_mul_f32 v[56:57], v[56:57], v[56:57]
	v_cvt_pk_bf16_f32 v59, v61, v63
	v_cvt_pk_bf16_f32 v58, v60, v62
	v_bfe_u32 v62, v56, 16, 1
	v_bfe_u32 v63, v57, 16, 1
	v_add3_u32 v57, v57, v63, s33
	v_add3_u32 v56, v56, v62, s33
	v_lshl_add_u64 v[60:61], v[124:125], 0, s[0:1]
	s_mov_b32 s0, 0x200000
	v_lshrrev_b32_e32 v56, 16, v56
	v_lshrrev_b32_e32 v57, 16, v57
	v_add_co_u32_e32 v62, vcc, s0, v124
	v_and_or_b32 v57, v67, s67, v57
	v_and_or_b32 v56, v68, s67, v56
	v_addc_co_u32_e32 v63, vcc, 0, v125, vcc
	global_store_dwordx4 v[62:63], v[56:59], off
	global_load_dwordx4 v[56:59], v[126:127], off offset:16
	s_nop 0
	global_load_dwordx4 v[66:69], v[126:127], off
	s_waitcnt vmcnt(1)
; __device__ __forceinline__ unsigned pk2(float lo, float hi) { return f2bf(lo) | (f2bf(hi) << 16); }
;     __device__ __forceinline__ void operator()(const f32x4 (&acc)[2][2][4][2], const pg8::Unit& u, int wr, int wc, int fr, int fq) const {
;     ...
;                 if constexpr (MODE == 8) rstd = 1.f / sqrtf(rs[row] * (1.f / DM) + EPS);
;     ...
;                     } else if constexpr (MODE == 8) {
;                         const f32x4 b0 = *(const f32x4*)(vec + col), b1 = *(const f32x4*)(vec + col + 4);
;                         float r[8] = {v0[0] * rstd + b0[0], v0[1] * rstd + b0[1], v0[2] * rstd + b0[2], v0[3] * rstd + b0[3], v1[0] * rstd + b1[0], v1[1] * rstd + b1[1], v1[2] * rstd + b1[2], v1[3] * rstd + b1[3]};
; #pragma unroll
;                         for (int i = 0; i < 8; ++i) { const float q = fmaxf(r[i], 0.f); r[i] = q * q; }
;                         u32x4 w; w.x = pk2(r[0], r[1]); w.y = pk2(r[2], r[3]); w.z = pk2(r[4], r[5]); w.w = pk2(r[6], r[7]);
;                         *(u32x4*)(ob + row * HIDN + col) = w;
	v_fmac_f32_e32 v59, v51, v64
	s_waitcnt vmcnt(0)
	v_fma_f32 v52, v52, v64, v66
	v_fma_f32 v53, v53, v64, v67
	v_fma_f32 v54, v54, v64, v68
	v_fmac_f32_e32 v69, v55, v64
	v_fma_f32 v55, v48, v64, v56
	v_fma_f32 v56, v49, v64, v57
	v_fma_f32 v57, v50, v64, v58
	v_max_f32_e32 v48, 0, v52
	v_max_f32_e32 v50, 0, v53
	v_max_f32_e32 v49, 0, v54
	v_max_f32_e32 v51, 0, v69
	v_max_f32_e32 v52, 0, v55
	v_max_f32_e32 v54, 0, v56
	v_max_f32_e32 v55, 0, v59
	v_max_f32_e32 v53, 0, v57
	v_pk_mul_f32 v[50:51], v[50:51], v[50:51]
	v_pk_mul_f32 v[54:55], v[54:55], v[54:55]
	v_pk_mul_f32 v[48:49], v[48:49], v[48:49]
	v_pk_mul_f32 v[52:53], v[52:53], v[52:53]
	v_cvt_pk_bf16_f32 v48, v48, v50
	v_cvt_pk_bf16_f32 v49, v49, v51
	v_cvt_pk_bf16_f32 v50, v52, v54
	v_cvt_pk_bf16_f32 v51, v53, v55
	global_store_dwordx4 v[60:61], v[48:51], off offset:256
	global_load_dword v48, v[138:139], off offset:576
	s_waitcnt vmcnt(0)
	v_fmamk_f32 v48, v48, 0x3a000000, v205
	s_mov_b64 s[0:1], 0x240000
	global_load_dwordx4 v[50:53], v[140:141], off offset:16
	global_load_dwordx4 v[54:57], v[140:141], off
	v_rsq_f32_e32 v48, v48
	s_waitcnt vmcnt(1)
	v_fma_f32 v49, v41, v48, v51
	s_waitcnt vmcnt(0)
	v_fma_f32 v44, v44, v48, v54
	v_fma_f32 v45, v45, v48, v55
	v_fma_f32 v46, v46, v48, v56
	v_fmac_f32_e32 v57, v47, v48
	v_fma_f32 v47, v40, v48, v50
	v_fmac_f32_e32 v53, v43, v48
	v_fma_f32 v50, v42, v48, v52
	v_max_f32_e32 v40, 0, v44
	v_max_f32_e32 v42, 0, v45
	v_max_f32_e32 v41, 0, v46
	v_max_f32_e32 v43, 0, v57
	v_max_f32_e32 v44, 0, v47
	v_max_f32_e32 v46, 0, v49
	v_max_f32_e32 v47, 0, v53
	v_max_f32_e32 v45, 0, v50
	v_pk_mul_f32 v[42:43], v[42:43], v[42:43]
	v_pk_mul_f32 v[46:47], v[46:47], v[46:47]
	v_pk_mul_f32 v[44:45], v[44:45], v[44:45]
	v_bfe_u32 v51, v43, 16, 1
	v_bfe_u32 v52, v42, 16, 1
	v_add3_u32 v52, v42, v52, s33
	v_add3_u32 v51, v43, v51, s33
	v_pk_mul_f32 v[40:41], v[40:41], v[40:41]
	v_cvt_pk_bf16_f32 v43, v45, v47
	v_cvt_pk_bf16_f32 v42, v44, v46
	v_bfe_u32 v46, v40, 16, 1
	v_bfe_u32 v47, v41, 16, 1
	v_add3_u32 v41, v41, v47, s33
	v_add3_u32 v40, v40, v46, s33
	v_lshl_add_u64 v[44:45], v[124:125], 0, s[0:1]
	s_mov_b32 s0, 0x240000
	v_lshrrev_b32_e32 v40, 16, v40
	v_lshrrev_b32_e32 v41, 16, v41
	v_add_co_u32_e32 v46, vcc, s0, v124
	v_and_or_b32 v41, v51, s67, v41
	v_and_or_b32 v40, v52, s67, v40
	v_addc_co_u32_e32 v47, vcc, 0, v125, vcc
	global_store_dwordx4 v[46:47], v[40:43], off
	global_load_dwordx4 v[40:43], v[126:127], off offset:16
	s_nop 0
	global_load_dwordx4 v[50:53], v[126:127], off
	s_waitcnt vmcnt(1)
	v_fmac_f32_e32 v43, v35, v48
	s_waitcnt vmcnt(0)
	v_fma_f32 v36, v36, v48, v50
	v_fma_f32 v37, v37, v48, v51
	v_fma_f32 v38, v38, v48, v52
	v_fmac_f32_e32 v53, v39, v48
	v_fma_f32 v39, v32, v48, v40
	v_fma_f32 v40, v33, v48, v41
	v_fma_f32 v41, v34, v48, v42
	v_max_f32_e32 v32, 0, v36
	v_max_f32_e32 v34, 0, v37
	v_max_f32_e32 v33, 0, v38
	v_max_f32_e32 v35, 0, v53
	v_max_f32_e32 v36, 0, v39
	v_max_f32_e32 v38, 0, v40
	v_max_f32_e32 v39, 0, v43
	v_max_f32_e32 v37, 0, v41
	v_pk_mul_f32 v[34:35], v[34:35], v[34:35]
	v_pk_mul_f32 v[38:39], v[38:39], v[38:39]
	v_pk_mul_f32 v[32:33], v[32:33], v[32:33]
	v_pk_mul_f32 v[36:37], v[36:37], v[36:37]
	v_cvt_pk_bf16_f32 v32, v32, v34
	v_cvt_pk_bf16_f32 v33, v33, v35
	v_cvt_pk_bf16_f32 v34, v36, v38
	v_cvt_pk_bf16_f32 v35, v37, v39
	global_store_dwordx4 v[44:45], v[32:35], off offset:256
	global_load_dword v32, v[138:139], off offset:640
	s_waitcnt vmcnt(0)
	v_fmamk_f32 v32, v32, 0x3a000000, v205
	s_mov_b64 s[0:1], 0x280000
	global_load_dwordx4 v[34:37], v[140:141], off offset:16
	global_load_dwordx4 v[38:41], v[140:141], off
	v_rsq_f32_e32 v32, v32
	s_waitcnt vmcnt(1)
	v_fma_f32 v33, v25, v32, v35
	s_waitcnt vmcnt(0)
;     __device__ __forceinline__ void operator()(const f32x4 (&acc)[2][2][4][2], const pg8::Unit& u, int wr, int wc, int fr, int fq) const {
;     ...
;                 const size_t row = (size_t)(row0 + ai * 128 + m * 16);
;                 float ssq = 0.f, rstd = 1.f;
;                 if constexpr (MODE == 8) rstd = 1.f / sqrtf(rs[row] * (1.f / DM) + EPS);
; #pragma unroll
;                 for (int bj = 0; bj < 2; ++bj) {
;                     const int col = col0 + bj * 128;
;                     f32x4 v0 = acc[ai][bj][m][0], v1 = acc[ai][bj][m][1];
;                     if constexpr (MODE == 0 || MODE == 1) { v0 = v0 * scale; v1 = v1 * scale; }
;                     if constexpr (MODE == 6) { float* p = of + row * IDXW + col; *(f32x4*)p = v0; *(f32x4*)(p + 4) = v1; }
;                     else if constexpr (MODE == 0) {
;                         if (u.pn >= COL_BV / 256) {
;                             const float x8[8] = {v0[0], v0[1], v0[2], v0[3], v1[0], v1[1], v1[2], v1[3]};
;                             *(u32x2*)((unsigned char*)aux + row * 1024 + (col - COL_BV)) = to_fp8x8(x8);
;                         } else { u32x4 w; w.x = pk2(v0[0], v0[1]); w.y = pk2(v0[2], v0[3]); w.z = pk2(v1[0], v1[1]); w.w = pk2(v1[2], v1[3]);
;                             *(u32x4*)(ob + row * QKVW + col) = w; }
;                     } else if constexpr (MODE == 1) {
;                         const f32x4 b0 = *(const f32x4*)(vec + col), b1 = *(const f32x4*)(vec + col + 4);
;                         float r[8];
; #pragma unroll
;                         for (int i = 0; i < 4; ++i) { r[i] = 1.f / (1.f + __expf(-(v0[i] + b0[i]))); r[4 + i] = 1.f / (1.f + __expf(-(v1[i] + b1[i]))); }
;                         u32x4 w; w.x = pk2(r[0], r[1]); w.y = pk2(r[2], r[3]); w.z = pk2(r[4], r[5]); w.w = pk2(r[6], r[7]);
;                         *(u32x4*)(ob + row * 4096 + col) = w;
;                     } else if constexpr (MODE == 2 || MODE == 3) {
;                         const u32x4 g = *(const u32x4*)(aux + row * 4096 + (MODE == 3 ? 2048 : 0) + col);
;                         float r[8] = {v0[0], v0[1], v0[2], v0[3], v1[0], v1[1], v1[2], v1[3]};
;                         const unsigned gw[4] = {g.x, g.y, g.z, g.w};
; #pragma unroll
;                         for (int i = 0; i < 4; ++i) { r[2 * i] *= bf2f(gw[i] & 0xffffu); r[2 * i + 1] *= __builtin_bit_cast(float, gw[i] & 0xffff0000u); }
	v_fma_f32 v28, v28, v32, v38
	v_fma_f32 v29, v29, v32, v39
	v_fma_f32 v30, v30, v32, v40
	v_fmac_f32_e32 v41, v31, v32
	v_fma_f32 v31, v24, v32, v34
	v_fmac_f32_e32 v37, v27, v32
	v_fma_f32 v34, v26, v32, v36
	v_max_f32_e32 v24, 0, v28
	v_max_f32_e32 v26, 0, v29
	v_max_f32_e32 v25, 0, v30
	v_max_f32_e32 v27, 0, v41
	v_max_f32_e32 v28, 0, v31
	v_max_f32_e32 v30, 0, v33
	v_max_f32_e32 v31, 0, v37
	v_max_f32_e32 v29, 0, v34
	v_pk_mul_f32 v[26:27], v[26:27], v[26:27]
	v_pk_mul_f32 v[30:31], v[30:31], v[30:31]
	v_pk_mul_f32 v[28:29], v[28:29], v[28:29]
	v_bfe_u32 v35, v27, 16, 1
	v_bfe_u32 v36, v26, 16, 1
	v_add3_u32 v36, v26, v36, s33
	v_add3_u32 v35, v27, v35, s33
	v_pk_mul_f32 v[24:25], v[24:25], v[24:25]
	v_cvt_pk_bf16_f32 v27, v29, v31
	v_cvt_pk_bf16_f32 v26, v28, v30
	v_bfe_u32 v30, v24, 16, 1
	v_bfe_u32 v31, v25, 16, 1
	v_add3_u32 v25, v25, v31, s33
	v_add3_u32 v24, v24, v30, s33
	v_lshl_add_u64 v[28:29], v[124:125], 0, s[0:1]
	s_mov_b32 s0, 0x280000
	v_lshrrev_b32_e32 v24, 16, v24
	v_lshrrev_b32_e32 v25, 16, v25
	v_add_co_u32_e32 v30, vcc, s0, v124
	v_and_or_b32 v25, v35, s67, v25
	v_and_or_b32 v24, v36, s67, v24
	v_addc_co_u32_e32 v31, vcc, 0, v125, vcc
	global_store_dwordx4 v[30:31], v[24:27], off
	global_load_dwordx4 v[24:27], v[126:127], off offset:16
	s_nop 0
	global_load_dwordx4 v[34:37], v[126:127], off
	s_waitcnt vmcnt(1)
	v_fmac_f32_e32 v27, v19, v32
	s_waitcnt vmcnt(0)
	v_fma_f32 v20, v20, v32, v34
	v_fma_f32 v21, v21, v32, v35
	v_fma_f32 v22, v22, v32, v36
	v_fmac_f32_e32 v37, v23, v32
	v_fma_f32 v23, v16, v32, v24
	v_fma_f32 v24, v17, v32, v25
	v_fma_f32 v25, v18, v32, v26
	v_max_f32_e32 v16, 0, v20
	v_max_f32_e32 v18, 0, v21
	v_max_f32_e32 v17, 0, v22
	v_max_f32_e32 v19, 0, v37
	v_max_f32_e32 v20, 0, v23
	v_max_f32_e32 v22, 0, v24
	v_max_f32_e32 v23, 0, v27
	v_max_f32_e32 v21, 0, v25
	v_pk_mul_f32 v[18:19], v[18:19], v[18:19]
	v_pk_mul_f32 v[22:23], v[22:23], v[22:23]
	v_pk_mul_f32 v[16:17], v[16:17], v[16:17]
	v_pk_mul_f32 v[20:21], v[20:21], v[20:21]
	v_cvt_pk_bf16_f32 v16, v16, v18
	v_cvt_pk_bf16_f32 v17, v17, v19
	v_cvt_pk_bf16_f32 v18, v20, v22
	v_cvt_pk_bf16_f32 v19, v21, v23
	global_store_dwordx4 v[28:29], v[16:19], off offset:256
	global_load_dword v16, v[138:139], off offset:704
	s_waitcnt vmcnt(0)
	v_fmamk_f32 v16, v16, 0x3a000000, v205
	s_mov_b64 s[0:1], 0x2c0000
	global_load_dwordx4 v[18:21], v[140:141], off offset:16
	global_load_dwordx4 v[22:25], v[140:141], off
	v_rsq_f32_e32 v16, v16
	s_waitcnt vmcnt(1)
	v_fma_f32 v17, v9, v16, v19
	s_waitcnt vmcnt(0)
	v_fma_f32 v12, v12, v16, v22
	v_fma_f32 v13, v13, v16, v23
	v_fma_f32 v14, v14, v16, v24
	v_fmac_f32_e32 v25, v15, v16
	v_fma_f32 v15, v8, v16, v18
	v_fmac_f32_e32 v21, v11, v16
	v_fma_f32 v18, v10, v16, v20
	v_max_f32_e32 v8, 0, v12
	v_max_f32_e32 v10, 0, v13
	v_max_f32_e32 v9, 0, v14
	v_max_f32_e32 v11, 0, v25
	v_max_f32_e32 v12, 0, v15
	v_max_f32_e32 v14, 0, v17
	v_max_f32_e32 v15, 0, v21
	v_max_f32_e32 v13, 0, v18
	v_pk_mul_f32 v[10:11], v[10:11], v[10:11]
	v_pk_mul_f32 v[14:15], v[14:15], v[14:15]
	v_pk_mul_f32 v[12:13], v[12:13], v[12:13]
	v_bfe_u32 v19, v11, 16, 1
	v_bfe_u32 v20, v10, 16, 1
	v_add3_u32 v20, v10, v20, s33
	v_add3_u32 v19, v11, v19, s33
	v_pk_mul_f32 v[8:9], v[8:9], v[8:9]
	v_cvt_pk_bf16_f32 v11, v13, v15
	v_cvt_pk_bf16_f32 v10, v12, v14
	v_bfe_u32 v14, v8, 16, 1
	v_bfe_u32 v15, v9, 16, 1
	v_add3_u32 v9, v9, v15, s33
	v_add3_u32 v8, v8, v14, s33
	v_lshl_add_u64 v[12:13], v[124:125], 0, s[0:1]
	s_mov_b32 s0, 0x2c0000
	v_lshrrev_b32_e32 v8, 16, v8
	v_lshrrev_b32_e32 v9, 16, v9
	v_add_co_u32_e32 v14, vcc, s0, v124
	v_and_or_b32 v9, v19, s67, v9
	v_and_or_b32 v8, v20, s67, v8
	v_addc_co_u32_e32 v15, vcc, 0, v125, vcc
	global_store_dwordx4 v[14:15], v[8:11], off
	global_load_dwordx4 v[8:11], v[126:127], off offset:16
	s_nop 0
	global_load_dwordx4 v[18:21], v[126:127], off
	s_mov_b64 s[0:1], -1
	s_andn2_b64 vcc, exec, s[38:39]
	s_waitcnt vmcnt(1)
	v_fmac_f32_e32 v11, v3, v16
	s_waitcnt vmcnt(0)
	v_fma_f32 v4, v4, v16, v18
	v_fma_f32 v5, v5, v16, v19
	v_fma_f32 v6, v6, v16, v20
	v_fmac_f32_e32 v21, v7, v16
	v_fma_f32 v7, v0, v16, v8
	v_fma_f32 v8, v1, v16, v9
	v_fma_f32 v9, v2, v16, v10
	v_max_f32_e32 v0, 0, v4
	v_max_f32_e32 v2, 0, v5
	v_max_f32_e32 v1, 0, v6
	v_max_f32_e32 v3, 0, v21
	v_max_f32_e32 v4, 0, v7
	v_max_f32_e32 v6, 0, v8
	v_max_f32_e32 v7, 0, v11
	v_max_f32_e32 v5, 0, v9
	v_pk_mul_f32 v[2:3], v[2:3], v[2:3]
	v_pk_mul_f32 v[6:7], v[6:7], v[6:7]
	v_pk_mul_f32 v[0:1], v[0:1], v[0:1]
	v_pk_mul_f32 v[4:5], v[4:5], v[4:5]
	v_cvt_pk_bf16_f32 v0, v0, v2
	v_cvt_pk_bf16_f32 v1, v1, v3
	v_cvt_pk_bf16_f32 v2, v4, v6
	v_cvt_pk_bf16_f32 v3, v5, v7
	global_store_dwordx4 v[12:13], v[0:3], off offset:256
	s_cbranch_vccnz .LBB0_24
	s_andn2_b64 vcc, exec, s[42:43]
	s_cbranch_vccnz .LBB0_23
	s_barrier
	s_branch .LBB0_23

; __device__ __forceinline__ unsigned pk2(float lo, float hi) { return f2bf(lo) | (f2bf(hi) << 16); }
; __device__ __forceinline__ void dilated_merge(const bf16_t* OG, const float* LSE, bf16_t* OA, int t, int hs, int lane) {
;     const float l0 = LSE[(size_t)t * 12 + hs], l1 = LSE[(size_t)t * 12 + 4 + hs], l2 = LSE[(size_t)t * 12 + 8 + hs];
;     const float mx = fmaxf(l0, fmaxf(l1, l2)); float w0 = __expf(l0 - mx), w1 = __expf(l1 - mx), w2 = __expf(l2 - mx);
;     const float inv = 1.f / (w0 + w1 + w2); w0 *= inv; w1 *= inv; w2 *= inv;
;     const size_t off = (size_t)t * 512 + hs * 128 + 2 * lane;
;     const unsigned v0 = *(const unsigned*)(OG + off), v1 = *(const unsigned*)(OG + (size_t)SEQ * 512 + off), v2 = *(const unsigned*)(OG + (size_t)2 * SEQ * 512 + off);
;     const float o0 = w0 * bf2f(v0 & 0xffffu) + w1 * bf2f(v1 & 0xffffu) + w2 * bf2f(v2 & 0xffffu);
;     const float o1 = w0 * __builtin_bit_cast(float, v0 & 0xffff0000u) + w1 * __builtin_bit_cast(float, v1 & 0xffff0000u) + w2 * __builtin_bit_cast(float, v2 & 0xffff0000u);
;     *(unsigned*)(OA + off) = pk2(o0, o1);
.Lmg_ld_done:
	s_waitcnt vmcnt(0)
	v_max3_f32 v25, v21, v23, v24
	v_sub_f32_e32 v21, v21, v25
	v_mul_f32_e32 v21, 0x3fb8aa3b, v21
	v_exp_f32_e32 v22, v21
	v_sub_f32_e32 v21, v23, v25
	v_mul_f32_e32 v21, 0x3fb8aa3b, v21
	v_exp_f32_e32 v23, v21
	v_sub_f32_e32 v21, v24, v25
	v_mul_f32_e32 v21, 0x3fb8aa3b, v21
	v_exp_f32_e32 v21, v21
	v_add_f32_e32 v24, v22, v23
	v_add_f32_e32 v24, v21, v24
	v_div_scale_f32 v25, s[10:11], v24, v24, 1.0
	v_rcp_f32_e32 v26, v25
	s_nop 0
	v_fma_f32 v27, -v25, v26, 1.0
	v_fmac_f32_e32 v26, v27, v26
	v_div_scale_f32 v27, vcc, 1.0, v24, 1.0
	v_mul_f32_e32 v28, v27, v26
	v_fma_f32 v29, -v25, v28, v27
	v_fmac_f32_e32 v28, v29, v26
	v_fma_f32 v25, -v25, v28, v27
	v_div_fmas_f32 v25, v25, v26, v28
	s_nop 0
	v_div_fixup_f32 v24, v25, v24, 1.0
	v_mul_f32_e32 v26, v21, v24
	v_mov_b32_e32 v21, v34
	v_mov_b32_e32 v27, v35
	v_mov_b32_e32 v25, v36
	v_lshlrev_b32_e32 v32, 16, v21
	v_and_b32_e32 v33, 0xffff0000, v27
	v_lshlrev_b32_e32 v30, 16, v25
	v_and_b32_e32 v31, 0xffff0000, v25
	v_pk_mul_f32 v[22:23], v[22:23], v[24:25] op_sel_hi:[1,0]
	v_and_b32_e32 v24, 0xffff0000, v21
	v_lshlrev_b32_e32 v25, 16, v27
	v_pk_mul_f32 v[24:25], v[22:23], v[24:25]
	s_nop 0
	v_pk_fma_f32 v[22:23], v[22:23], v[32:33], v[24:25] op_sel:[0,0,1] op_sel_hi:[1,1,0]
	s_nop 0
	v_pk_fma_f32 v[22:23], v[26:27], v[30:31], v[22:23] op_sel_hi:[0,1,1]
	v_cvt_pk_bf16_f32 v21, v22, v23
	v_lshl_add_u64 v[22:23], s[62:63], 0, v[38:39]
	global_store_dword v[22:23], v21, off
	s_cmp_lt_u32 s101, 2
	s_cbranch_scc1 .Lmg_cp_done
	v_max3_f32 v45, v41, v43, v44
	v_sub_f32_e32 v41, v41, v45
	v_mul_f32_e32 v41, 0x3fb8aa3b, v41
	v_exp_f32_e32 v42, v41
	v_sub_f32_e32 v41, v43, v45
	v_mul_f32_e32 v41, 0x3fb8aa3b, v41
	v_exp_f32_e32 v43, v41
	v_sub_f32_e32 v41, v44, v45
	v_mul_f32_e32 v41, 0x3fb8aa3b, v41
	v_exp_f32_e32 v41, v41
	v_add_f32_e32 v44, v42, v43
	v_add_f32_e32 v44, v41, v44
	v_div_scale_f32 v45, s[10:11], v44, v44, 1.0
	v_rcp_f32_e32 v46, v45
	s_nop 0
	v_fma_f32 v47, -v45, v46, 1.0
	v_fmac_f32_e32 v46, v47, v46
	v_div_scale_f32 v47, vcc, 1.0, v44, 1.0
	v_mul_f32_e32 v48, v47, v46
	v_fma_f32 v49, -v45, v48, v47
	v_fmac_f32_e32 v48, v49, v46
	v_fma_f32 v45, -v45, v48, v47
	v_div_fmas_f32 v45, v45, v46, v48
	s_nop 0
	v_div_fixup_f32 v44, v45, v44, 1.0
	v_mul_f32_e32 v46, v41, v44
	v_mov_b32_e32 v41, v54
	v_mov_b32_e32 v47, v55
	v_mov_b32_e32 v45, v56
	v_lshlrev_b32_e32 v52, 16, v41
	v_and_b32_e32 v53, 0xffff0000, v47
	v_lshlrev_b32_e32 v50, 16, v45
	v_and_b32_e32 v51, 0xffff0000, v45
	v_pk_mul_f32 v[42:43], v[42:43], v[44:45] op_sel_hi:[1,0]
	v_and_b32_e32 v44, 0xffff0000, v41
	v_lshlrev_b32_e32 v45, 16, v47
	v_pk_mul_f32 v[44:45], v[42:43], v[44:45]
	s_nop 0
	v_pk_fma_f32 v[42:43], v[42:43], v[52:53], v[44:45] op_sel:[0,0,1] op_sel_hi:[1,1,0]
	s_nop 0
	v_pk_fma_f32 v[42:43], v[46:47], v[50:51], v[42:43] op_sel_hi:[0,1,1]
	v_cvt_pk_bf16_f32 v41, v42, v43
	v_lshl_add_u64 v[42:43], s[62:63], 0, v[58:59]
	global_store_dword v[42:43], v41, off
	s_cmp_lt_u32 s101, 3
	s_cbranch_scc1 .Lmg_cp_done
	v_max3_f32 v65, v61, v63, v64
	v_sub_f32_e32 v61, v61, v65
	v_mul_f32_e32 v61, 0x3fb8aa3b, v61
	v_exp_f32_e32 v62, v61
	v_sub_f32_e32 v61, v63, v65
	v_mul_f32_e32 v61, 0x3fb8aa3b, v61
	v_exp_f32_e32 v63, v61
	v_sub_f32_e32 v61, v64, v65
	v_mul_f32_e32 v61, 0x3fb8aa3b, v61
	v_exp_f32_e32 v61, v61
	v_add_f32_e32 v64, v62, v63
	v_add_f32_e32 v64, v61, v64
	v_div_scale_f32 v65, s[10:11], v64, v64, 1.0
	v_rcp_f32_e32 v66, v65
	s_nop 0
	v_fma_f32 v67, -v65, v66, 1.0
	v_fmac_f32_e32 v66, v67, v66
	v_div_scale_f32 v67, vcc, 1.0, v64, 1.0
	v_mul_f32_e32 v68, v67, v66
	v_fma_f32 v69, -v65, v68, v67
	v_fmac_f32_e32 v68, v69, v66
	v_fma_f32 v65, -v65, v68, v67
	v_div_fmas_f32 v65, v65, v66, v68
	s_nop 0
	v_div_fixup_f32 v64, v65, v64, 1.0
	v_mul_f32_e32 v66, v61, v64
	v_mov_b32_e32 v61, v74
	v_mov_b32_e32 v67, v75
	v_mov_b32_e32 v65, v76
	v_lshlrev_b32_e32 v72, 16, v61
	v_and_b32_e32 v73, 0xffff0000, v67
	v_lshlrev_b32_e32 v70, 16, v65
	v_and_b32_e32 v71, 0xffff0000, v65
	v_pk_mul_f32 v[62:63], v[62:63], v[64:65] op_sel_hi:[1,0]
	v_and_b32_e32 v64, 0xffff0000, v61
	v_lshlrev_b32_e32 v65, 16, v67
	v_pk_mul_f32 v[64:65], v[62:63], v[64:65]
	s_nop 0
	v_pk_fma_f32 v[62:63], v[62:63], v[72:73], v[64:65] op_sel:[0,0,1] op_sel_hi:[1,1,0]
	s_nop 0
	v_pk_fma_f32 v[62:63], v[66:67], v[70:71], v[62:63] op_sel_hi:[0,1,1]
	v_cvt_pk_bf16_f32 v61, v62, v63
	v_lshl_add_u64 v[62:63], s[62:63], 0, v[78:79]
	global_store_dword v[62:63], v61, off
	s_cmp_lt_u32 s101, 4
	s_cbranch_scc1 .Lmg_cp_done
	v_max3_f32 v85, v81, v83, v84
	v_sub_f32_e32 v81, v81, v85
	v_mul_f32_e32 v81, 0x3fb8aa3b, v81
	v_exp_f32_e32 v82, v81
	v_sub_f32_e32 v81, v83, v85
	v_mul_f32_e32 v81, 0x3fb8aa3b, v81
	v_exp_f32_e32 v83, v81
	v_sub_f32_e32 v81, v84, v85
	v_mul_f32_e32 v81, 0x3fb8aa3b, v81
	v_exp_f32_e32 v81, v81
	v_add_f32_e32 v84, v82, v83
	v_add_f32_e32 v84, v81, v84
	v_div_scale_f32 v85, s[10:11], v84, v84, 1.0
	v_rcp_f32_e32 v86, v85
	s_nop 0
	v_fma_f32 v87, -v85, v86, 1.0
	v_fmac_f32_e32 v86, v87, v86
	v_div_scale_f32 v87, vcc, 1.0, v84, 1.0
	v_mul_f32_e32 v88, v87, v86
	v_fma_f32 v89, -v85, v88, v87
	v_fmac_f32_e32 v88, v89, v86
	v_fma_f32 v85, -v85, v88, v87
	v_div_fmas_f32 v85, v85, v86, v88
	s_nop 0
	v_div_fixup_f32 v84, v85, v84, 1.0
	v_mul_f32_e32 v86, v81, v84
	v_mov_b32_e32 v81, v94
	v_mov_b32_e32 v87, v95
	v_mov_b32_e32 v85, v96
	v_lshlrev_b32_e32 v92, 16, v81
	v_and_b32_e32 v93, 0xffff0000, v87
	v_lshlrev_b32_e32 v90, 16, v85
	v_and_b32_e32 v91, 0xffff0000, v85
	v_pk_mul_f32 v[82:83], v[82:83], v[84:85] op_sel_hi:[1,0]
	v_and_b32_e32 v84, 0xffff0000, v81
	v_lshlrev_b32_e32 v85, 16, v87
	v_pk_mul_f32 v[84:85], v[82:83], v[84:85]
	s_nop 0
	v_pk_fma_f32 v[82:83], v[82:83], v[92:93], v[84:85] op_sel:[0,0,1] op_sel_hi:[1,1,0]
	s_nop 0
	v_pk_fma_f32 v[82:83], v[86:87], v[90:91], v[82:83] op_sel_hi:[0,1,1]
	v_cvt_pk_bf16_f32 v81, v82, v83
	v_lshl_add_u64 v[82:83], s[62:63], 0, v[98:99]
	global_store_dword v[82:83], v81, off

; __device__ __forceinline__ unsigned pk2(float lo, float hi) { return f2bf(lo) | (f2bf(hi) << 16); }
; __device__ __forceinline__ float swap32_sum(float a, float b) { unsigned x, y; pl32(__builtin_bit_cast(unsigned, a), __builtin_bit_cast(unsigned, b), x, y); return __builtin_bit_cast(float, x) + __builtin_bit_cast(float, y); }
; __device__ __forceinline__ void sparse_unit7(const bf16_t* QKV, const unsigned char* K8, const unsigned char* V8, const int (&selv)[4], bf16_t* OB, LAS unsigned char* wl, int t, int h, int lane) {
;     ...
;     const float inv = 1.f / wave_sum(l);
;     const float r0 = swap32_sum(oa.x, oa.x), r1 = swap32_sum(oa.y, oa.y), r2 = swap32_sum(ob.x, ob.x), r3 = swap32_sum(ob.y, ob.y);
;     if (half == 0) { u32x2 o; o.x = pk2(r0 * inv, r1 * inv); o.y = pk2(r2 * inv, r3 * inv); *(u32x2*)(OB + (size_t)t * 1024 + h * 128 + l4) = o; }
.LBB0_157:
	s_waitcnt vmcnt(14)
	v_add_f32_dpp v0, v69, v69 row_ror:8 row_mask:0xf bank_mask:0xf bound_ctrl:1
	v_mov_b32_e32 v2, v51
	v_mov_b32_e32 v3, v53
	v_add_f32_dpp v0, v0, v0 row_ror:4 row_mask:0xf bank_mask:0xf bound_ctrl:1
	s_nop 1
	v_add_f32_dpp v0, v0, v0 quad_perm:[2,3,0,1] row_mask:0xf bank_mask:0xf bound_ctrl:1
	s_nop 1
	v_add_f32_dpp v0, v0, v0 quad_perm:[1,0,3,2] row_mask:0xf bank_mask:0xf bound_ctrl:1
	v_mov_b32_e32 v1, v0
	s_nop 1
	v_permlane16_swap_b32_e32 v0, v1
	s_nop 0
	v_add_f32_e32 v4, v0, v1
	v_mov_b32_e32 v5, v4
	v_mov_b32_e32 v0, v50
	s_nop 0
	v_permlane32_swap_b32_e32 v4, v5
	v_mov_b32_e32 v1, v52
	v_permlane32_swap_b32_e32 v50, v0
	s_nop 0
	v_permlane32_swap_b32_e32 v51, v2
	s_nop 0
	v_permlane32_swap_b32_e32 v52, v1
	s_nop 0
	v_permlane32_swap_b32_e32 v53, v3
	s_and_saveexec_b64 s[4:5], s[44:45]
	s_cbranch_execz .LBB0_132
	v_add_f32_e32 v4, v4, v5
	v_div_scale_f32 v5, s[8:9], v4, v4, 1.0
	v_rcp_f32_e32 v6, v5
	v_div_scale_f32 v7, vcc, 1.0, v4, 1.0
	s_lshl_b64 s[0:1], s[0:1], 11
	s_waitcnt vmcnt(12)
	v_fma_f32 v8, -v5, v6, 1.0
	v_fmac_f32_e32 v6, v8, v6
	v_mul_f32_e32 v8, v7, v6
	v_fma_f32 v9, -v5, v8, v7
	v_fmac_f32_e32 v8, v9, v6
	v_fma_f32 v5, -v5, v8, v7
	v_div_fmas_f32 v5, v5, v6, v8
	v_mov_b32_e32 v6, v51
	v_mov_b32_e32 v51, v52
	v_div_fixup_f32 v4, v5, v4, 1.0
	v_mov_b32_e32 v7, v53
	v_pk_add_f32 v[0:1], v[50:51], v[0:1]
	v_pk_add_f32 v[2:3], v[6:7], v[2:3]
	v_pk_mul_f32 v[0:1], v[4:5], v[0:1] op_sel_hi:[0,1]
	v_pk_mul_f32 v[2:3], v[4:5], v[2:3] op_sel_hi:[0,1]
	s_add_u32 s0, s96, s0
	v_readlane_b32 s8, v253, 22
	s_addc_u32 s1, s8, s1
	v_readlane_b32 s8, v252, 56
	s_lshl_b32 s8, s8, 1
	s_add_u32 s0, s0, s8
	v_cvt_pk_bf16_f32 v1, v1, v3
	v_cvt_pk_bf16_f32 v0, v0, v2
	s_addc_u32 s1, s1, 0
	v_lshlrev_b32_e32 v2, 1, v58
	v_readlane_b32 s9, v252, 57
	global_store_dwordx2 v2, v[0:1], s[0:1]
	s_branch .LBB0_132

; #define LAS __attribute__((address_space(3)))
; __device__ __forceinline__ unsigned pk2(float lo, float hi) { return f2bf(lo) | (f2bf(hi) << 16); }
; __device__ __forceinline__ void dilated_block(const bf16_t* QKV, bf16_t* OG, float* LSE, LAS unsigned char* lds, int u, int tid) {
;     ...
; #pragma unroll
;     for (int u2 = 0; u2 < 5; ++u2) {
;         u32x4 pw; pw.x = pk2(sacc[2 * u2][0], sacc[2 * u2][1]); pw.y = pk2(sacc[2 * u2][2], sacc[2 * u2][3]); pw.z = pk2(sacc[2 * u2 + 1][0], sacc[2 * u2 + 1][1]); pw.w = pk2(sacc[2 * u2 + 1][2], sacc[2 * u2 + 1][3]);
;         const bf16x8 pf = __builtin_bit_cast(bf16x8, pw);
;         const int r0 = min(i0 + 32 * u2 + 4 * slab + q4, 255), r1 = min(i0 + 32 * u2 + 16 + 4 * slab + q4, 255);
;         LAS unsigned char* a0p = lds + r0 * VRS + 8 * p4; LAS unsigned char* a1p = lds + r1 * VRS + 8 * p4;
; #pragma unroll
;         for (int c = 0; c < 8; ++c) {
;             const v4i16_t lo = __builtin_amdgcn_ds_read_tr16_b64_v4i16((LAS v4i16_t*)(a0p + c * 32)), hi = __builtin_amdgcn_ds_read_tr16_b64_v4i16((LAS v4i16_t*)(a1p + c * 32));
;             const bf16x8 vf = __builtin_shufflevector(lo, hi, 0, 1, 2, 3, 4, 5, 6, 7);
;             oacc[c] = __builtin_amdgcn_mfma_f32_16x16x32_bf16(vf, pf, oacc[c], 0, 0, 0);
;         }
;     }
.LBB0_196:
	s_or_b64 exec, exec, s[10:11]
	v_bfe_u32 v38, v35, 16, 1
	v_bfe_u32 v39, v33, 16, 1
	v_bfe_u32 v40, v31, 16, 1
	v_add3_u32 v40, v31, v40, s33
	v_add3_u32 v39, v33, v39, s33
	v_add3_u32 v35, v35, v38, s33
	v_bfe_u32 v31, v29, 16, 1
	v_bfe_u32 v33, v30, 16, 1
	v_bfe_u32 v37, v32, 16, 1
	v_add3_u32 v38, v30, v33, s33
	v_add3_u32 v29, v29, v31, s33
	v_or_b32_e32 v30, s1, v63
	v_add_u32_e32 v31, s1, v64
	v_add3_u32 v37, v32, v37, s33
	v_min_i32_e32 v30, 0xff, v30
	v_min_i32_e32 v31, 0xff, v31
	s_movk_i32 s10, 0x110
	v_lshrrev_b32_e32 v29, 16, v29
	v_mad_u64_u32 v[46:47], s[4:5], v30, s10, v[50:51]
	v_mad_u64_u32 v[54:55], s[4:5], v31, s10, v[50:51]
	v_lshrrev_b32_e32 v38, 16, v38
	v_lshrrev_b32_e32 v41, 16, v37
	ds_read_b64_tr_b16 v[32:33], v54
	ds_read_b64_tr_b16 v[30:31], v46
	v_cvt_pk_bf16_f32 v37, v34, v36
	v_and_or_b32 v36, v35, s67, v41
	v_and_or_b32 v35, v39, s67, v38
	v_and_or_b32 v34, v40, s67, v29
	ds_read_b64_tr_b16 v[40:41], v54 offset:32
	ds_read_b64_tr_b16 v[38:39], v46 offset:32
	ds_read_b64_tr_b16 v[42:43], v46 offset:64
	ds_read_b64_tr_b16 v[44:45], v54 offset:64
	ds_read_b64_tr_b16 v[74:75], v46 offset:96
	ds_read_b64_tr_b16 v[76:77], v54 offset:96
	ds_read_b64_tr_b16 v[78:79], v46 offset:128
	ds_read_b64_tr_b16 v[80:81], v54 offset:128
	ds_read_b64_tr_b16 v[82:83], v46 offset:160
	ds_read_b64_tr_b16 v[84:85], v54 offset:160
	ds_read_b64_tr_b16 v[86:87], v46 offset:192
	ds_read_b64_tr_b16 v[88:89], v54 offset:192
	ds_read_b64_tr_b16 v[90:91], v46 offset:224
	ds_read_b64_tr_b16 v[92:93], v54 offset:224
	v_bfe_u32 v47, v25, 16, 1
	v_bfe_u32 v54, v23, 16, 1
	s_waitcnt lgkmcnt(14)
	v_mfma_f32_16x16x32_bf16 v[30:33], v[30:33], v[34:37], 0
	v_add3_u32 v73, v23, v54, s33
	v_bfe_u32 v23, v21, 16, 1
	s_add_i32 s4, s1, 32
	s_waitcnt lgkmcnt(12)
	v_mfma_f32_16x16x32_bf16 v[38:41], v[38:41], v[34:37], 0
	v_bfe_u32 v46, v27, 16, 1
	v_add3_u32 v21, v21, v23, s33
	s_waitcnt lgkmcnt(10)
	v_mfma_f32_16x16x32_bf16 v[42:45], v[42:45], v[34:37], 0
	v_add_u32_e32 v23, s4, v64
	v_add3_u32 v27, v27, v46, s33
	s_waitcnt lgkmcnt(8)
	v_mfma_f32_16x16x32_bf16 v[74:77], v[74:77], v[34:37], 0
	v_bfe_u32 v29, v24, 16, 1
	v_min_i32_e32 v23, 0xff, v23
	s_waitcnt lgkmcnt(6)
	v_mfma_f32_16x16x32_bf16 v[78:81], v[78:81], v[34:37], 0
	v_add3_u32 v29, v24, v29, s33
	s_waitcnt lgkmcnt(4)
	v_mfma_f32_16x16x32_bf16 v[82:85], v[82:85], v[34:37], 0
	v_lshrrev_b32_e32 v21, 16, v21
	s_waitcnt lgkmcnt(2)
	v_mfma_f32_16x16x32_bf16 v[86:89], v[86:89], v[34:37], 0
	s_waitcnt lgkmcnt(0)
	v_mfma_f32_16x16x32_bf16 v[34:37], v[90:93], v[34:37], 0
	v_add3_u32 v90, v25, v47, s33
	v_bfe_u32 v25, v22, 16, 1
	v_add3_u32 v91, v22, v25, s33
	v_or_b32_e32 v22, s4, v63
	v_min_i32_e32 v22, 0xff, v22
	v_mad_u64_u32 v[46:47], s[4:5], v22, s10, v[50:51]
	v_mad_u64_u32 v[54:55], s[4:5], v23, s10, v[50:51]
	v_lshrrev_b32_e32 v47, 16, v91
	v_lshrrev_b32_e32 v55, 16, v29
	ds_read_b64_tr_b16 v[24:25], v54
	ds_read_b64_tr_b16 v[22:23], v46
	v_cvt_pk_bf16_f32 v29, v26, v28
	v_and_or_b32 v28, v27, s67, v55
	v_and_or_b32 v27, v90, s67, v47
	ds_read_b64_tr_b16 v[92:93], v54 offset:32
	ds_read_b64_tr_b16 v[90:91], v46 offset:32
	v_and_or_b32 v26, v73, s67, v21
	s_add_i32 s4, s1, 64
	s_waitcnt lgkmcnt(2)
	v_mfma_f32_16x16x32_bf16 v[22:25], v[22:25], v[26:29], v[30:33]
	v_bfe_u32 v21, v16, 16, 1
	v_add3_u32 v21, v16, v21, s33
	s_waitcnt lgkmcnt(0)
	v_mfma_f32_16x16x32_bf16 v[30:33], v[90:93], v[26:29], v[38:41]
	s_nop 2
	ds_read_b64_tr_b16 v[38:39], v46 offset:64
	ds_read_b64_tr_b16 v[40:41], v54 offset:64
	s_waitcnt lgkmcnt(0)
	v_mfma_f32_16x16x32_bf16 v[38:41], v[38:41], v[26:29], v[42:45]
	s_nop 2
	ds_read_b64_tr_b16 v[42:43], v46 offset:96
	ds_read_b64_tr_b16 v[44:45], v54 offset:96
	s_waitcnt lgkmcnt(0)
	v_mfma_f32_16x16x32_bf16 v[42:45], v[42:45], v[26:29], v[74:77]
	s_nop 2
	ds_read_b64_tr_b16 v[74:75], v46 offset:128
	ds_read_b64_tr_b16 v[76:77], v54 offset:128
	s_waitcnt lgkmcnt(0)
	v_mfma_f32_16x16x32_bf16 v[74:77], v[74:77], v[26:29], v[78:81]
	s_nop 2
	ds_read_b64_tr_b16 v[78:79], v46 offset:160
	ds_read_b64_tr_b16 v[80:81], v54 offset:160
	s_waitcnt lgkmcnt(0)
	v_mfma_f32_16x16x32_bf16 v[78:81], v[78:81], v[26:29], v[82:85]
	s_nop 2
	ds_read_b64_tr_b16 v[82:83], v46 offset:192
	ds_read_b64_tr_b16 v[84:85], v54 offset:192
	s_waitcnt lgkmcnt(0)
	v_mfma_f32_16x16x32_bf16 v[82:85], v[82:85], v[26:29], v[86:89]
	s_nop 2
	ds_read_b64_tr_b16 v[86:87], v46 offset:224
	ds_read_b64_tr_b16 v[88:89], v54 offset:224
	s_waitcnt lgkmcnt(0)
	v_mfma_f32_16x16x32_bf16 v[26:29], v[86:89], v[26:29], v[34:37]
	s_nop 2
	v_bfe_u32 v34, v19, 16, 1
	v_bfe_u32 v35, v17, 16, 1
	v_bfe_u32 v36, v15, 16, 1
	v_add3_u32 v36, v15, v36, s33
	v_add3_u32 v35, v17, v35, s33
	v_add3_u32 v19, v19, v34, s33
	v_bfe_u32 v15, v13, 16, 1
	v_bfe_u32 v17, v14, 16, 1
	v_add3_u32 v34, v14, v17, s33
	v_add3_u32 v13, v13, v15, s33
	v_or_b32_e32 v14, s4, v63
	v_add_u32_e32 v15, s4, v64
	v_min_i32_e32 v14, 0xff, v14
	v_min_i32_e32 v15, 0xff, v15
	v_lshrrev_b32_e32 v13, 16, v13
	v_mad_u64_u32 v[46:47], s[4:5], v14, s10, v[50:51]
	v_mad_u64_u32 v[54:55], s[4:5], v15, s10, v[50:51]
	v_lshrrev_b32_e32 v34, 16, v34
	v_lshrrev_b32_e32 v37, 16, v21
	ds_read_b64_tr_b16 v[16:17], v54
	ds_read_b64_tr_b16 v[14:15], v46
	v_cvt_pk_bf16_f32 v21, v18, v20
	v_and_or_b32 v20, v19, s67, v37
	v_and_or_b32 v19, v35, s67, v34
	v_and_or_b32 v18, v36, s67, v13
	ds_read_b64_tr_b16 v[36:37], v54 offset:32
	ds_read_b64_tr_b16 v[34:35], v46 offset:32
	s_waitcnt lgkmcnt(2)
	v_mfma_f32_16x16x32_bf16 v[14:17], v[14:17], v[18:21], v[22:25]
	s_add_i32 s4, s1, 0x60
	s_waitcnt lgkmcnt(0)
; #define LAS __attribute__((address_space(3)))
; __device__ __forceinline__ unsigned pk2(float lo, float hi) { return f2bf(lo) | (f2bf(hi) << 16); }
; __device__ __forceinline__ void dilated_block(const bf16_t* QKV, bf16_t* OG, float* LSE, LAS unsigned char* lds, int u, int tid) {
;     ...
; #pragma unroll
;     for (int u2 = 0; u2 < 5; ++u2) {
;         u32x4 pw; pw.x = pk2(sacc[2 * u2][0], sacc[2 * u2][1]); pw.y = pk2(sacc[2 * u2][2], sacc[2 * u2][3]); pw.z = pk2(sacc[2 * u2 + 1][0], sacc[2 * u2 + 1][1]); pw.w = pk2(sacc[2 * u2 + 1][2], sacc[2 * u2 + 1][3]);
;         const bf16x8 pf = __builtin_bit_cast(bf16x8, pw);
;         const int r0 = min(i0 + 32 * u2 + 4 * slab + q4, 255), r1 = min(i0 + 32 * u2 + 16 + 4 * slab + q4, 255);
;         LAS unsigned char* a0p = lds + r0 * VRS + 8 * p4; LAS unsigned char* a1p = lds + r1 * VRS + 8 * p4;
; #pragma unroll
;         for (int c = 0; c < 8; ++c) {
;             const v4i16_t lo = __builtin_amdgcn_ds_read_tr16_b64_v4i16((LAS v4i16_t*)(a0p + c * 32)), hi = __builtin_amdgcn_ds_read_tr16_b64_v4i16((LAS v4i16_t*)(a1p + c * 32));
;             const bf16x8 vf = __builtin_shufflevector(lo, hi, 0, 1, 2, 3, 4, 5, 6, 7);
;             oacc[c] = __builtin_amdgcn_mfma_f32_16x16x32_bf16(vf, pf, oacc[c], 0, 0, 0);
;         }
;     }
;     const float inv = 1.f / lsum;
	v_mfma_f32_16x16x32_bf16 v[22:25], v[34:37], v[18:21], v[30:33]
	s_nop 2
	ds_read_b64_tr_b16 v[30:31], v46 offset:64
	ds_read_b64_tr_b16 v[32:33], v54 offset:64
	ds_read_b64_tr_b16 v[34:35], v46 offset:96
	ds_read_b64_tr_b16 v[36:37], v54 offset:96
	v_bfe_u32 v13, v8, 16, 1
	s_waitcnt lgkmcnt(2)
	v_mfma_f32_16x16x32_bf16 v[30:33], v[30:33], v[18:21], v[38:41]
	s_nop 2
	ds_read_b64_tr_b16 v[38:39], v46 offset:128
	ds_read_b64_tr_b16 v[40:41], v54 offset:128
	v_add3_u32 v13, v8, v13, s33
	s_addk_i32 s1, 0x80
	s_waitcnt lgkmcnt(2)
	v_mfma_f32_16x16x32_bf16 v[34:37], v[34:37], v[18:21], v[42:45]
	s_nop 2
	ds_read_b64_tr_b16 v[42:43], v46 offset:160
	ds_read_b64_tr_b16 v[44:45], v54 offset:160
	s_waitcnt lgkmcnt(2)
	v_mfma_f32_16x16x32_bf16 v[38:41], v[38:41], v[18:21], v[74:77]
	s_nop 2
	ds_read_b64_tr_b16 v[74:75], v46 offset:192
	ds_read_b64_tr_b16 v[76:77], v54 offset:192
	s_waitcnt lgkmcnt(2)
	v_mfma_f32_16x16x32_bf16 v[42:45], v[42:45], v[18:21], v[78:81]
	s_nop 2
	ds_read_b64_tr_b16 v[78:79], v46 offset:224
	ds_read_b64_tr_b16 v[80:81], v54 offset:224
	s_waitcnt lgkmcnt(2)
	v_mfma_f32_16x16x32_bf16 v[74:77], v[74:77], v[18:21], v[82:85]
	s_waitcnt lgkmcnt(0)
	v_mfma_f32_16x16x32_bf16 v[18:21], v[78:81], v[18:21], v[26:29]
	s_nop 2
	v_bfe_u32 v26, v11, 16, 1
	v_bfe_u32 v27, v9, 16, 1
	v_bfe_u32 v28, v7, 16, 1
	v_add3_u32 v28, v7, v28, s33
	v_add3_u32 v27, v9, v27, s33
	v_add3_u32 v11, v11, v26, s33
	v_bfe_u32 v7, v5, 16, 1
	v_bfe_u32 v9, v6, 16, 1
	v_add3_u32 v26, v6, v9, s33
	v_add3_u32 v5, v5, v7, s33
	v_or_b32_e32 v6, s4, v63
	v_add_u32_e32 v7, s4, v64
	v_min_i32_e32 v6, 0xff, v6
	v_min_i32_e32 v7, 0xff, v7
	v_lshrrev_b32_e32 v5, 16, v5
	v_mad_u64_u32 v[46:47], s[4:5], v6, s10, v[50:51]
	v_mad_u64_u32 v[54:55], s[4:5], v7, s10, v[50:51]
	v_lshrrev_b32_e32 v26, 16, v26
	v_lshrrev_b32_e32 v29, 16, v13
	ds_read_b64_tr_b16 v[8:9], v54
	ds_read_b64_tr_b16 v[6:7], v46
	v_cvt_pk_bf16_f32 v13, v10, v12
	v_and_or_b32 v12, v11, s67, v29
	v_and_or_b32 v11, v27, s67, v26
	v_and_or_b32 v10, v28, s67, v5
	ds_read_b64_tr_b16 v[28:29], v54 offset:32
	ds_read_b64_tr_b16 v[26:27], v46 offset:32
	s_waitcnt lgkmcnt(2)
	v_mfma_f32_16x16x32_bf16 v[6:9], v[6:9], v[10:13], v[14:17]
	s_waitcnt lgkmcnt(0)
	v_mfma_f32_16x16x32_bf16 v[14:17], v[26:29], v[10:13], v[22:25]
	s_nop 2
	ds_read_b64_tr_b16 v[22:23], v46 offset:64
	ds_read_b64_tr_b16 v[24:25], v54 offset:64
	ds_read_b64_tr_b16 v[26:27], v46 offset:96
	ds_read_b64_tr_b16 v[28:29], v54 offset:96
	s_waitcnt lgkmcnt(2)
	v_mfma_f32_16x16x32_bf16 v[22:25], v[22:25], v[10:13], v[30:33]
	s_nop 2
	ds_read_b64_tr_b16 v[30:31], v46 offset:128
	ds_read_b64_tr_b16 v[32:33], v54 offset:128
	s_waitcnt lgkmcnt(2)
	v_mfma_f32_16x16x32_bf16 v[26:29], v[26:29], v[10:13], v[34:37]
	s_nop 2
	ds_read_b64_tr_b16 v[34:35], v46 offset:160
	ds_read_b64_tr_b16 v[36:37], v54 offset:160
	s_waitcnt lgkmcnt(2)
	v_mfma_f32_16x16x32_bf16 v[30:33], v[30:33], v[10:13], v[38:41]
	s_nop 2
	ds_read_b64_tr_b16 v[38:39], v46 offset:192
	ds_read_b64_tr_b16 v[40:41], v54 offset:192
	s_waitcnt lgkmcnt(2)
	v_mfma_f32_16x16x32_bf16 v[34:37], v[34:37], v[10:13], v[42:45]
	s_nop 2
	ds_read_b64_tr_b16 v[42:43], v46 offset:224
	ds_read_b64_tr_b16 v[44:45], v54 offset:224
	s_waitcnt lgkmcnt(2)
	v_mfma_f32_16x16x32_bf16 v[38:41], v[38:41], v[10:13], v[74:77]
	s_waitcnt lgkmcnt(0)
	v_mfma_f32_16x16x32_bf16 v[10:13], v[42:45], v[10:13], v[18:21]
	s_nop 2
	v_cvt_pk_bf16_f32 v19, v3, v4
	v_cvt_pk_bf16_f32 v18, v2, v1
	v_add_u32_e32 v3, s1, v64
	v_or_b32_e32 v2, s1, v63
	v_min_i32_e32 v3, 0xff, v3
	v_min_i32_e32 v2, 0xff, v2
	v_mad_u64_u32 v[54:55], s[4:5], v3, s10, v[50:51]
	v_mad_u64_u32 v[46:47], s[4:5], v2, s10, v[50:51]
	ds_read_b64_tr_b16 v[4:5], v54
	ds_read_b64_tr_b16 v[2:3], v46
	ds_read_b64_tr_b16 v[44:45], v54 offset:32
	ds_read_b64_tr_b16 v[42:43], v46 offset:32
	v_mov_b32_e32 v20, v161
	v_mov_b32_e32 v21, v161
	v_div_scale_f32 v1, s[4:5], v0, v0, 1.0
	s_waitcnt lgkmcnt(2)
	v_mfma_f32_16x16x32_bf16 v[2:5], v[2:5], v[18:21], v[6:9]
	s_nop 2
	ds_read_b64_tr_b16 v[6:7], v46 offset:64
	ds_read_b64_tr_b16 v[8:9], v54 offset:64
	s_ashr_i32 s1, s0, 31
	s_lshl_b64 s[0:1], s[0:1], 24
	s_waitcnt lgkmcnt(2)
; __device__ __forceinline__ unsigned pk2(float lo, float hi) { return f2bf(lo) | (f2bf(hi) << 16); }
; __device__ __forceinline__ void dilated_block(const bf16_t* QKV, bf16_t* OG, float* LSE, LAS unsigned char* lds, int u, int tid) {
;     ...
;     const float inv = 1.f / lsum;
;     bf16_t* op = OG + ((size_t)g * SEQ + tq) * 512 + hs * 128 + 4 * slab;
; #pragma unroll
;     for (int c = 0; c < 8; ++c) { u32x2 o; o.x = pk2(oacc[c][0] * inv, oacc[c][1] * inv); o.y = pk2(oacc[c][2] * inv, oacc[c][3] * inv); *(u32x2*)(op + 16 * c) = o; }
	v_mfma_f32_16x16x32_bf16 v[14:17], v[42:45], v[18:21], v[14:17]
	ds_read_b64_tr_b16 v[42:43], v46 offset:96
	ds_read_b64_tr_b16 v[44:45], v54 offset:96
	s_add_u32 s0, s30, s0
	s_addc_u32 s1, s31, s1
	s_waitcnt lgkmcnt(2)
	v_mfma_f32_16x16x32_bf16 v[6:9], v[6:9], v[18:21], v[22:25]
	s_nop 2
	ds_read_b64_tr_b16 v[22:23], v46 offset:128
	ds_read_b64_tr_b16 v[24:25], v54 offset:128
	s_lshl_b32 s4, s9, 8
	s_add_i32 s8, s8, s94
	s_waitcnt lgkmcnt(2)
	v_mfma_f32_16x16x32_bf16 v[26:29], v[42:45], v[18:21], v[26:29]
	ds_read_b64_tr_b16 v[42:43], v46 offset:160
	ds_read_b64_tr_b16 v[44:45], v54 offset:160
	s_cmpk_gt_i32 s8, 0x5ff
	s_waitcnt lgkmcnt(2)
	v_mfma_f32_16x16x32_bf16 v[22:25], v[22:25], v[18:21], v[30:33]
	s_nop 2
	ds_read_b64_tr_b16 v[30:31], v46 offset:192
	ds_read_b64_tr_b16 v[32:33], v54 offset:192
	s_waitcnt lgkmcnt(2)
	v_mfma_f32_16x16x32_bf16 v[34:37], v[42:45], v[18:21], v[34:37]
	ds_read_b64_tr_b16 v[42:43], v46 offset:224
	ds_read_b64_tr_b16 v[44:45], v54 offset:224
	s_waitcnt lgkmcnt(2)
	v_mfma_f32_16x16x32_bf16 v[30:33], v[30:33], v[18:21], v[38:41]
	s_nop 2
	v_rcp_f32_e32 v38, v1
	s_waitcnt lgkmcnt(0)
	v_mfma_f32_16x16x32_bf16 v[10:13], v[42:45], v[18:21], v[10:13]
	v_fma_f32 v18, -v1, v38, 1.0
	v_fmac_f32_e32 v38, v18, v38
	v_div_scale_f32 v18, vcc, 1.0, v0, 1.0
	v_mul_f32_e32 v19, v18, v38
	v_fma_f32 v20, -v1, v19, v18
	v_fmac_f32_e32 v19, v20, v38
	v_fma_f32 v1, -v1, v19, v18
	v_div_fmas_f32 v1, v1, v38, v19
	v_lshlrev_b64 v[18:19], 10, v[52:53]
	v_lshl_add_u64 v[18:19], s[0:1], 0, v[18:19]
	v_readlane_b32 s0, v252, 56
	v_readlane_b32 s1, v252, 57
	s_mov_b32 s5, s1
	v_lshl_add_u64 v[18:19], v[18:19], 0, s[4:5]
	v_lshlrev_b32_e32 v20, 1, v49
	v_div_fixup_f32 v0, v1, v0, 1.0
	v_lshl_add_u64 v[18:19], v[18:19], 0, v[20:21]
	v_mov_b32_e32 v20, v2
	v_mov_b32_e32 v21, v4
	v_pk_mul_f32 v[20:21], v[0:1], v[20:21] op_sel_hi:[0,1]
	v_mov_b32_e32 v4, v3
	v_pk_mul_f32 v[2:3], v[0:1], v[4:5] op_sel_hi:[0,1]
	v_cvt_pk_bf16_f32 v3, v21, v3
	v_cvt_pk_bf16_f32 v2, v20, v2
	global_store_dwordx2 v[18:19], v[2:3], off
	v_mov_b32_e32 v2, v14
	v_mov_b32_e32 v3, v16
	v_pk_mul_f32 v[2:3], v[0:1], v[2:3] op_sel_hi:[0,1]
	v_mov_b32_e32 v16, v15
	v_pk_mul_f32 v[4:5], v[0:1], v[16:17] op_sel_hi:[0,1]
	v_cvt_pk_bf16_f32 v3, v3, v5
	v_cvt_pk_bf16_f32 v2, v2, v4
	global_store_dwordx2 v[18:19], v[2:3], off offset:32
	v_mov_b32_e32 v2, v6
	v_mov_b32_e32 v3, v8
	v_pk_mul_f32 v[2:3], v[0:1], v[2:3] op_sel_hi:[0,1]
	v_mov_b32_e32 v8, v7
	v_pk_mul_f32 v[4:5], v[0:1], v[8:9] op_sel_hi:[0,1]
	v_cvt_pk_bf16_f32 v3, v3, v5
	v_cvt_pk_bf16_f32 v2, v2, v4
	global_store_dwordx2 v[18:19], v[2:3], off offset:64
	v_mov_b32_e32 v2, v26
	v_mov_b32_e32 v3, v28
	v_pk_mul_f32 v[2:3], v[0:1], v[2:3] op_sel_hi:[0,1]
	v_mov_b32_e32 v28, v27
	v_pk_mul_f32 v[4:5], v[0:1], v[28:29] op_sel_hi:[0,1]
	v_cvt_pk_bf16_f32 v3, v3, v5
	v_cvt_pk_bf16_f32 v2, v2, v4
	global_store_dwordx2 v[18:19], v[2:3], off offset:96
	v_mov_b32_e32 v2, v22
	v_mov_b32_e32 v3, v24
	v_pk_mul_f32 v[2:3], v[0:1], v[2:3] op_sel_hi:[0,1]
	v_mov_b32_e32 v24, v23
	v_pk_mul_f32 v[4:5], v[0:1], v[24:25] op_sel_hi:[0,1]
	v_cvt_pk_bf16_f32 v3, v3, v5
	v_cvt_pk_bf16_f32 v2, v2, v4
	global_store_dwordx2 v[18:19], v[2:3], off offset:128
	v_mov_b32_e32 v2, v34
	v_mov_b32_e32 v3, v36
	v_pk_mul_f32 v[2:3], v[0:1], v[2:3] op_sel_hi:[0,1]
	v_mov_b32_e32 v36, v35
	v_pk_mul_f32 v[4:5], v[0:1], v[36:37] op_sel_hi:[0,1]
	v_cvt_pk_bf16_f32 v3, v3, v5
	v_cvt_pk_bf16_f32 v2, v2, v4
	global_store_dwordx2 v[18:19], v[2:3], off offset:160
	v_mov_b32_e32 v2, v30
	v_mov_b32_e32 v3, v32
	v_pk_mul_f32 v[2:3], v[0:1], v[2:3] op_sel_hi:[0,1]
	v_mov_b32_e32 v32, v31
	v_pk_mul_f32 v[4:5], v[0:1], v[32:33] op_sel_hi:[0,1]
	v_cvt_pk_bf16_f32 v3, v3, v5
	v_cvt_pk_bf16_f32 v2, v2, v4
	global_store_dwordx2 v[18:19], v[2:3], off offset:192
	v_mov_b32_e32 v2, v10
	v_mov_b32_e32 v3, v12
	v_pk_mul_f32 v[2:3], v[0:1], v[2:3] op_sel_hi:[0,1]
	v_mov_b32_e32 v12, v11
	v_pk_mul_f32 v[0:1], v[0:1], v[12:13] op_sel_hi:[0,1]
	v_writelane_b32 v252, s0, 56
	v_writelane_b32 v252, s1, 57
	v_cvt_pk_bf16_f32 v1, v3, v1
	v_cvt_pk_bf16_f32 v0, v2, v0
	global_store_dwordx2 v[18:19], v[0:1], off offset:224
	s_cbranch_scc1 .LBB0_220

; __device__ __forceinline__ float row16_sum(float v) { v += dpp_f<0x128>(v); v += dpp_f<0x124>(v); v += dpp_f<0x4E>(v); v += dpp_f<0xB1>(v); return v; }
; template <int NIT, bool F8>
; __device__ __forceinline__ void post_segment(bf16_t* seg, const float* gain, const float (&cs)[8], const float (&sn)[8], int c, int grp, unsigned char* k8 = nullptr) {
;     const f32x4 g0 = *(const f32x4*)(gain + 8 * c), g1 = *(const f32x4*)(gain + 8 * c + 4);
;     const float g[8] = {g0[0], g0[1], g0[2], g0[3], g1[0], g1[1], g1[2], g1[3]};
;     u32x4 raw[NIT];
; #pragma unroll
;     for (int it = 0; it < NIT; ++it) raw[it] = *(const u32x4*)(seg + (it * 4 + grp) * 128 + c * 8);
; #pragma unroll
;     for (int it = 0; it < NIT; ++it) {
;         const unsigned w[4] = {raw[it].x, raw[it].y, raw[it].z, raw[it].w}; float x[8];
; #pragma unroll
;         for (int i = 0; i < 4; ++i) { x[2 * i] = bf2f(w[i] & 0xffffu); x[2 * i + 1] = __builtin_bit_cast(float, w[i] & 0xffff0000u); }
;         float ss = 0.f;
; #pragma unroll
;         for (int e = 0; e < 8; ++e) ss += x[e] * x[e];
;         ss = row16_sum(ss); const float r = 1.f / sqrtf(ss * (1.f / 128.f) + EPS);
; __device__ __forceinline__ void post_token(int pos, const float* gaq, const float* gak, const float* gbq, const float* gbk, const float* gik, ...
;     const float pf = (float)pos; const int c = lane & 15, grp = lane >> 4; const float sgn = (c < 8) ? -1.f : 1.f;
;     float cs[8], sn[8];
; #pragma unroll
;     for (int e = 0; e < 8; ++e) { float s_; rope_cs(pf * INVF[8 * (c & 7) + e], cs[e], s_); sn[e] = s_ * sgn; }
.LBB0_1008:
	global_load_dword v52, v161, s[4:5]
	v_lshl_add_u64 v[20:21], s[90:91], 0, v[40:41]
	s_mov_b32 s0, 0x12302000
	v_add_co_u32_e32 v64, vcc, s0, v20
	s_mov_b32 s0, 0x12300000
	s_nop 0
	v_addc_co_u32_e32 v65, vcc, 0, v21, vcc
	global_load_dwordx4 v[16:19], v[64:65], off offset:3072
	global_load_dwordx4 v[8:11], v[24:25], off offset:16
	global_load_dwordx4 v[12:15], v[24:25], off
	v_add_co_u32_e32 v76, vcc, s0, v20
	s_mov_b32 s0, 0x12303000
	v_add_co_u32_e64 v22, s[0:1], s0, v20
	v_addc_co_u32_e32 v77, vcc, 0, v21, vcc
	s_nop 0
	v_addc_co_u32_e64 v23, vcc, 0, v21, s[0:1]
	global_load_dwordx4 v[54:57], v[22:23], off
	s_mov_b32 s0, 0x6dc9c883
	s_mov_b32 s1, 0x3fc45f30
	s_mov_b32 s8, 0xf800000
	s_waitcnt vmcnt(4)
	v_cvt_f32_i32_e32 v22, v52
	v_mul_f32_e32 v23, v2, v22
	v_mul_f32_e32 v52, v3, v22
	s_waitcnt vmcnt(3)
	v_lshlrev_b32_e32 v78, 16, v16
	v_and_b32_e32 v79, 0xffff0000, v16
	v_lshlrev_b32_e32 v82, 16, v18
	v_and_b32_e32 v83, 0xffff0000, v18
	v_mul_f32_e32 v16, v0, v22
	v_mul_f32_e32 v18, v1, v22
	v_mul_f32_e32 v58, v4, v22
	v_mul_f32_e32 v60, v5, v22
	v_mul_f32_e32 v62, v6, v22
	v_mul_f32_e32 v66, v7, v22
	v_lshlrev_b32_e32 v80, 16, v17
	v_and_b32_e32 v81, 0xffff0000, v17
	v_lshlrev_b32_e32 v84, 16, v19
	v_and_b32_e32 v85, 0xffff0000, v19
	v_cvt_f64_f32_e32 v[16:17], v16
	v_cvt_f64_f32_e32 v[18:19], v18
	v_cvt_f64_f32_e32 v[22:23], v23
	v_cvt_f64_f32_e32 v[52:53], v52
	v_cvt_f64_f32_e32 v[58:59], v58
	v_cvt_f64_f32_e32 v[60:61], v60
	v_cvt_f64_f32_e32 v[62:63], v62
	v_cvt_f64_f32_e32 v[66:67], v66
	v_mul_f64 v[68:69], v[16:17], s[0:1]
	v_mul_f64 v[70:71], v[18:19], s[0:1]
	v_mul_f64 v[72:73], v[22:23], s[0:1]
	v_mul_f64 v[74:75], v[52:53], s[0:1]
	v_mul_f64 v[86:87], v[58:59], s[0:1]
	v_mul_f64 v[88:89], v[60:61], s[0:1]
	v_mul_f64 v[90:91], v[62:63], s[0:1]
	v_mul_f64 v[92:93], v[66:67], s[0:1]
	v_rndne_f64_e32 v[68:69], v[68:69]
	v_rndne_f64_e32 v[70:71], v[70:71]
	v_rndne_f64_e32 v[72:73], v[72:73]
	v_rndne_f64_e32 v[74:75], v[74:75]
	v_rndne_f64_e32 v[86:87], v[86:87]
	v_rndne_f64_e32 v[88:89], v[88:89]
	v_rndne_f64_e32 v[90:91], v[90:91]
	v_rndne_f64_e32 v[92:93], v[92:93]
	v_fma_f64 v[16:17], v[16:17], s[0:1], -v[68:69]
	v_fma_f64 v[18:19], v[18:19], s[0:1], -v[70:71]
	v_fma_f64 v[22:23], v[22:23], s[0:1], -v[72:73]
	v_fma_f64 v[52:53], v[52:53], s[0:1], -v[74:75]
	v_fma_f64 v[58:59], v[58:59], s[0:1], -v[86:87]
	v_fma_f64 v[60:61], v[60:61], s[0:1], -v[88:89]
	v_fma_f64 v[62:63], v[62:63], s[0:1], -v[90:91]
	v_fma_f64 v[66:67], v[66:67], s[0:1], -v[92:93]
	s_mov_b32 s0, 0x12301000
	v_add_co_u32_e64 v74, s[0:1], s0, v20
	v_cvt_f32_f64_e32 v16, v[16:17]
	s_nop 0
	v_addc_co_u32_e64 v75, s[0:1], 0, v21, s[0:1]
	global_load_dwordx4 v[68:71], v[74:75], off offset:-4096
	v_cvt_f32_f64_e32 v17, v[18:19]
	v_cvt_f32_f64_e32 v18, v[22:23]
	v_cvt_f32_f64_e32 v22, v[58:59]
	v_cvt_f32_f64_e32 v23, v[60:61]
	v_cvt_f32_f64_e32 v61, v[66:67]
	v_sin_f32_e32 v66, v16
	v_cos_f32_e32 v58, v16
	v_mul_f32_e32 v16, v79, v79
	v_fmac_f32_e32 v16, v78, v78
	v_fmac_f32_e32 v16, v80, v80
	v_fmac_f32_e32 v16, v81, v81
	v_fmac_f32_e32 v16, v82, v82
	v_fmac_f32_e32 v16, v83, v83
	v_fmac_f32_e32 v16, v84, v84
	v_fmac_f32_e32 v16, v85, v85
	v_cvt_f32_f64_e32 v19, v[52:53]
	v_cvt_f32_f64_e32 v53, v[62:63]
	v_add_f32_dpp v16, v16, v16 row_ror:8 row_mask:0xf bank_mask:0xf bound_ctrl:1
	v_sin_f32_e32 v72, v17
	v_cos_f32_e32 v62, v17
	v_add_f32_dpp v16, v16, v16 row_ror:4 row_mask:0xf bank_mask:0xf bound_ctrl:1
	v_sin_f32_e32 v102, v18
	v_cos_f32_e32 v59, v18
	v_add_f32_dpp v16, v16, v16 quad_perm:[2,3,0,1] row_mask:0xf bank_mask:0xf bound_ctrl:1
	v_sin_f32_e32 v73, v19
	v_cos_f32_e32 v63, v19
	v_add_f32_dpp v16, v16, v16 quad_perm:[1,0,3,2] row_mask:0xf bank_mask:0xf bound_ctrl:1
	v_fmamk_f32 v16, v16, 0x3c000000, v205
	v_mul_f32_e32 v17, 0x4f800000, v16
	v_cmp_gt_f32_e32 vcc, s8, v16
	s_waitcnt vmcnt(1)
	v_and_b32_e32 v87, 0xffff0000, v54
	v_lshlrev_b32_e32 v88, 16, v55
	v_cndmask_b32_e32 v16, v16, v17, vcc
	v_sqrt_f32_e32 v17, v16
	v_and_b32_e32 v89, 0xffff0000, v55
	v_lshlrev_b32_e32 v90, 16, v56
	v_and_b32_e32 v91, 0xffff0000, v56
	v_add_u32_e32 v18, -1, v17
	v_fma_f32 v19, -v18, v17, v16
	v_cmp_ge_f32_e64 s[0:1], 0, v19
	v_add_u32_e32 v19, 1, v17
	v_lshlrev_b32_e32 v92, 16, v57
	v_cndmask_b32_e64 v18, v17, v18, s[0:1]
	v_fma_f32 v17, -v19, v17, v16
	v_cmp_lt_f32_e64 s[0:1], 0, v17
	v_and_b32_e32 v93, 0xffff0000, v57
	v_sin_f32_e32 v67, v22
	v_cndmask_b32_e64 v17, v18, v19, s[0:1]
	v_mul_f32_e32 v18, 0x37800000, v17
	v_cndmask_b32_e32 v17, v17, v18, vcc
	v_cmp_class_f32_e32 vcc, v16, v206
	v_cos_f32_e32 v52, v22
	v_sin_f32_e32 v104, v23
	v_cndmask_b32_e32 v94, v17, v16, vcc
	v_div_scale_f32 v96, s[0:1], v94, v94, 1.0
	v_rcp_f32_e32 v97, v96
	v_cos_f32_e32 v60, v23
	global_load_dwordx4 v[98:101], v[76:77], off offset:1024
	global_load_dwordx4 v[20:23], v[76:77], off offset:2048
	global_load_dwordx4 v[16:19], v[76:77], off offset:3072
	v_div_scale_f32 v106, vcc, 1.0, v94, 1.0
	v_fma_f32 v86, -v96, v97, 1.0
	v_fmac_f32_e32 v97, v86, v97
	v_lshlrev_b32_e32 v86, 16, v54
	v_mul_f32_e32 v54, v87, v87
	v_fmac_f32_e32 v54, v86, v86
	v_fmac_f32_e32 v54, v88, v88
	v_fmac_f32_e32 v54, v89, v89
	v_fmac_f32_e32 v54, v90, v90
	v_fmac_f32_e32 v54, v91, v91
	v_fmac_f32_e32 v54, v92, v92
	v_fmac_f32_e32 v54, v93, v93
	v_mul_f32_e32 v56, v106, v97
	v_fma_f32 v57, -v96, v56, v106
	v_add_f32_dpp v54, v54, v54 row_ror:8 row_mask:0xf bank_mask:0xf bound_ctrl:1
	v_fmac_f32_e32 v56, v57, v97
	v_sin_f32_e32 v103, v53
	v_add_f32_dpp v54, v54, v54 row_ror:4 row_mask:0xf bank_mask:0xf bound_ctrl:1
	v_sin_f32_e32 v105, v61
	s_waitcnt vmcnt(3)
; __device__ __forceinline__ unsigned pk2(float lo, float hi) { return f2bf(lo) | (f2bf(hi) << 16); }
; template <int CTRL> __device__ __forceinline__ float dpp_f(float v) { return __builtin_bit_cast(float, __builtin_amdgcn_update_dpp(0, __builtin_bit_cast(int, v), CTRL, 0xF, 0xF, true)); }
; __device__ __forceinline__ float row16_sum(float v) { v += dpp_f<0x128>(v); v += dpp_f<0x124>(v); v += dpp_f<0x4E>(v); v += dpp_f<0xB1>(v); return v; }
; template <int NIT, bool F8>
; __device__ __forceinline__ void post_segment(bf16_t* seg, const float* gain, const float (&cs)[8], const float (&sn)[8], int c, int grp, unsigned char* k8 = nullptr) {
;     ...
;     for (int it = 0; it < NIT; ++it) {
;         const unsigned w[4] = {raw[it].x, raw[it].y, raw[it].z, raw[it].w}; float x[8];
; #pragma unroll
;         for (int i = 0; i < 4; ++i) { x[2 * i] = bf2f(w[i] & 0xffffu); x[2 * i + 1] = __builtin_bit_cast(float, w[i] & 0xffff0000u); }
;         float ss = 0.f;
; #pragma unroll
;         for (int e = 0; e < 8; ++e) ss += x[e] * x[e];
;         ss = row16_sum(ss); const float r = 1.f / sqrtf(ss * (1.f / 128.f) + EPS);
;         float o[8];
; #pragma unroll
;         for (int e = 0; e < 8; ++e) { const float y = x[e] * r * g[e]; const float py = dpp_f<0x128>(y); o[e] = y * cs[e] + py * sn[e]; }
;         u32x4 ow; ow.x = pk2(o[0], o[1]); ow.y = pk2(o[2], o[3]); ow.z = pk2(o[4], o[5]); ow.w = pk2(o[6], o[7]);
;         if constexpr (F8) *(u32x2*)(k8 + (it * 4 + grp) * 128 + c * 8) = to_fp8x8(o);
;         else *(u32x4*)(seg + (it * 4 + grp) * 128 + c * 8) = ow;
	v_lshlrev_b32_e32 v108, 16, v70
	v_add_f32_dpp v54, v54, v54 quad_perm:[2,3,0,1] row_mask:0xf bank_mask:0xf bound_ctrl:1
	v_and_b32_e32 v110, 0xffff0000, v70
	v_lshlrev_b32_e32 v109, 16, v71
	v_add_f32_dpp v54, v54, v54 quad_perm:[1,0,3,2] row_mask:0xf bank_mask:0xf bound_ctrl:1
	v_fmamk_f32 v54, v54, 0x3c000000, v205
	v_mul_f32_e32 v55, 0x4f800000, v54
	v_cmp_gt_f32_e64 s[0:1], s8, v54
	v_and_b32_e32 v111, 0xffff0000, v71
	v_mov_b32_e32 v70, v110
	v_cndmask_b32_e64 v54, v54, v55, s[0:1]
	v_sqrt_f32_e32 v55, v54
	v_mov_b32_e32 v71, v108
	v_pk_mul_f32 v[70:71], v[70:71], v[70:71]
	v_mov_b32_e32 v112, v111
	v_add_u32_e32 v57, -1, v55
	v_fma_f32 v95, -v57, v55, v54
	v_cmp_ge_f32_e64 s[40:41], 0, v95
	v_add_u32_e32 v95, 1, v55
	v_mov_b32_e32 v113, v109
	v_cndmask_b32_e64 v57, v55, v57, s[40:41]
	v_fma_f32 v55, -v95, v55, v54
	v_cmp_lt_f32_e64 s[40:41], 0, v55
	v_pk_mul_f32 v[112:113], v[112:113], v[112:113]
	v_cos_f32_e32 v61, v61
	v_cndmask_b32_e64 v55, v57, v95, s[40:41]
	v_mul_f32_e32 v57, 0x37800000, v55
	v_cndmask_b32_e64 v55, v55, v57, s[0:1]
	v_cmp_class_f32_e64 s[0:1], v54, v206
	v_fma_f32 v57, -v96, v56, v106
	v_div_fmas_f32 v97, v57, v97, v56
	v_cndmask_b32_e64 v95, v55, v54, s[0:1]
	v_div_scale_f32 v54, s[0:1], v95, v95, 1.0
	v_rcp_f32_e32 v55, v54
	v_cos_f32_e32 v53, v53
	v_fma_f32 v56, -v54, v55, 1.0
	v_fmac_f32_e32 v55, v56, v55
	v_div_scale_f32 v56, vcc, 1.0, v95, 1.0
	v_mul_f32_e32 v57, v56, v55
	v_fma_f32 v96, -v54, v57, v56
	v_fmac_f32_e32 v57, v96, v55
	v_fma_f32 v54, -v54, v57, v56
	v_div_fmas_f32 v96, v54, v55, v57
	v_pk_mul_f32 v[54:55], v[34:35], v[66:67]
	v_pk_mul_f32 v[56:57], v[34:35], v[102:103]
	v_pk_mul_f32 v[66:67], v[34:35], v[72:73]
	v_lshlrev_b32_e32 v73, 16, v69
	v_lshlrev_b32_e32 v72, 16, v68
	v_and_b32_e32 v103, 0xffff0000, v69
	v_and_b32_e32 v102, 0xffff0000, v68
	v_pk_mul_f32 v[68:69], v[72:73], v[72:73]
	v_pk_mul_f32 v[106:107], v[102:103], v[102:103]
	s_nop 0
	v_add_f32_e32 v68, v68, v106
	v_add_f32_e32 v68, v69, v68
	v_add_f32_e32 v68, v107, v68
	v_add_f32_e32 v68, v71, v68
	v_add_f32_e32 v68, v70, v68
	v_add_f32_e32 v68, v113, v68
	v_add_f32_e32 v68, v112, v68
	v_mov_b32_e32 v106, v12
	v_mov_b32_e32 v107, v14
	v_add_f32_dpp v68, v68, v68 row_ror:8 row_mask:0xf bank_mask:0xf bound_ctrl:1
	v_mov_b32_e32 v14, v13
	v_mov_b32_e32 v70, v54
	v_add_f32_dpp v68, v68, v68 row_ror:4 row_mask:0xf bank_mask:0xf bound_ctrl:1
	v_mov_b32_e32 v71, v56
	s_nop 0
	v_add_f32_dpp v68, v68, v68 quad_perm:[2,3,0,1] row_mask:0xf bank_mask:0xf bound_ctrl:1
	s_nop 1
	v_add_f32_dpp v68, v68, v68 quad_perm:[1,0,3,2] row_mask:0xf bank_mask:0xf bound_ctrl:1
	v_fmamk_f32 v68, v68, 0x3c000000, v205
	s_nop 1
	v_rsq_f32_e32 v12, v68
	v_pk_mul_f32 v[68:69], v[34:35], v[104:105]
	v_pk_mul_f32 v[102:103], v[12:13], v[102:103] op_sel_hi:[0,1]
	v_pk_mul_f32 v[102:103], v[14:15], v[102:103]
	v_pk_mul_f32 v[72:73], v[12:13], v[72:73] op_sel_hi:[0,1]
	v_pk_mul_f32 v[108:109], v[12:13], v[108:109] op_sel_hi:[0,1]
	v_mov_b32_dpp v112, v102 row_ror:8 row_mask:0xf bank_mask:0xf bound_ctrl:1
	v_mov_b32_dpp v113, v103 row_ror:8 row_mask:0xf bank_mask:0xf bound_ctrl:1
	v_pk_mul_f32 v[102:103], v[62:63], v[102:103]
	v_pk_mul_f32 v[12:13], v[12:13], v[110:111] op_sel_hi:[0,1]
	v_pk_fma_f32 v[102:103], v[66:67], v[112:113], v[102:103]
	v_mov_b32_e32 v113, v10
	v_mov_b32_e32 v10, v9
	v_pk_mul_f32 v[72:73], v[106:107], v[72:73]
	v_mov_b32_e32 v112, v8
	v_pk_mul_f32 v[12:13], v[10:11], v[12:13]
	v_mov_b32_dpp v104, v72 row_ror:8 row_mask:0xf bank_mask:0xf bound_ctrl:1
	v_mov_b32_dpp v105, v73 row_ror:8 row_mask:0xf bank_mask:0xf bound_ctrl:1
	v_pk_mul_f32 v[72:73], v[58:59], v[72:73]
	v_pk_mul_f32 v[108:109], v[112:113], v[108:109]
	v_mov_b32_dpp v110, v12 row_ror:8 row_mask:0xf bank_mask:0xf bound_ctrl:1
	v_mov_b32_dpp v111, v13 row_ror:8 row_mask:0xf bank_mask:0xf bound_ctrl:1
	v_pk_mul_f32 v[12:13], v[60:61], v[12:13]
	v_mov_b32_dpp v8, v108 row_ror:8 row_mask:0xf bank_mask:0xf bound_ctrl:1
	v_mov_b32_dpp v9, v109 row_ror:8 row_mask:0xf bank_mask:0xf bound_ctrl:1
	v_pk_mul_f32 v[108:109], v[52:53], v[108:109]
	v_pk_fma_f32 v[12:13], v[68:69], v[110:111], v[12:13]
	v_pk_fma_f32 v[104:105], v[70:71], v[104:105], v[72:73]
	v_mov_b32_e32 v72, v55
	v_mov_b32_e32 v73, v57
	v_pk_fma_f32 v[8:9], v[72:73], v[8:9], v[108:109]
	v_bfe_u32 v108, v13, 16, 1
	v_bfe_u32 v109, v12, 16, 1
	v_bfe_u32 v110, v103, 16, 1
	v_bfe_u32 v111, v102, 16, 1
	v_add3_u32 v114, v102, v111, s33
	v_add3_u32 v115, v103, v110, s33
	v_add3_u32 v116, v12, v109, s33
	v_add3_u32 v117, v13, v108, s33
	v_bfe_u32 v12, v104, 16, 1
	v_bfe_u32 v13, v105, 16, 1
	v_bfe_u32 v102, v8, 16, 1
	v_bfe_u32 v103, v9, 16, 1
	v_add3_u32 v118, v9, v103, s33
	v_add3_u32 v8, v8, v102, s33
	v_add3_u32 v9, v105, v13, s33
	v_add3_u32 v12, v104, v12, s33
	v_lshrrev_b32_e32 v119, 16, v12
	v_lshrrev_b32_e32 v120, 16, v9
	v_lshrrev_b32_e32 v121, 16, v8
	s_waitcnt vmcnt(2)
; __device__ __forceinline__ unsigned pk2(float lo, float hi) { return f2bf(lo) | (f2bf(hi) << 16); }
; template <int CTRL> __device__ __forceinline__ float dpp_f(float v) { return __builtin_bit_cast(float, __builtin_amdgcn_update_dpp(0, __builtin_bit_cast(int, v), CTRL, 0xF, 0xF, true)); }
; __device__ __forceinline__ float row16_sum(float v) { v += dpp_f<0x128>(v); v += dpp_f<0x124>(v); v += dpp_f<0x4E>(v); v += dpp_f<0xB1>(v); return v; }
; template <int NIT, bool F8>
; __device__ __forceinline__ void post_segment(bf16_t* seg, const float* gain, const float (&cs)[8], const float (&sn)[8], int c, int grp, unsigned char* k8 = nullptr) {
;     ...
;     for (int it = 0; it < NIT; ++it) {
;         const unsigned w[4] = {raw[it].x, raw[it].y, raw[it].z, raw[it].w}; float x[8];
; #pragma unroll
;         for (int i = 0; i < 4; ++i) { x[2 * i] = bf2f(w[i] & 0xffffu); x[2 * i + 1] = __builtin_bit_cast(float, w[i] & 0xffff0000u); }
;         float ss = 0.f;
; #pragma unroll
;         for (int e = 0; e < 8; ++e) ss += x[e] * x[e];
;         ss = row16_sum(ss); const float r = 1.f / sqrtf(ss * (1.f / 128.f) + EPS);
;         float o[8];
; #pragma unroll
;         for (int e = 0; e < 8; ++e) { const float y = x[e] * r * g[e]; const float py = dpp_f<0x128>(y); o[e] = y * cs[e] + py * sn[e]; }
;         u32x4 ow; ow.x = pk2(o[0], o[1]); ow.y = pk2(o[2], o[3]); ow.z = pk2(o[4], o[5]); ow.w = pk2(o[6], o[7]);
;         if constexpr (F8) *(u32x2*)(k8 + (it * 4 + grp) * 128 + c * 8) = to_fp8x8(o);
;         else *(u32x4*)(seg + (it * 4 + grp) * 128 + c * 8) = ow;
	v_lshlrev_b32_e32 v9, 16, v99
	v_lshlrev_b32_e32 v8, 16, v98
	v_and_b32_e32 v13, 0xffff0000, v99
	v_and_b32_e32 v12, 0xffff0000, v98
	v_pk_mul_f32 v[98:99], v[8:9], v[8:9]
	v_pk_mul_f32 v[102:103], v[12:13], v[12:13]
	v_lshlrev_b32_e32 v104, 16, v100
	v_and_b32_e32 v108, 0xffff0000, v100
	v_add_f32_e32 v98, v98, v102
	v_lshlrev_b32_e32 v105, 16, v101
	v_and_b32_e32 v109, 0xffff0000, v101
	v_mov_b32_e32 v100, v108
	v_mov_b32_e32 v101, v104
	v_add_f32_e32 v98, v99, v98
	v_pk_mul_f32 v[100:101], v[100:101], v[100:101]
	v_add_f32_e32 v98, v103, v98
	v_mov_b32_e32 v110, v109
	v_mov_b32_e32 v111, v105
	v_add_f32_e32 v98, v101, v98
	v_pk_mul_f32 v[110:111], v[110:111], v[110:111]
	v_add_f32_e32 v98, v100, v98
	v_add_f32_e32 v98, v111, v98
	v_add_f32_e32 v98, v110, v98
	v_lshrrev_b32_e32 v100, 16, v118
	v_and_or_b32 v101, v117, s67, v100
	v_add_f32_dpp v98, v98, v98 row_ror:8 row_mask:0xf bank_mask:0xf bound_ctrl:1
	v_and_or_b32 v100, v116, s67, v121
	s_nop 0
	v_add_f32_dpp v98, v98, v98 row_ror:4 row_mask:0xf bank_mask:0xf bound_ctrl:1
	s_nop 1
	v_add_f32_dpp v98, v98, v98 quad_perm:[2,3,0,1] row_mask:0xf bank_mask:0xf bound_ctrl:1
	s_nop 1
	v_add_f32_dpp v98, v98, v98 quad_perm:[1,0,3,2] row_mask:0xf bank_mask:0xf bound_ctrl:1
	v_fmamk_f32 v98, v98, 0x3c000000, v205
	s_nop 1
	v_rsq_f32_e32 v102, v98
	v_and_or_b32 v99, v115, s67, v120
	v_and_or_b32 v98, v114, s67, v119
	global_store_dwordx4 v[74:75], v[98:101], off offset:-4096
	s_nop 1
	v_mov_b32_e32 v98, v102
	v_pk_mul_f32 v[8:9], v[98:99], v[8:9] op_sel_hi:[0,1]
	v_pk_mul_f32 v[12:13], v[98:99], v[12:13] op_sel_hi:[0,1]
	v_pk_mul_f32 v[104:105], v[98:99], v[104:105] op_sel_hi:[0,1]
	v_pk_mul_f32 v[98:99], v[98:99], v[108:109] op_sel_hi:[0,1]
	v_pk_mul_f32 v[12:13], v[14:15], v[12:13]
	v_pk_mul_f32 v[98:99], v[10:11], v[98:99]
	v_pk_mul_f32 v[8:9], v[106:107], v[8:9]
	v_mov_b32_dpp v102, v12 row_ror:8 row_mask:0xf bank_mask:0xf bound_ctrl:1
	v_mov_b32_dpp v103, v13 row_ror:8 row_mask:0xf bank_mask:0xf bound_ctrl:1
	v_pk_mul_f32 v[12:13], v[62:63], v[12:13]
	v_pk_mul_f32 v[104:105], v[112:113], v[104:105]
	v_mov_b32_dpp v108, v98 row_ror:8 row_mask:0xf bank_mask:0xf bound_ctrl:1
	v_mov_b32_dpp v109, v99 row_ror:8 row_mask:0xf bank_mask:0xf bound_ctrl:1
	v_mov_b32_dpp v100, v8 row_ror:8 row_mask:0xf bank_mask:0xf bound_ctrl:1
	v_mov_b32_dpp v101, v9 row_ror:8 row_mask:0xf bank_mask:0xf bound_ctrl:1
	v_pk_mul_f32 v[8:9], v[58:59], v[8:9]
	v_mov_b32_dpp v110, v104 row_ror:8 row_mask:0xf bank_mask:0xf bound_ctrl:1
	v_mov_b32_dpp v111, v105 row_ror:8 row_mask:0xf bank_mask:0xf bound_ctrl:1
	v_pk_fma_f32 v[12:13], v[66:67], v[102:103], v[12:13]
	v_pk_mul_f32 v[102:103], v[68:69], v[108:109]
	v_pk_fma_f32 v[8:9], v[70:71], v[100:101], v[8:9]
	v_pk_fma_f32 v[98:99], v[60:61], v[98:99], v[102:103]
	v_pk_mul_f32 v[100:101], v[72:73], v[110:111]
	v_bfe_u32 v102, v13, 16, 1
	v_pk_fma_f32 v[100:101], v[52:53], v[104:105], v[100:101]
	v_bfe_u32 v103, v12, 16, 1
	v_bfe_u32 v104, v99, 16, 1
	v_bfe_u32 v105, v98, 16, 1
	v_add3_u32 v108, v98, v105, s33
	v_add3_u32 v109, v99, v104, s33
	v_add3_u32 v110, v12, v103, s33
	v_add3_u32 v111, v13, v102, s33
	v_bfe_u32 v12, v100, 16, 1
	v_bfe_u32 v13, v101, 16, 1
	v_bfe_u32 v98, v8, 16, 1
	v_bfe_u32 v99, v9, 16, 1
	v_add3_u32 v114, v9, v99, s33
	v_add3_u32 v8, v8, v98, s33
	v_add3_u32 v9, v101, v13, s33
	v_add3_u32 v12, v100, v12, s33
	v_lshrrev_b32_e32 v115, 16, v12
	v_lshrrev_b32_e32 v116, 16, v9
	v_lshrrev_b32_e32 v117, 16, v8
	s_waitcnt vmcnt(2)
	v_lshlrev_b32_e32 v9, 16, v21
	v_lshlrev_b32_e32 v8, 16, v20
	v_and_b32_e32 v13, 0xffff0000, v21
	v_and_b32_e32 v12, 0xffff0000, v20
	v_pk_mul_f32 v[20:21], v[8:9], v[8:9]
	v_pk_mul_f32 v[98:99], v[12:13], v[12:13]
	v_lshlrev_b32_e32 v100, 16, v22
	v_and_b32_e32 v102, 0xffff0000, v22
	v_add_f32_e32 v20, v20, v98
	v_lshlrev_b32_e32 v101, 16, v23
	v_and_b32_e32 v103, 0xffff0000, v23
	v_mov_b32_e32 v22, v102
	v_mov_b32_e32 v23, v100
	v_add_f32_e32 v20, v21, v20
	v_pk_mul_f32 v[22:23], v[22:23], v[22:23]
	v_add_f32_e32 v20, v99, v20
	v_mov_b32_e32 v104, v103
	v_mov_b32_e32 v105, v101
	v_add_f32_e32 v20, v23, v20
	v_pk_mul_f32 v[104:105], v[104:105], v[104:105]
	v_add_f32_e32 v20, v22, v20
	v_add_f32_e32 v20, v105, v20
	v_add_f32_e32 v20, v104, v20
	s_waitcnt vmcnt(1)
; __device__ __forceinline__ unsigned pk2(float lo, float hi) { return f2bf(lo) | (f2bf(hi) << 16); }
; template <int CTRL> __device__ __forceinline__ float dpp_f(float v) { return __builtin_bit_cast(float, __builtin_amdgcn_update_dpp(0, __builtin_bit_cast(int, v), CTRL, 0xF, 0xF, true)); }
; __device__ __forceinline__ float row16_sum(float v) { v += dpp_f<0x128>(v); v += dpp_f<0x124>(v); v += dpp_f<0x4E>(v); v += dpp_f<0xB1>(v); return v; }
; template <int NIT, bool F8>
; __device__ __forceinline__ void post_segment(bf16_t* seg, const float* gain, const float (&cs)[8], const float (&sn)[8], int c, int grp, unsigned char* k8 = nullptr) {
;     ...
;     for (int it = 0; it < NIT; ++it) {
;         const unsigned w[4] = {raw[it].x, raw[it].y, raw[it].z, raw[it].w}; float x[8];
; #pragma unroll
;         for (int i = 0; i < 4; ++i) { x[2 * i] = bf2f(w[i] & 0xffffu); x[2 * i + 1] = __builtin_bit_cast(float, w[i] & 0xffff0000u); }
;         float ss = 0.f;
; #pragma unroll
;         for (int e = 0; e < 8; ++e) ss += x[e] * x[e];
;         ss = row16_sum(ss); const float r = 1.f / sqrtf(ss * (1.f / 128.f) + EPS);
;         float o[8];
; #pragma unroll
;         for (int e = 0; e < 8; ++e) { const float y = x[e] * r * g[e]; const float py = dpp_f<0x128>(y); o[e] = y * cs[e] + py * sn[e]; }
;         u32x4 ow; ow.x = pk2(o[0], o[1]); ow.y = pk2(o[2], o[3]); ow.z = pk2(o[4], o[5]); ow.w = pk2(o[6], o[7]);
;         if constexpr (F8) *(u32x2*)(k8 + (it * 4 + grp) * 128 + c * 8) = to_fp8x8(o);
;         else *(u32x4*)(seg + (it * 4 + grp) * 128 + c * 8) = ow;
	v_and_b32_e32 v105, 0xffff0000, v17
	v_add_f32_dpp v20, v20, v20 row_ror:8 row_mask:0xf bank_mask:0xf bound_ctrl:1
	s_nop 1
	v_add_f32_dpp v20, v20, v20 row_ror:4 row_mask:0xf bank_mask:0xf bound_ctrl:1
	s_nop 1
	v_add_f32_dpp v20, v20, v20 quad_perm:[2,3,0,1] row_mask:0xf bank_mask:0xf bound_ctrl:1
	s_nop 1
	v_add_f32_dpp v20, v20, v20 quad_perm:[1,0,3,2] row_mask:0xf bank_mask:0xf bound_ctrl:1
	v_fmamk_f32 v20, v20, 0x3c000000, v205
	s_nop 1
	v_rsq_f32_e32 v98, v20
	v_lshrrev_b32_e32 v20, 16, v114
	v_and_or_b32 v21, v111, s67, v20
	v_and_or_b32 v20, v110, s67, v117
	v_and_or_b32 v23, v109, s67, v116
	v_and_or_b32 v22, v108, s67, v115
	global_store_dwordx4 v[76:77], v[20:23], off offset:1024
	v_and_b32_e32 v108, 0xffff0000, v18
	v_and_b32_e32 v109, 0xffff0000, v19
	v_mov_b32_e32 v20, v98
	v_pk_mul_f32 v[8:9], v[20:21], v[8:9] op_sel_hi:[0,1]
	v_pk_mul_f32 v[12:13], v[20:21], v[12:13] op_sel_hi:[0,1]
	v_pk_mul_f32 v[98:99], v[20:21], v[100:101] op_sel_hi:[0,1]
	v_pk_mul_f32 v[20:21], v[20:21], v[102:103] op_sel_hi:[0,1]
	v_pk_mul_f32 v[12:13], v[14:15], v[12:13]
	v_pk_mul_f32 v[10:11], v[10:11], v[20:21]
	v_pk_mul_f32 v[98:99], v[112:113], v[98:99]
	v_mov_b32_dpp v14, v12 row_ror:8 row_mask:0xf bank_mask:0xf bound_ctrl:1
	v_mov_b32_dpp v15, v13 row_ror:8 row_mask:0xf bank_mask:0xf bound_ctrl:1
	v_pk_mul_f32 v[12:13], v[62:63], v[12:13]
	v_mov_b32_dpp v20, v10 row_ror:8 row_mask:0xf bank_mask:0xf bound_ctrl:1
	v_mov_b32_dpp v21, v11 row_ror:8 row_mask:0xf bank_mask:0xf bound_ctrl:1
	v_pk_mul_f32 v[8:9], v[106:107], v[8:9]
	v_mov_b32_dpp v100, v98 row_ror:8 row_mask:0xf bank_mask:0xf bound_ctrl:1
	v_mov_b32_dpp v101, v99 row_ror:8 row_mask:0xf bank_mask:0xf bound_ctrl:1
	v_pk_fma_f32 v[12:13], v[66:67], v[14:15], v[12:13]
	v_pk_mul_f32 v[14:15], v[68:69], v[20:21]
	v_mov_b32_dpp v22, v8 row_ror:8 row_mask:0xf bank_mask:0xf bound_ctrl:1
	v_mov_b32_dpp v23, v9 row_ror:8 row_mask:0xf bank_mask:0xf bound_ctrl:1
	v_pk_mul_f32 v[8:9], v[58:59], v[8:9]
	v_pk_fma_f32 v[10:11], v[60:61], v[10:11], v[14:15]
	v_pk_mul_f32 v[14:15], v[72:73], v[100:101]
	v_pk_fma_f32 v[8:9], v[70:71], v[22:23], v[8:9]
	v_pk_fma_f32 v[14:15], v[52:53], v[98:99], v[14:15]
	v_cvt_pk_bf16_f32 v9, v9, v13
	v_cvt_pk_bf16_f32 v8, v8, v12
	v_cvt_pk_bf16_f32 v11, v15, v11
	v_cvt_pk_bf16_f32 v10, v14, v10
	global_store_dwordx4 v[76:77], v[8:11], off offset:2048
	global_load_dwordx4 v[20:23], v[26:27], off
	global_load_dwordx4 v[12:15], v[26:27], off offset:16
	global_load_dwordx4 v[98:101], v[74:75], off
	v_lshlrev_b32_e32 v103, 16, v17
	v_lshlrev_b32_e32 v102, 16, v16
	v_and_b32_e32 v104, 0xffff0000, v16
	v_pk_mul_f32 v[8:9], v[102:103], v[102:103]
	v_pk_mul_f32 v[10:11], v[104:105], v[104:105]
	v_lshlrev_b32_e32 v106, 16, v18
	v_add_f32_e32 v8, v8, v10
	v_mov_b32_e32 v16, v108
	v_mov_b32_e32 v17, v106
	v_add_f32_e32 v8, v9, v8
	v_lshlrev_b32_e32 v107, 16, v19
	v_pk_mul_f32 v[16:17], v[16:17], v[16:17]
	v_add_f32_e32 v8, v11, v8
	v_mov_b32_e32 v18, v109
	v_mov_b32_e32 v19, v107
	v_add_f32_e32 v8, v17, v8
	v_pk_mul_f32 v[18:19], v[18:19], v[18:19]
	v_add_f32_e32 v8, v16, v8
	v_add_f32_e32 v8, v19, v8
	v_add_f32_e32 v8, v18, v8
	s_nop 1
	v_add_f32_dpp v8, v8, v8 row_ror:8 row_mask:0xf bank_mask:0xf bound_ctrl:1
	s_nop 1
	v_add_f32_dpp v8, v8, v8 row_ror:4 row_mask:0xf bank_mask:0xf bound_ctrl:1
	s_nop 1
	v_add_f32_dpp v8, v8, v8 quad_perm:[2,3,0,1] row_mask:0xf bank_mask:0xf bound_ctrl:1
	s_nop 1
	v_add_f32_dpp v8, v8, v8 quad_perm:[1,0,3,2] row_mask:0xf bank_mask:0xf bound_ctrl:1
	v_fmamk_f32 v8, v8, 0x3c000000, v205
	s_nop 1
	v_rsq_f32_e32 v112, v8
	global_load_dwordx4 v[8:11], v[64:65], off offset:1024
	global_load_dwordx4 v[16:19], v[74:75], off offset:1024
	s_waitcnt vmcnt(4)
	v_mov_b32_e32 v110, v20
	v_mov_b32_e32 v111, v22
	v_mov_b32_e32 v22, v21
	v_mov_b32_e32 v20, v112
	v_pk_mul_f32 v[102:103], v[20:21], v[102:103] op_sel_hi:[0,1]
	v_pk_mul_f32 v[102:103], v[110:111], v[102:103]
	v_pk_mul_f32 v[104:105], v[20:21], v[104:105] op_sel_hi:[0,1]
	v_pk_mul_f32 v[106:107], v[20:21], v[106:107] op_sel_hi:[0,1]
	v_pk_mul_f32 v[20:21], v[20:21], v[108:109] op_sel_hi:[0,1]
	v_mov_b32_dpp v108, v102 row_ror:8 row_mask:0xf bank_mask:0xf bound_ctrl:1
	v_mov_b32_dpp v109, v103 row_ror:8 row_mask:0xf bank_mask:0xf bound_ctrl:1
	v_pk_mul_f32 v[102:103], v[58:59], v[102:103]
	v_pk_mul_f32 v[104:105], v[22:23], v[104:105]
	v_pk_fma_f32 v[102:103], v[70:71], v[108:109], v[102:103]
	s_waitcnt vmcnt(3)
	v_mov_b32_e32 v109, v14
	v_mov_b32_e32 v14, v13
	v_mov_b32_dpp v112, v104 row_ror:8 row_mask:0xf bank_mask:0xf bound_ctrl:1
	v_mov_b32_dpp v113, v105 row_ror:8 row_mask:0xf bank_mask:0xf bound_ctrl:1
	v_pk_mul_f32 v[104:105], v[62:63], v[104:105]
	v_mov_b32_e32 v108, v12
	v_pk_mul_f32 v[20:21], v[14:15], v[20:21]
	v_pk_fma_f32 v[104:105], v[66:67], v[112:113], v[104:105]
	v_pk_mul_f32 v[106:107], v[108:109], v[106:107]
	v_mov_b32_dpp v112, v20 row_ror:8 row_mask:0xf bank_mask:0xf bound_ctrl:1
	v_mov_b32_dpp v113, v21 row_ror:8 row_mask:0xf bank_mask:0xf bound_ctrl:1
	v_pk_mul_f32 v[20:21], v[60:61], v[20:21]
	v_mov_b32_dpp v12, v106 row_ror:8 row_mask:0xf bank_mask:0xf bound_ctrl:1
	v_mov_b32_dpp v13, v107 row_ror:8 row_mask:0xf bank_mask:0xf bound_ctrl:1
	v_pk_mul_f32 v[106:107], v[52:53], v[106:107]
	v_pk_fma_f32 v[20:21], v[68:69], v[112:113], v[20:21]
	v_pk_fma_f32 v[12:13], v[72:73], v[12:13], v[106:107]
	v_bfe_u32 v106, v21, 16, 1
	v_bfe_u32 v107, v20, 16, 1
	v_bfe_u32 v112, v105, 16, 1
	v_bfe_u32 v113, v104, 16, 1
	v_add3_u32 v114, v104, v113, s33
	v_add3_u32 v115, v105, v112, s33
	v_add3_u32 v116, v20, v107, s33
	v_add3_u32 v117, v21, v106, s33
	v_bfe_u32 v20, v102, 16, 1
	v_bfe_u32 v21, v103, 16, 1
	v_bfe_u32 v104, v12, 16, 1
	v_bfe_u32 v105, v13, 16, 1
	v_add3_u32 v118, v13, v105, s33
	v_add3_u32 v12, v12, v104, s33
	v_add3_u32 v13, v103, v21, s33
	v_add3_u32 v20, v102, v20, s33
	v_lshrrev_b32_e32 v119, 16, v20
	v_lshrrev_b32_e32 v120, 16, v13
	v_lshrrev_b32_e32 v121, 16, v12
	s_waitcnt vmcnt(2)
; __device__ __forceinline__ unsigned pk2(float lo, float hi) { return f2bf(lo) | (f2bf(hi) << 16); }
; template <int CTRL> __device__ __forceinline__ float dpp_f(float v) { return __builtin_bit_cast(float, __builtin_amdgcn_update_dpp(0, __builtin_bit_cast(int, v), CTRL, 0xF, 0xF, true)); }
; __device__ __forceinline__ float row16_sum(float v) { v += dpp_f<0x128>(v); v += dpp_f<0x124>(v); v += dpp_f<0x4E>(v); v += dpp_f<0xB1>(v); return v; }
; template <int NIT, bool F8>
; __device__ __forceinline__ void post_segment(bf16_t* seg, const float* gain, const float (&cs)[8], const float (&sn)[8], int c, int grp, unsigned char* k8 = nullptr) {
;     ...
;     for (int it = 0; it < NIT; ++it) {
;         const unsigned w[4] = {raw[it].x, raw[it].y, raw[it].z, raw[it].w}; float x[8];
; #pragma unroll
;         for (int i = 0; i < 4; ++i) { x[2 * i] = bf2f(w[i] & 0xffffu); x[2 * i + 1] = __builtin_bit_cast(float, w[i] & 0xffff0000u); }
;         float ss = 0.f;
; #pragma unroll
;         for (int e = 0; e < 8; ++e) ss += x[e] * x[e];
;         ss = row16_sum(ss); const float r = 1.f / sqrtf(ss * (1.f / 128.f) + EPS);
;         float o[8];
; #pragma unroll
;         for (int e = 0; e < 8; ++e) { const float y = x[e] * r * g[e]; const float py = dpp_f<0x128>(y); o[e] = y * cs[e] + py * sn[e]; }
;         u32x4 ow; ow.x = pk2(o[0], o[1]); ow.y = pk2(o[2], o[3]); ow.z = pk2(o[4], o[5]); ow.w = pk2(o[6], o[7]);
;         if constexpr (F8) *(u32x2*)(k8 + (it * 4 + grp) * 128 + c * 8) = to_fp8x8(o);
;         else *(u32x4*)(seg + (it * 4 + grp) * 128 + c * 8) = ow;
	v_lshlrev_b32_e32 v13, 16, v99
	v_lshlrev_b32_e32 v12, 16, v98
	v_and_b32_e32 v21, 0xffff0000, v99
	v_and_b32_e32 v20, 0xffff0000, v98
	v_pk_mul_f32 v[98:99], v[12:13], v[12:13]
	v_pk_mul_f32 v[102:103], v[20:21], v[20:21]
	v_lshlrev_b32_e32 v104, 16, v100
	v_and_b32_e32 v106, 0xffff0000, v100
	v_add_f32_e32 v98, v98, v102
	v_lshlrev_b32_e32 v105, 16, v101
	v_and_b32_e32 v107, 0xffff0000, v101
	v_mov_b32_e32 v100, v106
	v_mov_b32_e32 v101, v104
	v_add_f32_e32 v98, v99, v98
	v_pk_mul_f32 v[100:101], v[100:101], v[100:101]
	v_add_f32_e32 v98, v103, v98
	v_mov_b32_e32 v112, v107
	v_mov_b32_e32 v113, v105
	v_add_f32_e32 v98, v101, v98
	v_pk_mul_f32 v[112:113], v[112:113], v[112:113]
	v_add_f32_e32 v98, v100, v98
	v_add_f32_e32 v98, v113, v98
	v_add_f32_e32 v98, v112, v98
	v_lshrrev_b32_e32 v100, 16, v118
	v_and_or_b32 v101, v117, s67, v100
	v_add_f32_dpp v98, v98, v98 row_ror:8 row_mask:0xf bank_mask:0xf bound_ctrl:1
	v_and_or_b32 v100, v116, s67, v121
	s_nop 0
	v_add_f32_dpp v98, v98, v98 row_ror:4 row_mask:0xf bank_mask:0xf bound_ctrl:1
	s_nop 1
	v_add_f32_dpp v98, v98, v98 quad_perm:[2,3,0,1] row_mask:0xf bank_mask:0xf bound_ctrl:1
	s_nop 1
	v_add_f32_dpp v98, v98, v98 quad_perm:[1,0,3,2] row_mask:0xf bank_mask:0xf bound_ctrl:1
	v_fmamk_f32 v98, v98, 0x3c000000, v205
	s_nop 1
	v_rsq_f32_e32 v102, v98
	v_and_or_b32 v99, v115, s67, v120
	v_and_or_b32 v98, v114, s67, v119
	global_store_dwordx4 v[76:77], v[98:101], off offset:3072
	v_mov_b32_e32 v76, v102
	v_pk_mul_f32 v[12:13], v[76:77], v[12:13] op_sel_hi:[0,1]
	v_pk_mul_f32 v[20:21], v[76:77], v[20:21] op_sel_hi:[0,1]
	v_pk_mul_f32 v[98:99], v[76:77], v[104:105] op_sel_hi:[0,1]
	v_pk_mul_f32 v[12:13], v[110:111], v[12:13]
	v_pk_mul_f32 v[76:77], v[76:77], v[106:107] op_sel_hi:[0,1]
	v_pk_mul_f32 v[20:21], v[22:23], v[20:21]
	v_mov_b32_dpp v100, v12 row_ror:8 row_mask:0xf bank_mask:0xf bound_ctrl:1
	v_mov_b32_dpp v101, v13 row_ror:8 row_mask:0xf bank_mask:0xf bound_ctrl:1
	v_pk_mul_f32 v[12:13], v[58:59], v[12:13]
	v_pk_mul_f32 v[98:99], v[108:109], v[98:99]
	v_mov_b32_dpp v102, v20 row_ror:8 row_mask:0xf bank_mask:0xf bound_ctrl:1
	v_pk_fma_f32 v[12:13], v[70:71], v[100:101], v[12:13]
	v_mov_b32_dpp v103, v21 row_ror:8 row_mask:0xf bank_mask:0xf bound_ctrl:1
	v_pk_mul_f32 v[20:21], v[62:63], v[20:21]
	v_mov_b32_dpp v100, v98 row_ror:8 row_mask:0xf bank_mask:0xf bound_ctrl:1
	v_pk_mul_f32 v[76:77], v[14:15], v[76:77]
	v_mov_b32_dpp v101, v99 row_ror:8 row_mask:0xf bank_mask:0xf bound_ctrl:1
	v_pk_fma_f32 v[20:21], v[66:67], v[102:103], v[20:21]
	v_mov_b32_dpp v102, v76 row_ror:8 row_mask:0xf bank_mask:0xf bound_ctrl:1
	v_pk_mul_f32 v[100:101], v[72:73], v[100:101]
	v_mov_b32_dpp v103, v77 row_ror:8 row_mask:0xf bank_mask:0xf bound_ctrl:1
	v_pk_fma_f32 v[98:99], v[52:53], v[98:99], v[100:101]
	v_pk_mul_f32 v[100:101], v[68:69], v[102:103]
	s_nop 0
	v_pk_fma_f32 v[76:77], v[60:61], v[76:77], v[100:101]
	v_bfe_u32 v100, v21, 16, 1
	v_bfe_u32 v101, v20, 16, 1
	v_bfe_u32 v102, v77, 16, 1
	v_bfe_u32 v103, v76, 16, 1
	v_add3_u32 v104, v76, v103, s33
	v_add3_u32 v105, v77, v102, s33
	v_add3_u32 v106, v20, v101, s33
	v_add3_u32 v107, v21, v100, s33
	v_bfe_u32 v20, v98, 16, 1
	v_bfe_u32 v21, v99, 16, 1
	v_bfe_u32 v76, v12, 16, 1
	v_bfe_u32 v77, v13, 16, 1
	v_add3_u32 v112, v13, v77, s33
	v_add3_u32 v12, v12, v76, s33
	v_add3_u32 v13, v99, v21, s33
	v_add3_u32 v20, v98, v20, s33
	v_lshrrev_b32_e32 v113, 16, v20
	v_lshrrev_b32_e32 v114, 16, v13
	v_lshrrev_b32_e32 v115, 16, v12
	s_waitcnt vmcnt(1)
	v_lshlrev_b32_e32 v13, 16, v17
	v_lshlrev_b32_e32 v12, 16, v16
	v_and_b32_e32 v21, 0xffff0000, v17
	v_and_b32_e32 v20, 0xffff0000, v16
	v_pk_mul_f32 v[16:17], v[12:13], v[12:13]
	v_pk_mul_f32 v[76:77], v[20:21], v[20:21]
	v_lshlrev_b32_e32 v98, 16, v18
	v_and_b32_e32 v100, 0xffff0000, v18
	v_add_f32_e32 v16, v16, v76
	v_lshlrev_b32_e32 v99, 16, v19
	v_and_b32_e32 v101, 0xffff0000, v19
	v_mov_b32_e32 v18, v100
	v_mov_b32_e32 v19, v98
	v_add_f32_e32 v16, v17, v16
	v_pk_mul_f32 v[18:19], v[18:19], v[18:19]
	v_add_f32_e32 v16, v77, v16
	v_mov_b32_e32 v102, v101
	v_mov_b32_e32 v103, v99
	v_add_f32_e32 v16, v19, v16
	v_pk_mul_f32 v[102:103], v[102:103], v[102:103]
	v_add_f32_e32 v16, v18, v16
	v_add_f32_e32 v16, v103, v16
	v_add_f32_e32 v16, v102, v16
	s_nop 1
	v_add_f32_dpp v16, v16, v16 row_ror:8 row_mask:0xf bank_mask:0xf bound_ctrl:1
	s_nop 1
	v_add_f32_dpp v16, v16, v16 row_ror:4 row_mask:0xf bank_mask:0xf bound_ctrl:1
	s_nop 1
	v_add_f32_dpp v16, v16, v16 quad_perm:[2,3,0,1] row_mask:0xf bank_mask:0xf bound_ctrl:1
	s_nop 1
	v_add_f32_dpp v16, v16, v16 quad_perm:[1,0,3,2] row_mask:0xf bank_mask:0xf bound_ctrl:1
	v_fmamk_f32 v16, v16, 0x3c000000, v205
	s_nop 1
	v_rsq_f32_e32 v76, v16
	v_lshrrev_b32_e32 v16, 16, v112
	v_and_or_b32 v17, v107, s67, v16
	v_and_or_b32 v16, v106, s67, v115
	v_and_or_b32 v19, v105, s67, v114
	v_and_or_b32 v18, v104, s67, v113
	global_store_dwordx4 v[74:75], v[16:19], off
	s_nop 1
	v_mov_b32_e32 v16, v76
	v_pk_mul_f32 v[12:13], v[16:17], v[12:13] op_sel_hi:[0,1]
	v_pk_mul_f32 v[18:19], v[16:17], v[20:21] op_sel_hi:[0,1]
	v_pk_mul_f32 v[20:21], v[16:17], v[98:99] op_sel_hi:[0,1]
	v_pk_mul_f32 v[16:17], v[16:17], v[100:101] op_sel_hi:[0,1]
	v_pk_mul_f32 v[18:19], v[22:23], v[18:19]
	v_pk_mul_f32 v[14:15], v[14:15], v[16:17]
	v_pk_mul_f32 v[20:21], v[108:109], v[20:21]
	v_mov_b32_dpp v22, v18 row_ror:8 row_mask:0xf bank_mask:0xf bound_ctrl:1
	v_mov_b32_dpp v23, v19 row_ror:8 row_mask:0xf bank_mask:0xf bound_ctrl:1
	v_pk_mul_f32 v[18:19], v[62:63], v[18:19]
	v_mov_b32_dpp v16, v14 row_ror:8 row_mask:0xf bank_mask:0xf bound_ctrl:1
	v_mov_b32_dpp v17, v15 row_ror:8 row_mask:0xf bank_mask:0xf bound_ctrl:1
; __device__ __forceinline__ unsigned pk2(float lo, float hi) { return f2bf(lo) | (f2bf(hi) << 16); }
; template <int CTRL> __device__ __forceinline__ float dpp_f(float v) { return __builtin_bit_cast(float, __builtin_amdgcn_update_dpp(0, __builtin_bit_cast(int, v), CTRL, 0xF, 0xF, true)); }
; __device__ __forceinline__ float row16_sum(float v) { v += dpp_f<0x128>(v); v += dpp_f<0x124>(v); v += dpp_f<0x4E>(v); v += dpp_f<0xB1>(v); return v; }
; template <int NIT, bool F8>
; __device__ __forceinline__ void post_segment(bf16_t* seg, const float* gain, const float (&cs)[8], const float (&sn)[8], int c, int grp, unsigned char* k8 = nullptr) {
;     ...
;     for (int it = 0; it < NIT; ++it) {
;         const unsigned w[4] = {raw[it].x, raw[it].y, raw[it].z, raw[it].w}; float x[8];
; #pragma unroll
;         for (int i = 0; i < 4; ++i) { x[2 * i] = bf2f(w[i] & 0xffffu); x[2 * i + 1] = __builtin_bit_cast(float, w[i] & 0xffff0000u); }
;         float ss = 0.f;
; #pragma unroll
;         for (int e = 0; e < 8; ++e) ss += x[e] * x[e];
;         ss = row16_sum(ss); const float r = 1.f / sqrtf(ss * (1.f / 128.f) + EPS);
;         float o[8];
; #pragma unroll
;         for (int e = 0; e < 8; ++e) { const float y = x[e] * r * g[e]; const float py = dpp_f<0x128>(y); o[e] = y * cs[e] + py * sn[e]; }
;         u32x4 ow; ow.x = pk2(o[0], o[1]); ow.y = pk2(o[2], o[3]); ow.z = pk2(o[4], o[5]); ow.w = pk2(o[6], o[7]);
;         if constexpr (F8) *(u32x2*)(k8 + (it * 4 + grp) * 128 + c * 8) = to_fp8x8(o);
;         else *(u32x4*)(seg + (it * 4 + grp) * 128 + c * 8) = ow;
	v_pk_mul_f32 v[12:13], v[110:111], v[12:13]
	v_pk_fma_f32 v[18:19], v[66:67], v[22:23], v[18:19]
	v_mov_b32_dpp v22, v20 row_ror:8 row_mask:0xf bank_mask:0xf bound_ctrl:1
	v_mov_b32_dpp v23, v21 row_ror:8 row_mask:0xf bank_mask:0xf bound_ctrl:1
	v_pk_mul_f32 v[16:17], v[68:69], v[16:17]
	v_mov_b32_dpp v76, v12 row_ror:8 row_mask:0xf bank_mask:0xf bound_ctrl:1
	v_mov_b32_dpp v77, v13 row_ror:8 row_mask:0xf bank_mask:0xf bound_ctrl:1
	v_pk_mul_f32 v[12:13], v[58:59], v[12:13]
	v_pk_mul_f32 v[22:23], v[72:73], v[22:23]
	v_pk_fma_f32 v[14:15], v[60:61], v[14:15], v[16:17]
	v_pk_fma_f32 v[12:13], v[70:71], v[76:77], v[12:13]
	v_pk_fma_f32 v[20:21], v[52:53], v[20:21], v[22:23]
	v_cvt_pk_bf16_f32 v12, v12, v18
	v_cvt_pk_bf16_f32 v13, v13, v19
	v_cvt_pk_bf16_f32 v15, v21, v15
	v_cvt_pk_bf16_f32 v14, v20, v14
	global_store_dwordx4 v[74:75], v[12:15], off offset:1024
	global_load_dwordx4 v[16:19], v[28:29], off
	s_nop 0
	global_load_dwordx4 v[12:15], v[28:29], off offset:16
	global_load_dwordx4 v[20:23], v[64:65], off offset:2048
	v_lshlrev_b32_e32 v75, 16, v9
	v_lshlrev_b32_e32 v74, 16, v8
	v_and_b32_e32 v9, 0xffff0000, v9
	v_and_b32_e32 v8, 0xffff0000, v8
	v_pk_mul_f32 v[76:77], v[74:75], v[74:75]
	v_pk_mul_f32 v[98:99], v[8:9], v[8:9]
	v_lshlrev_b32_e32 v100, 16, v10
	v_and_b32_e32 v10, 0xffff0000, v10
	v_add_f32_e32 v76, v76, v98
	v_mov_b32_e32 v102, v10
	v_mov_b32_e32 v103, v100
	v_add_f32_e32 v76, v77, v76
	v_lshlrev_b32_e32 v101, 16, v11
	v_and_b32_e32 v11, 0xffff0000, v11
	v_pk_mul_f32 v[102:103], v[102:103], v[102:103]
	v_add_f32_e32 v76, v99, v76
	v_mov_b32_e32 v104, v11
	v_mov_b32_e32 v105, v101
	v_add_f32_e32 v76, v103, v76
	v_pk_mul_f32 v[104:105], v[104:105], v[104:105]
	v_add_f32_e32 v76, v102, v76
	v_add_f32_e32 v76, v105, v76
	v_add_f32_e32 v76, v104, v76
	s_nop 1
	v_add_f32_dpp v76, v76, v76 row_ror:8 row_mask:0xf bank_mask:0xf bound_ctrl:1
	s_nop 1
	v_add_f32_dpp v76, v76, v76 row_ror:4 row_mask:0xf bank_mask:0xf bound_ctrl:1
	s_nop 1
	v_add_f32_dpp v76, v76, v76 quad_perm:[2,3,0,1] row_mask:0xf bank_mask:0xf bound_ctrl:1
	s_nop 1
	v_add_f32_dpp v76, v76, v76 quad_perm:[1,0,3,2] row_mask:0xf bank_mask:0xf bound_ctrl:1
	v_fmamk_f32 v76, v76, 0x3c000000, v205
	s_nop 1
	v_rsq_f32_e32 v98, v76
	s_waitcnt vmcnt(2)
	v_mov_b32_e32 v76, v16
	v_mov_b32_e32 v77, v18
	v_mov_b32_e32 v18, v17
	v_mov_b32_e32 v16, v98
	v_pk_mul_f32 v[74:75], v[16:17], v[74:75] op_sel_hi:[0,1]
	v_pk_mul_f32 v[8:9], v[16:17], v[8:9] op_sel_hi:[0,1]
	v_pk_mul_f32 v[98:99], v[16:17], v[100:101] op_sel_hi:[0,1]
	v_pk_mul_f32 v[10:11], v[16:17], v[10:11] op_sel_hi:[0,1]
	v_pk_mul_f32 v[16:17], v[76:77], v[74:75]
	v_pk_mul_f32 v[8:9], v[18:19], v[8:9]
	s_nop 0
	v_mov_b32_dpp v74, v16 row_ror:8 row_mask:0xf bank_mask:0xf bound_ctrl:1
	v_mov_b32_dpp v75, v17 row_ror:8 row_mask:0xf bank_mask:0xf bound_ctrl:1
	v_pk_mul_f32 v[16:17], v[58:59], v[16:17]
	v_mov_b32_dpp v100, v8 row_ror:8 row_mask:0xf bank_mask:0xf bound_ctrl:1
	v_pk_fma_f32 v[16:17], v[70:71], v[74:75], v[16:17]
	s_waitcnt vmcnt(1)
	v_mov_b32_e32 v75, v14
	v_mov_b32_e32 v14, v13
	v_mov_b32_dpp v101, v9 row_ror:8 row_mask:0xf bank_mask:0xf bound_ctrl:1
	v_pk_mul_f32 v[8:9], v[62:63], v[8:9]
	v_mov_b32_e32 v74, v12
	v_pk_mul_f32 v[10:11], v[14:15], v[10:11]
	v_pk_fma_f32 v[8:9], v[66:67], v[100:101], v[8:9]
	v_pk_mul_f32 v[98:99], v[74:75], v[98:99]
	v_mov_b32_dpp v100, v10 row_ror:8 row_mask:0xf bank_mask:0xf bound_ctrl:1
	v_mov_b32_dpp v101, v11 row_ror:8 row_mask:0xf bank_mask:0xf bound_ctrl:1
	v_pk_mul_f32 v[10:11], v[60:61], v[10:11]
	v_mov_b32_dpp v12, v98 row_ror:8 row_mask:0xf bank_mask:0xf bound_ctrl:1
	v_mov_b32_dpp v13, v99 row_ror:8 row_mask:0xf bank_mask:0xf bound_ctrl:1
	v_pk_mul_f32 v[98:99], v[52:53], v[98:99]
	v_pk_fma_f32 v[10:11], v[68:69], v[100:101], v[10:11]
	v_pk_fma_f32 v[12:13], v[72:73], v[12:13], v[98:99]
	v_bfe_u32 v98, v11, 16, 1
	v_bfe_u32 v99, v10, 16, 1
	v_bfe_u32 v100, v9, 16, 1
	v_bfe_u32 v101, v8, 16, 1
	v_add3_u32 v102, v8, v101, s33
	v_add3_u32 v103, v9, v100, s33
	v_add3_u32 v104, v10, v99, s33
	v_add3_u32 v105, v11, v98, s33
	v_bfe_u32 v8, v16, 16, 1
	v_bfe_u32 v9, v17, 16, 1
	v_bfe_u32 v10, v12, 16, 1
	v_bfe_u32 v11, v13, 16, 1
	v_add3_u32 v106, v13, v11, s33
	v_add3_u32 v10, v12, v10, s33
	v_add3_u32 v9, v17, v9, s33
	v_add3_u32 v8, v16, v8, s33
	s_waitcnt vmcnt(0)
; __device__ __forceinline__ unsigned pk2(float lo, float hi) { return f2bf(lo) | (f2bf(hi) << 16); }
; template <int CTRL> __device__ __forceinline__ float dpp_f(float v) { return __builtin_bit_cast(float, __builtin_amdgcn_update_dpp(0, __builtin_bit_cast(int, v), CTRL, 0xF, 0xF, true)); }
; __device__ __forceinline__ float row16_sum(float v) { v += dpp_f<0x128>(v); v += dpp_f<0x124>(v); v += dpp_f<0x4E>(v); v += dpp_f<0xB1>(v); return v; }
; __device__ __forceinline__ u32x2 to_fp8x8(const float (&o)[8]) {
;     u32x2 w; int t0 = __builtin_amdgcn_cvt_pk_fp8_f32(o[0], o[1], 0, false); t0 = __builtin_amdgcn_cvt_pk_fp8_f32(o[2], o[3], t0, true);
;     int t1 = __builtin_amdgcn_cvt_pk_fp8_f32(o[4], o[5], 0, false); t1 = __builtin_amdgcn_cvt_pk_fp8_f32(o[6], o[7], t1, true); w.x = (unsigned)t0; w.y = (unsigned)t1; return w;
; template <int NIT, bool F8>
; __device__ __forceinline__ void post_segment(bf16_t* seg, const float* gain, const float (&cs)[8], const float (&sn)[8], int c, int grp, unsigned char* k8 = nullptr) {
;     ...
;     for (int it = 0; it < NIT; ++it) {
;         const unsigned w[4] = {raw[it].x, raw[it].y, raw[it].z, raw[it].w}; float x[8];
; #pragma unroll
;         for (int i = 0; i < 4; ++i) { x[2 * i] = bf2f(w[i] & 0xffffu); x[2 * i + 1] = __builtin_bit_cast(float, w[i] & 0xffff0000u); }
;         float ss = 0.f;
; #pragma unroll
;         for (int e = 0; e < 8; ++e) ss += x[e] * x[e];
;         ss = row16_sum(ss); const float r = 1.f / sqrtf(ss * (1.f / 128.f) + EPS);
;         float o[8];
; #pragma unroll
;         for (int e = 0; e < 8; ++e) { const float y = x[e] * r * g[e]; const float py = dpp_f<0x128>(y); o[e] = y * cs[e] + py * sn[e]; }
;         u32x4 ow; ow.x = pk2(o[0], o[1]); ow.y = pk2(o[2], o[3]); ow.z = pk2(o[4], o[5]); ow.w = pk2(o[6], o[7]);
;         if constexpr (F8) *(u32x2*)(k8 + (it * 4 + grp) * 128 + c * 8) = to_fp8x8(o);
;         else *(u32x4*)(seg + (it * 4 + grp) * 128 + c * 8) = ow;
;     }
	v_lshlrev_b32_e32 v13, 16, v21
	v_lshlrev_b32_e32 v12, 16, v20
	v_and_b32_e32 v17, 0xffff0000, v21
	v_and_b32_e32 v16, 0xffff0000, v20
	v_lshrrev_b32_e32 v107, 16, v8
	v_lshrrev_b32_e32 v108, 16, v9
	v_lshrrev_b32_e32 v109, 16, v10
	v_pk_mul_f32 v[8:9], v[12:13], v[12:13]
	v_pk_mul_f32 v[10:11], v[16:17], v[16:17]
	v_lshlrev_b32_e32 v20, 16, v22
	v_and_b32_e32 v22, 0xffff0000, v22
	v_add_f32_e32 v8, v8, v10
	v_mov_b32_e32 v98, v22
	v_mov_b32_e32 v99, v20
	v_add_f32_e32 v8, v9, v8
	v_lshlrev_b32_e32 v21, 16, v23
	v_and_b32_e32 v23, 0xffff0000, v23
	v_pk_mul_f32 v[98:99], v[98:99], v[98:99]
	v_add_f32_e32 v8, v11, v8
	v_mov_b32_e32 v100, v23
	v_mov_b32_e32 v101, v21
	v_add_f32_e32 v8, v99, v8
	v_pk_mul_f32 v[100:101], v[100:101], v[100:101]
	v_add_f32_e32 v8, v98, v8
	v_add_f32_e32 v8, v101, v8
	v_add_f32_e32 v8, v100, v8
	v_lshrrev_b32_e32 v10, 16, v106
	v_and_or_b32 v11, v105, s67, v10
	v_add_f32_dpp v8, v8, v8 row_ror:8 row_mask:0xf bank_mask:0xf bound_ctrl:1
	v_and_or_b32 v10, v104, s67, v109
	s_nop 0
	v_add_f32_dpp v8, v8, v8 row_ror:4 row_mask:0xf bank_mask:0xf bound_ctrl:1
	s_nop 1
	v_add_f32_dpp v8, v8, v8 quad_perm:[2,3,0,1] row_mask:0xf bank_mask:0xf bound_ctrl:1
	s_nop 1
	v_add_f32_dpp v8, v8, v8 quad_perm:[1,0,3,2] row_mask:0xf bank_mask:0xf bound_ctrl:1
	v_fmamk_f32 v8, v8, 0x3c000000, v205
	v_mul_f32_e32 v9, 0x4f800000, v8
	v_cmp_gt_f32_e32 vcc, s8, v8
	s_nop 1
	v_cndmask_b32_e32 v8, v8, v9, vcc
	v_sqrt_f32_e32 v9, v8
	s_nop 0
	v_add_u32_e32 v98, -1, v9
	v_fma_f32 v99, -v98, v9, v8
	v_cmp_ge_f32_e64 s[0:1], 0, v99
	v_add_u32_e32 v99, 1, v9
	s_nop 0
	v_cndmask_b32_e64 v98, v9, v98, s[0:1]
	v_fma_f32 v9, -v99, v9, v8
	v_cmp_lt_f32_e64 s[0:1], 0, v9
	s_nop 1
	v_cndmask_b32_e64 v9, v98, v99, s[0:1]
	v_mul_f32_e32 v98, 0x37800000, v9
	v_cndmask_b32_e32 v9, v9, v98, vcc
	v_cmp_class_f32_e32 vcc, v8, v206
	s_nop 1
	v_cndmask_b32_e32 v98, v9, v8, vcc
	v_div_scale_f32 v99, s[0:1], v98, v98, 1.0
	v_rcp_f32_e32 v100, v99
	v_and_or_b32 v9, v103, s67, v108
	v_and_or_b32 v8, v102, s67, v107
	global_store_dwordx4 v[64:65], v[8:11], off offset:1024
	s_mov_b32 s0, 0x3af00000
	s_nop 0
	v_fma_f32 v8, -v99, v100, 1.0
	v_fmac_f32_e32 v100, v8, v100
	v_div_scale_f32 v8, vcc, 1.0, v98, 1.0
	v_mul_f32_e32 v9, v8, v100
	v_fma_f32 v10, -v99, v9, v8
	v_fmac_f32_e32 v9, v10, v100
	v_fma_f32 v8, -v99, v9, v8
	v_div_fmas_f32 v8, v8, v100, v9
	v_div_fixup_f32 v8, v8, v98, 1.0
	v_pk_mul_f32 v[10:11], v[8:9], v[12:13] op_sel_hi:[0,1]
	v_pk_mul_f32 v[12:13], v[8:9], v[16:17] op_sel_hi:[0,1]
	v_pk_mul_f32 v[16:17], v[8:9], v[20:21] op_sel_hi:[0,1]
	v_pk_mul_f32 v[8:9], v[8:9], v[22:23] op_sel_hi:[0,1]
	v_pk_mul_f32 v[12:13], v[18:19], v[12:13]
	v_pk_mul_f32 v[8:9], v[14:15], v[8:9]
	v_pk_mul_f32 v[16:17], v[74:75], v[16:17]
	v_mov_b32_dpp v18, v12 row_ror:8 row_mask:0xf bank_mask:0xf bound_ctrl:1
	v_mov_b32_dpp v19, v13 row_ror:8 row_mask:0xf bank_mask:0xf bound_ctrl:1
	v_pk_mul_f32 v[12:13], v[62:63], v[12:13]
	v_mov_b32_dpp v14, v8 row_ror:8 row_mask:0xf bank_mask:0xf bound_ctrl:1
	v_mov_b32_dpp v15, v9 row_ror:8 row_mask:0xf bank_mask:0xf bound_ctrl:1
	v_pk_mul_f32 v[10:11], v[76:77], v[10:11]
	v_pk_fma_f32 v[12:13], v[66:67], v[18:19], v[12:13]
	v_mov_b32_dpp v18, v16 row_ror:8 row_mask:0xf bank_mask:0xf bound_ctrl:1
	v_mov_b32_dpp v19, v17 row_ror:8 row_mask:0xf bank_mask:0xf bound_ctrl:1
	v_pk_mul_f32 v[14:15], v[68:69], v[14:15]
	v_mov_b32_dpp v20, v10 row_ror:8 row_mask:0xf bank_mask:0xf bound_ctrl:1
	v_mov_b32_dpp v21, v11 row_ror:8 row_mask:0xf bank_mask:0xf bound_ctrl:1
	v_pk_mul_f32 v[10:11], v[58:59], v[10:11]
	v_pk_mul_f32 v[18:19], v[72:73], v[18:19]
	v_pk_fma_f32 v[8:9], v[60:61], v[8:9], v[14:15]
	v_pk_fma_f32 v[10:11], v[70:71], v[20:21], v[10:11]
	v_pk_fma_f32 v[16:17], v[52:53], v[16:17], v[18:19]
	v_bfe_u32 v18, v9, 16, 1
	v_bfe_u32 v19, v8, 16, 1
	v_add3_u32 v19, v8, v19, s33
	v_add3_u32 v18, v9, v18, s33
	v_cvt_pk_bf16_f32 v8, v10, v12
	v_cvt_pk_bf16_f32 v9, v11, v13
	v_bfe_u32 v12, v16, 16, 1
	v_bfe_u32 v13, v17, 16, 1
	v_add3_u32 v13, v17, v13, s33
	v_add3_u32 v12, v16, v12, s33
	v_lshrrev_b32_e32 v12, 16, v12
	v_lshrrev_b32_e32 v13, 16, v13
	v_and_or_b32 v11, v18, s67, v13
	v_and_or_b32 v10, v19, s67, v12
	global_store_dwordx4 v[64:65], v[8:11], off offset:2048
	global_load_dwordx4 v[8:11], v[30:31], off
	s_nop 0
	global_load_dwordx4 v[12:15], v[30:31], off offset:16
	v_div_fixup_f32 v16, v97, v94, 1.0
	v_mul_f32_e32 v18, v16, v78
	v_mul_f32_e32 v19, v16, v79
	v_mul_f32_e32 v20, v16, v80
	v_mul_f32_e32 v21, v16, v81
	v_mul_f32_e32 v64, v16, v82
	v_mul_f32_e32 v65, v16, v83
	v_mul_f32_e32 v70, v16, v84
	v_div_fixup_f32 v22, v96, v95, 1.0
	v_mul_f32_e32 v72, v22, v86
	v_mul_f32_e32 v73, v22, v87
	v_mul_f32_e32 v74, v22, v88
	v_mul_f32_e32 v75, v22, v89
	v_mul_f32_e32 v76, v22, v90
	v_mul_f32_e32 v77, v22, v91
	v_mul_f32_e32 v78, v22, v92
	v_mul_f32_e32 v71, v16, v85
	v_mul_f32_e32 v79, v22, v93
	v_lshl_add_u64 v[16:17], s[90:91], 0, v[44:45]
	v_lshl_add_u64 v[22:23], s[90:91], 0, v[46:47]
	s_waitcnt vmcnt(1)
	v_mul_f32_e32 v18, v8, v18
	s_nop 1
	v_mov_b32_dpp v80, v18 row_ror:8 row_mask:0xf bank_mask:0xf bound_ctrl:1
	v_mul_f32_e32 v81, v58, v18
	v_mul_f32_e32 v18, v9, v19
	v_fmac_f32_e32 v81, v54, v80
	v_mul_f32_e32 v80, v62, v18
	v_mov_b32_dpp v19, v18 row_ror:8 row_mask:0xf bank_mask:0xf bound_ctrl:1
	v_mul_f32_e32 v18, v10, v20
	v_fmac_f32_e32 v80, v66, v19
	v_mul_f32_e32 v20, v59, v18
	v_mov_b32_dpp v19, v18 row_ror:8 row_mask:0xf bank_mask:0xf bound_ctrl:1
	v_mul_f32_e32 v18, v11, v21
	v_fmac_f32_e32 v20, v56, v19
	v_mul_f32_e32 v21, v63, v18
	v_mov_b32_dpp v19, v18 row_ror:8 row_mask:0xf bank_mask:0xf bound_ctrl:1
	s_waitcnt vmcnt(0)
; __device__ __forceinline__ unsigned pk2(float lo, float hi) { return f2bf(lo) | (f2bf(hi) << 16); }
; template <int CTRL> __device__ __forceinline__ float dpp_f(float v) { return __builtin_bit_cast(float, __builtin_amdgcn_update_dpp(0, __builtin_bit_cast(int, v), CTRL, 0xF, 0xF, true)); }
; __device__ __forceinline__ u32x2 to_fp8x8(const float (&o)[8]) {
;     u32x2 w; int t0 = __builtin_amdgcn_cvt_pk_fp8_f32(o[0], o[1], 0, false); t0 = __builtin_amdgcn_cvt_pk_fp8_f32(o[2], o[3], t0, true);
;     int t1 = __builtin_amdgcn_cvt_pk_fp8_f32(o[4], o[5], 0, false); t1 = __builtin_amdgcn_cvt_pk_fp8_f32(o[6], o[7], t1, true); w.x = (unsigned)t0; w.y = (unsigned)t1; return w;
; __device__ __forceinline__ void post_token(int pos, const float* gaq, const float* gak, const float* gbq, const float* gbk, const float* gik, ...
;     ...
;     f32x4 xi[4];
; #pragma unroll
;     for (int it = 0; it < 4; ++it) xi[it] = *(const f32x4*)(irow + (it * 4 + grp) * 64 + 4 * c);
;     const f32x4 xk = *(const f32x4*)(irow + 1024 + 4 * c);
; #pragma unroll
;     for (int it = 0; it < 4; ++it) { float o[4];
; #pragma unroll
;         for (int e = 0; e < 4; ++e) { const float x = xi[it][e]; const float px = dpp_f<0x128>(x); o[e] = x * ci[e] + px * si[e]; }
;         u32x2 ow; ow.x = pk2(o[0], o[1]); ow.y = pk2(o[2], o[3]); *(u32x2*)(iq + (it * 4 + grp) * 64 + 4 * c) = ow; }
	v_mul_f32_e32 v18, v12, v64
	v_fmac_f32_e32 v21, v67, v19
	v_mul_f32_e32 v64, v52, v18
	v_mov_b32_dpp v19, v18 row_ror:8 row_mask:0xf bank_mask:0xf bound_ctrl:1
	v_mul_f32_e32 v18, v13, v65
	v_fmac_f32_e32 v64, v55, v19
	v_mul_f32_e32 v65, v60, v18
	v_mov_b32_dpp v19, v18 row_ror:8 row_mask:0xf bank_mask:0xf bound_ctrl:1
	v_mul_f32_e32 v18, v14, v70
	v_fmac_f32_e32 v65, v68, v19
	v_mul_f32_e32 v70, v53, v18
	v_mov_b32_dpp v19, v18 row_ror:8 row_mask:0xf bank_mask:0xf bound_ctrl:1
	v_mov_b32_e32 v18, 0
	v_cvt_pk_fp8_f32 v18, v81, v80
	v_mul_f32_e32 v8, v8, v72
	v_fmac_f32_e32 v70, v57, v19
	v_mov_b32_e32 v19, 0
	v_cvt_pk_fp8_f32 v18, v20, v21 op_sel:[0,0,1]
	v_mov_b32_dpp v20, v8 row_ror:8 row_mask:0xf bank_mask:0xf bound_ctrl:1
	v_mul_f32_e32 v21, v58, v8
	v_mul_f32_e32 v8, v9, v73
	v_fmac_f32_e32 v21, v54, v20
	v_mul_f32_e32 v20, v62, v8
	v_mov_b32_dpp v9, v8 row_ror:8 row_mask:0xf bank_mask:0xf bound_ctrl:1
	v_mul_f32_e32 v8, v10, v74
	v_fmac_f32_e32 v20, v66, v9
	v_mul_f32_e32 v10, v59, v8
	v_mov_b32_dpp v9, v8 row_ror:8 row_mask:0xf bank_mask:0xf bound_ctrl:1
	v_mul_f32_e32 v8, v11, v75
	v_fmac_f32_e32 v10, v56, v9
	v_mul_f32_e32 v11, v63, v8
	v_mov_b32_dpp v9, v8 row_ror:8 row_mask:0xf bank_mask:0xf bound_ctrl:1
	v_mul_f32_e32 v8, v12, v76
	v_fmac_f32_e32 v11, v67, v9
	v_mul_f32_e32 v12, v52, v8
	v_mov_b32_dpp v9, v8 row_ror:8 row_mask:0xf bank_mask:0xf bound_ctrl:1
	v_mul_f32_e32 v8, v13, v77
	v_fmac_f32_e32 v12, v55, v9
	v_mul_f32_e32 v13, v60, v8
	v_mov_b32_dpp v9, v8 row_ror:8 row_mask:0xf bank_mask:0xf bound_ctrl:1
	v_mul_f32_e32 v8, v14, v78
	v_cvt_pk_fp8_f32 v19, v64, v65
	v_fmac_f32_e32 v13, v68, v9
	v_mul_f32_dpp v14, v8, v57 row_ror:8 row_mask:0xf bank_mask:0xf bound_ctrl:1
	v_fmac_f32_e32 v14, v53, v8
	v_mov_b32_e32 v8, 0
	v_mov_b32_e32 v9, 0
	v_mul_f32_e32 v71, v15, v71
	v_cvt_pk_fp8_f32 v8, v21, v20
	v_cvt_pk_fp8_f32 v9, v12, v13
	v_mov_b32_dpp v82, v71 row_ror:8 row_mask:0xf bank_mask:0xf bound_ctrl:1
	v_mul_f32_e32 v64, v61, v71
	v_mul_f32_e32 v15, v15, v79
	v_fmac_f32_e32 v64, v69, v82
	v_cvt_pk_fp8_f32 v19, v70, v64 op_sel:[0,0,1]
	v_mul_f32_dpp v12, v15, v69 row_ror:8 row_mask:0xf bank_mask:0xf bound_ctrl:1
	v_fmac_f32_e32 v12, v61, v15
	v_cvt_pk_fp8_f32 v8, v10, v11 op_sel:[0,0,1]
	v_cvt_pk_fp8_f32 v9, v14, v12 op_sel:[0,0,1]
	v_add_co_u32_e32 v10, vcc, s0, v16
	s_nop 1
	v_addc_co_u32_e32 v11, vcc, 0, v17, vcc
	global_store_dwordx2 v[10:11], v[18:19], off
	global_store_dwordx2 v[10:11], v[8:9], off offset:512
	global_load_dwordx4 v[10:13], v[22:23], off offset:-2048
	s_nop 0
	global_load_dwordx4 v[14:17], v[22:23], off offset:-1024
	global_load_dwordx4 v[18:21], v[22:23], off
	global_load_dwordx4 v[60:63], v[22:23], off offset:1024
	v_lshl_add_u64 v[8:9], s[90:91], 0, v[48:49]
	global_load_dwordx4 v[64:67], v[8:9], off
	v_mov_b32_e32 v9, v52
	v_mov_b32_e32 v52, v59
	v_mov_b32_e32 v8, v58
	v_lshl_add_u64 v[22:23], s[90:91], 0, v[42:43]
	s_waitcnt vmcnt(4)
	v_mov_b32_dpp v70, v11 row_ror:8 row_mask:0xf bank_mask:0xf bound_ctrl:1
	v_mov_b32_dpp v71, v13 row_ror:8 row_mask:0xf bank_mask:0xf bound_ctrl:1
	v_mov_b32_dpp v68, v10 row_ror:8 row_mask:0xf bank_mask:0xf bound_ctrl:1
	v_mov_b32_dpp v69, v12 row_ror:8 row_mask:0xf bank_mask:0xf bound_ctrl:1
	v_mov_b32_e32 v72, v10
	v_mov_b32_e32 v73, v12
	v_mov_b32_e32 v12, v11
	v_pk_mul_f32 v[10:11], v[56:57], v[70:71]
	v_pk_mul_f32 v[68:69], v[54:55], v[68:69]
	v_pk_fma_f32 v[10:11], v[12:13], v[52:53], v[10:11]
	v_pk_fma_f32 v[68:69], v[72:73], v[8:9], v[68:69]
	v_cvt_pk_bf16_f32 v11, v69, v11
	v_cvt_pk_bf16_f32 v10, v68, v10
	global_store_dwordx2 v[22:23], v[10:11], off offset:-1024
	s_waitcnt vmcnt(4)
	v_mov_b32_dpp v11, v16 row_ror:8 row_mask:0xf bank_mask:0xf bound_ctrl:1
	v_mov_b32_dpp v10, v14 row_ror:8 row_mask:0xf bank_mask:0xf bound_ctrl:1
	v_mov_b32_dpp v12, v15 row_ror:8 row_mask:0xf bank_mask:0xf bound_ctrl:1
	v_mov_b32_dpp v13, v17 row_ror:8 row_mask:0xf bank_mask:0xf bound_ctrl:1
	v_mov_b32_e32 v58, v14
	v_mov_b32_e32 v59, v16
	v_pk_mul_f32 v[10:11], v[54:55], v[10:11]
	v_mov_b32_e32 v16, v15
	v_pk_fma_f32 v[10:11], v[58:59], v[8:9], v[10:11]
	v_pk_mul_f32 v[12:13], v[56:57], v[12:13]
	v_pk_fma_f32 v[12:13], v[16:17], v[52:53], v[12:13]
	v_cvt_pk_bf16_f32 v11, v11, v13
	v_cvt_pk_bf16_f32 v10, v10, v12
	global_store_dwordx2 v[22:23], v[10:11], off offset:-512
	s_waitcnt vmcnt(4)
; __device__ __forceinline__ unsigned pk2(float lo, float hi) { return f2bf(lo) | (f2bf(hi) << 16); }
; template <int CTRL> __device__ __forceinline__ float dpp_f(float v) { return __builtin_bit_cast(float, __builtin_amdgcn_update_dpp(0, __builtin_bit_cast(int, v), CTRL, 0xF, 0xF, true)); }
; __device__ __forceinline__ float row16_sum(float v) { v += dpp_f<0x128>(v); v += dpp_f<0x124>(v); v += dpp_f<0x4E>(v); v += dpp_f<0xB1>(v); return v; }
; __device__ __forceinline__ void post_token(int pos, const float* gaq, const float* gak, const float* gbq, const float* gbk, const float* gik, ...
;     ...
;     f32x4 xi[4];
; #pragma unroll
;     for (int it = 0; it < 4; ++it) xi[it] = *(const f32x4*)(irow + (it * 4 + grp) * 64 + 4 * c);
;     const f32x4 xk = *(const f32x4*)(irow + 1024 + 4 * c);
; #pragma unroll
;     for (int it = 0; it < 4; ++it) { float o[4];
; #pragma unroll
;         for (int e = 0; e < 4; ++e) { const float x = xi[it][e]; const float px = dpp_f<0x128>(x); o[e] = x * ci[e] + px * si[e]; }
;         u32x2 ow; ow.x = pk2(o[0], o[1]); ow.y = pk2(o[2], o[3]); *(u32x2*)(iq + (it * 4 + grp) * 64 + 4 * c) = ow; }
;     { const f32x4 gk = *(const f32x4*)(gik + 4 * c);
;       float ss = (xk[0] * xk[0] + xk[1] * xk[1]) + (xk[2] * xk[2] + xk[3] * xk[3]); ss = row16_sum(ss); const float r = 1.f / sqrtf(ss * (1.f / 64.f) + EPS);
;       float o[4];
; #pragma unroll
;       for (int e = 0; e < 4; ++e) { const float y = xk[e] * r * gk[e]; const float py = dpp_f<0x128>(y); o[e] = y * ci[e] + py * si[e]; }
;       if (grp == 0) { u32x2 ow; ow.x = pk2(o[0], o[1]); ow.y = pk2(o[2], o[3]); *(u32x2*)(ik + 4 * c) = ow; } }
;     if (lane < 16) iw[lane] = irow[1088 + lane] * 0.25f;
	v_mov_b32_dpp v11, v20 row_ror:8 row_mask:0xf bank_mask:0xf bound_ctrl:1
	v_mov_b32_dpp v10, v18 row_ror:8 row_mask:0xf bank_mask:0xf bound_ctrl:1
	v_mov_b32_dpp v12, v19 row_ror:8 row_mask:0xf bank_mask:0xf bound_ctrl:1
	v_mov_b32_dpp v13, v21 row_ror:8 row_mask:0xf bank_mask:0xf bound_ctrl:1
	v_mov_b32_e32 v14, v18
	v_mov_b32_e32 v15, v20
	v_pk_mul_f32 v[10:11], v[54:55], v[10:11]
	v_mov_b32_e32 v20, v19
	v_pk_fma_f32 v[10:11], v[8:9], v[14:15], v[10:11]
	v_pk_mul_f32 v[12:13], v[56:57], v[12:13]
	v_pk_fma_f32 v[12:13], v[20:21], v[52:53], v[12:13]
	v_cvt_pk_bf16_f32 v11, v11, v13
	v_cvt_pk_bf16_f32 v10, v10, v12
	global_store_dwordx2 v[22:23], v[10:11], off
	s_waitcnt vmcnt(4)
	v_mov_b32_dpp v11, v62 row_ror:8 row_mask:0xf bank_mask:0xf bound_ctrl:1
	v_mov_b32_dpp v10, v60 row_ror:8 row_mask:0xf bank_mask:0xf bound_ctrl:1
	v_mov_b32_dpp v12, v61 row_ror:8 row_mask:0xf bank_mask:0xf bound_ctrl:1
	v_mov_b32_dpp v13, v63 row_ror:8 row_mask:0xf bank_mask:0xf bound_ctrl:1
	v_mov_b32_e32 v14, v60
	v_mov_b32_e32 v15, v62
	v_pk_mul_f32 v[10:11], v[54:55], v[10:11]
	v_mov_b32_e32 v62, v61
	v_pk_fma_f32 v[10:11], v[8:9], v[14:15], v[10:11]
	v_pk_mul_f32 v[12:13], v[56:57], v[12:13]
	v_pk_fma_f32 v[12:13], v[52:53], v[62:63], v[12:13]
	v_cvt_pk_bf16_f32 v11, v11, v13
	v_cvt_pk_bf16_f32 v10, v10, v12
	global_store_dwordx2 v[22:23], v[10:11], off offset:512
	global_load_dwordx4 v[14:17], v[32:33], off
	s_waitcnt vmcnt(5)
	v_pk_mul_f32 v[10:11], v[66:67], v[66:67]
	v_pk_mul_f32 v[12:13], v[64:65], v[64:65]
	s_nop 0
	v_pk_mov_b32 v[18:19], v[12:13], v[10:11] op_sel:[1,0]
	v_mov_b32_e32 v13, v11
	v_pk_add_f32 v[10:11], v[18:19], v[12:13]
	s_nop 0
	v_add_f32_e32 v10, v10, v11
	s_nop 1
	v_add_f32_dpp v10, v10, v10 row_ror:8 row_mask:0xf bank_mask:0xf bound_ctrl:1
	s_nop 1
	v_add_f32_dpp v10, v10, v10 row_ror:4 row_mask:0xf bank_mask:0xf bound_ctrl:1
	s_nop 1
	v_add_f32_dpp v10, v10, v10 quad_perm:[2,3,0,1] row_mask:0xf bank_mask:0xf bound_ctrl:1
	s_nop 1
	v_add_f32_dpp v10, v10, v10 quad_perm:[1,0,3,2] row_mask:0xf bank_mask:0xf bound_ctrl:1
	v_fmamk_f32 v10, v10, 0x3c800000, v205
	v_mul_f32_e32 v11, 0x4f800000, v10
	v_cmp_gt_f32_e32 vcc, s8, v10
	s_nop 1
	v_cndmask_b32_e32 v10, v10, v11, vcc
	v_sqrt_f32_e32 v11, v10
	s_nop 0
	v_add_u32_e32 v12, -1, v11
	v_fma_f32 v13, -v12, v11, v10
	v_cmp_ge_f32_e64 s[0:1], 0, v13
	v_add_u32_e32 v13, 1, v11
	s_nop 0
	v_cndmask_b32_e64 v12, v11, v12, s[0:1]
	v_fma_f32 v11, -v13, v11, v10
	v_cmp_lt_f32_e64 s[0:1], 0, v11
	s_nop 1
	v_cndmask_b32_e64 v11, v12, v13, s[0:1]
	v_mul_f32_e32 v12, 0x37800000, v11
	v_cndmask_b32_e32 v11, v11, v12, vcc
	v_cmp_class_f32_e32 vcc, v10, v206
	s_nop 1
	v_cndmask_b32_e32 v10, v11, v10, vcc
	v_div_scale_f32 v11, s[0:1], v10, v10, 1.0
	v_rcp_f32_e32 v12, v11
	s_nop 0
	v_fma_f32 v13, -v11, v12, 1.0
	v_fmac_f32_e32 v12, v13, v12
	v_div_scale_f32 v13, vcc, 1.0, v10, 1.0
	v_mul_f32_e32 v18, v13, v12
	v_fma_f32 v19, -v11, v18, v13
	v_fmac_f32_e32 v18, v19, v12
	v_fma_f32 v11, -v11, v18, v13
	v_div_fmas_f32 v11, v11, v12, v18
	v_div_fixup_f32 v18, v11, v10, 1.0
	v_mov_b32_e32 v10, v64
	v_mov_b32_e32 v11, v66
	v_mov_b32_e32 v66, v65
	v_pk_mul_f32 v[10:11], v[10:11], v[18:19] op_sel_hi:[1,0]
	v_pk_mul_f32 v[18:19], v[66:67], v[18:19] op_sel_hi:[1,0]
	s_waitcnt vmcnt(0)
	v_mov_b32_e32 v12, v14
	v_mov_b32_e32 v13, v16
	v_mov_b32_e32 v16, v15
	v_pk_mul_f32 v[12:13], v[12:13], v[10:11]
	v_pk_mul_f32 v[16:17], v[16:17], v[18:19]
	s_nop 0
	v_mov_b32_dpp v10, v12 row_ror:8 row_mask:0xf bank_mask:0xf bound_ctrl:1
	v_mov_b32_dpp v14, v16 row_ror:8 row_mask:0xf bank_mask:0xf bound_ctrl:1
	v_mov_b32_dpp v11, v13 row_ror:8 row_mask:0xf bank_mask:0xf bound_ctrl:1
	v_mov_b32_dpp v15, v17 row_ror:8 row_mask:0xf bank_mask:0xf bound_ctrl:1
	s_and_saveexec_b64 s[0:1], s[38:39]
	s_cbranch_execz .LBB0_1007
	v_pk_mul_f32 v[8:9], v[8:9], v[12:13]
	v_pk_mul_f32 v[16:17], v[52:53], v[16:17]
	v_pk_fma_f32 v[8:9], v[54:55], v[10:11], v[8:9]
	v_pk_fma_f32 v[12:13], v[56:57], v[14:15], v[16:17]
	v_cvt_pk_bf16_f32 v9, v9, v13
	v_cvt_pk_bf16_f32 v8, v8, v12
	v_lshl_add_u64 v[10:11], s[90:91], 0, v[38:39]
	global_store_dwordx2 v[10:11], v[8:9], off
	v_lshl_add_u64 v[8:9], s[90:91], 0, v[50:51]
	global_load_dword v10, v[8:9], off
	v_lshl_add_u64 v[8:9], s[90:91], 0, v[36:37]
	s_waitcnt vmcnt(0)
	v_mul_f32_e32 v10, 0x3e800000, v10
	global_store_dword v[8:9], v10, off
	s_branch .LBB0_1007

; __device__ __forceinline__ unsigned pk2(float lo, float hi) { return f2bf(lo) | (f2bf(hi) << 16); }
;     __device__ __forceinline__ void operator()(const f32x4 (&acc)[2][2][4][2], const pg8::Unit& u, int wr, int wc, int fr, int fq) const {
;     ...
;                     } else if constexpr (MODE == 1) {
;                         const f32x4 b0 = *(const f32x4*)(vec + col), b1 = *(const f32x4*)(vec + col + 4);
;                         float r[8];
; #pragma unroll
;                         for (int i = 0; i < 4; ++i) { r[i] = 1.f / (1.f + __expf(-(v0[i] + b0[i]))); r[4 + i] = 1.f / (1.f + __expf(-(v1[i] + b1[i]))); }
;                         u32x4 w; w.x = pk2(r[0], r[1]); w.y = pk2(r[2], r[3]); w.z = pk2(r[4], r[5]); w.w = pk2(r[6], r[7]);
;                         *(u32x4*)(ob + row * 4096 + col) = w;
.LBB0_1125:
	v_lshl_or_b32 v2, s8, 8, v214
	v_ashrrev_i32_e32 v3, 31, v2
	v_lshl_add_u64 v[0:1], v[2:3], 2, s[4:5]
	s_nop 15
	s_nop 15
	global_load_dwordx4 v[10:13], v[0:1], off offset:16
	global_load_dwordx4 v[14:17], v[0:1], off
	v_lshl_add_u32 v4, s9, 8, v203
	v_ashrrev_i32_e32 v5, 31, v4
	v_lshlrev_b64 v[6:7], 13, v[4:5]
	s_mov_b64 s[10:11], -1
	s_waitcnt vmcnt(0)
	v_fmac_f32_e32 v13, 0x3c800000, v155
	v_fmamk_f32 v5, v156, 0x3c800000, v14
	v_mul_f32_e32 v5, 0xbfb8aa3b, v5
	v_exp_f32_e32 v14, v5
	v_fmamk_f32 v5, v152, 0x3c800000, v10
	v_mul_f32_e32 v5, 0xbfb8aa3b, v5
	v_exp_f32_e32 v10, v5
	v_fmamk_f32 v5, v157, 0x3c800000, v15
	v_mul_f32_e32 v5, 0xbfb8aa3b, v5
	v_exp_f32_e32 v18, v5
	v_fmamk_f32 v5, v153, 0x3c800000, v11
	v_mul_f32_e32 v5, 0xbfb8aa3b, v5
	v_exp_f32_e32 v8, v5
	v_fmamk_f32 v5, v158, 0x3c800000, v16
	v_mul_f32_e32 v5, 0xbfb8aa3b, v5
	v_exp_f32_e32 v15, v5
	v_fmamk_f32 v5, v154, 0x3c800000, v12
	v_mul_f32_e32 v5, 0xbfb8aa3b, v5
	v_fmac_f32_e32 v17, 0x3c800000, v159
	v_exp_f32_e32 v11, v5
	v_mul_f32_e32 v5, 0xbfb8aa3b, v17
	v_exp_f32_e32 v19, v5
	v_mul_f32_e32 v5, 0xbfb8aa3b, v13
	v_pk_add_f32 v[12:13], v[14:15], 1.0 op_sel_hi:[1,0]
	v_exp_f32_e32 v9, v5
	v_pk_add_f32 v[10:11], v[10:11], 1.0 op_sel_hi:[1,0]
	v_pk_add_f32 v[8:9], v[8:9], 1.0 op_sel_hi:[1,0]
	v_rcp_f32_e32 v5, v13
	v_pk_add_f32 v[14:15], v[18:19], 1.0 op_sel_hi:[1,0]
	v_rcp_f32_e32 v12, v12
	v_rcp_f32_e32 v13, v14
	v_rcp_f32_e32 v14, v15
	v_rcp_f32_e32 v11, v11
	v_rcp_f32_e32 v10, v10
	v_rcp_f32_e32 v8, v8
	v_rcp_f32_e32 v9, v9
	v_cvt_pk_bf16_f32 v10, v10, v8
	v_cvt_pk_bf16_f32 v8, v12, v13
	v_lshl_add_u64 v[12:13], s[24:25], 0, v[6:7]
	v_lshlrev_b64 v[6:7], 1, v[2:3]
	v_cvt_pk_bf16_f32 v11, v11, v9
	v_cvt_pk_bf16_f32 v9, v5, v14
	v_lshl_add_u64 v[2:3], v[12:13], 0, v[6:7]
	global_store_dwordx4 v[2:3], v[8:11], off
	global_load_dwordx4 v[10:13], v[0:1], off offset:528
	s_nop 0
	global_load_dwordx4 v[14:17], v[0:1], off offset:512
	s_waitcnt vmcnt(1)
	v_fmac_f32_e32 v13, 0x3c800000, v147
	s_waitcnt vmcnt(0)
	v_fmamk_f32 v5, v148, 0x3c800000, v14
	v_mul_f32_e32 v5, 0xbfb8aa3b, v5
	v_exp_f32_e32 v14, v5
	v_fmamk_f32 v5, v144, 0x3c800000, v10
	v_mul_f32_e32 v5, 0xbfb8aa3b, v5
	v_exp_f32_e32 v10, v5
	v_fmamk_f32 v5, v149, 0x3c800000, v15
	v_mul_f32_e32 v5, 0xbfb8aa3b, v5
	v_exp_f32_e32 v18, v5
	v_fmamk_f32 v5, v145, 0x3c800000, v11
	v_mul_f32_e32 v5, 0xbfb8aa3b, v5
	v_exp_f32_e32 v8, v5
	v_fmamk_f32 v5, v150, 0x3c800000, v16
	v_mul_f32_e32 v5, 0xbfb8aa3b, v5
	v_exp_f32_e32 v15, v5
	v_fmamk_f32 v5, v146, 0x3c800000, v12
	v_mul_f32_e32 v5, 0xbfb8aa3b, v5
	v_fmac_f32_e32 v17, 0x3c800000, v151
	v_exp_f32_e32 v11, v5
	v_mul_f32_e32 v5, 0xbfb8aa3b, v17
	v_exp_f32_e32 v19, v5
	v_mul_f32_e32 v5, 0xbfb8aa3b, v13
	v_pk_add_f32 v[12:13], v[14:15], 1.0 op_sel_hi:[1,0]
	v_exp_f32_e32 v9, v5
	v_pk_add_f32 v[10:11], v[10:11], 1.0 op_sel_hi:[1,0]
	v_pk_add_f32 v[8:9], v[8:9], 1.0 op_sel_hi:[1,0]
	v_rcp_f32_e32 v5, v13
	v_rcp_f32_e32 v14, v12
	v_pk_add_f32 v[12:13], v[18:19], 1.0 op_sel_hi:[1,0]
	s_nop 0
	v_rcp_f32_e32 v12, v12
	v_rcp_f32_e32 v13, v13
	v_rcp_f32_e32 v11, v11
	v_rcp_f32_e32 v10, v10
	v_rcp_f32_e32 v8, v8
	v_rcp_f32_e32 v9, v9
	s_nop 0
	v_cvt_pk_bf16_f32 v11, v11, v9
	v_cvt_pk_bf16_f32 v10, v10, v8
	v_cvt_pk_bf16_f32 v9, v5, v13
	v_cvt_pk_bf16_f32 v8, v14, v12
	global_store_dwordx4 v[2:3], v[8:11], off offset:256
	global_load_dwordx4 v[10:13], v[0:1], off offset:16
	s_nop 0
	global_load_dwordx4 v[14:17], v[0:1], off
	v_or_b32_e32 v8, 16, v4
	v_ashrrev_i32_e32 v9, 31, v8
	v_lshlrev_b64 v[8:9], 13, v[8:9]
	v_lshl_add_u64 v[8:9], s[24:25], 0, v[8:9]
	v_lshl_add_u64 v[8:9], v[8:9], 0, v[6:7]
	s_waitcnt vmcnt(1)
	v_fmac_f32_e32 v13, 0x3c800000, v139
	s_waitcnt vmcnt(0)
	v_fmamk_f32 v5, v140, 0x3c800000, v14
	v_mul_f32_e32 v5, 0xbfb8aa3b, v5
	v_exp_f32_e32 v14, v5
	v_fmamk_f32 v5, v136, 0x3c800000, v10
	v_mul_f32_e32 v5, 0xbfb8aa3b, v5
	v_exp_f32_e32 v18, v5
	v_fmamk_f32 v5, v141, 0x3c800000, v15
	v_mul_f32_e32 v5, 0xbfb8aa3b, v5
	v_exp_f32_e32 v20, v5
	v_fmamk_f32 v5, v137, 0x3c800000, v11
	v_mul_f32_e32 v5, 0xbfb8aa3b, v5
	v_exp_f32_e32 v10, v5
	v_fmamk_f32 v5, v142, 0x3c800000, v16
	v_mul_f32_e32 v5, 0xbfb8aa3b, v5
	v_exp_f32_e32 v15, v5
	v_fmamk_f32 v5, v138, 0x3c800000, v12
	v_mul_f32_e32 v5, 0xbfb8aa3b, v5
	v_fmac_f32_e32 v17, 0x3c800000, v143
	v_exp_f32_e32 v19, v5
	v_mul_f32_e32 v5, 0xbfb8aa3b, v17
	v_exp_f32_e32 v21, v5
	v_mul_f32_e32 v5, 0xbfb8aa3b, v13
	v_pk_add_f32 v[12:13], v[14:15], 1.0 op_sel_hi:[1,0]
	v_exp_f32_e32 v11, v5
	s_nop 0
	v_pk_add_f32 v[10:11], v[10:11], 1.0 op_sel_hi:[1,0]
	v_rcp_f32_e32 v5, v13
	v_rcp_f32_e32 v14, v12
	v_pk_add_f32 v[12:13], v[20:21], 1.0 op_sel_hi:[1,0]
	s_nop 0
	v_rcp_f32_e32 v15, v12
	v_rcp_f32_e32 v16, v13
	v_pk_add_f32 v[12:13], v[18:19], 1.0 op_sel_hi:[1,0]
	s_nop 0
	v_rcp_f32_e32 v13, v13
	v_rcp_f32_e32 v12, v12
	v_rcp_f32_e32 v10, v10
	v_rcp_f32_e32 v11, v11
	s_nop 0
	v_cvt_pk_bf16_f32 v13, v13, v11
	v_cvt_pk_bf16_f32 v12, v12, v10
	v_cvt_pk_bf16_f32 v11, v5, v16
	v_cvt_pk_bf16_f32 v10, v14, v15
	global_store_dwordx4 v[8:9], v[10:13], off
	global_load_dwordx4 v[10:13], v[0:1], off offset:528
	s_nop 0
	global_load_dwordx4 v[14:17], v[0:1], off offset:512
	s_waitcnt vmcnt(1)
	v_fmac_f32_e32 v13, 0x3c800000, v131
	s_waitcnt vmcnt(0)
; __device__ __forceinline__ unsigned pk2(float lo, float hi) { return f2bf(lo) | (f2bf(hi) << 16); }
;     __device__ __forceinline__ void operator()(const f32x4 (&acc)[2][2][4][2], const pg8::Unit& u, int wr, int wc, int fr, int fq) const {
;     ...
;                     } else if constexpr (MODE == 1) {
;                         const f32x4 b0 = *(const f32x4*)(vec + col), b1 = *(const f32x4*)(vec + col + 4);
;                         float r[8];
; #pragma unroll
;                         for (int i = 0; i < 4; ++i) { r[i] = 1.f / (1.f + __expf(-(v0[i] + b0[i]))); r[4 + i] = 1.f / (1.f + __expf(-(v1[i] + b1[i]))); }
;                         u32x4 w; w.x = pk2(r[0], r[1]); w.y = pk2(r[2], r[3]); w.z = pk2(r[4], r[5]); w.w = pk2(r[6], r[7]);
;                         *(u32x4*)(ob + row * 4096 + col) = w;
	v_fmamk_f32 v5, v132, 0x3c800000, v14
	v_mul_f32_e32 v5, 0xbfb8aa3b, v5
	v_exp_f32_e32 v14, v5
	v_fmamk_f32 v5, v128, 0x3c800000, v10
	v_mul_f32_e32 v5, 0xbfb8aa3b, v5
	v_exp_f32_e32 v18, v5
	v_fmamk_f32 v5, v133, 0x3c800000, v15
	v_mul_f32_e32 v5, 0xbfb8aa3b, v5
	v_exp_f32_e32 v20, v5
	v_fmamk_f32 v5, v129, 0x3c800000, v11
	v_mul_f32_e32 v5, 0xbfb8aa3b, v5
	v_exp_f32_e32 v10, v5
	v_fmamk_f32 v5, v134, 0x3c800000, v16
	v_mul_f32_e32 v5, 0xbfb8aa3b, v5
	v_exp_f32_e32 v15, v5
	v_fmamk_f32 v5, v130, 0x3c800000, v12
	v_mul_f32_e32 v5, 0xbfb8aa3b, v5
	v_fmac_f32_e32 v17, 0x3c800000, v135
	v_exp_f32_e32 v19, v5
	v_mul_f32_e32 v5, 0xbfb8aa3b, v17
	v_exp_f32_e32 v21, v5
	v_mul_f32_e32 v5, 0xbfb8aa3b, v13
	v_pk_add_f32 v[12:13], v[14:15], 1.0 op_sel_hi:[1,0]
	v_exp_f32_e32 v11, v5
	s_nop 0
	v_pk_add_f32 v[10:11], v[10:11], 1.0 op_sel_hi:[1,0]
	v_rcp_f32_e32 v5, v13
	v_rcp_f32_e32 v14, v12
	v_pk_add_f32 v[12:13], v[20:21], 1.0 op_sel_hi:[1,0]
	s_nop 0
	v_rcp_f32_e32 v15, v12
	v_rcp_f32_e32 v16, v13
	v_pk_add_f32 v[12:13], v[18:19], 1.0 op_sel_hi:[1,0]
	s_nop 0
	v_rcp_f32_e32 v13, v13
	v_rcp_f32_e32 v12, v12
	v_rcp_f32_e32 v10, v10
	v_rcp_f32_e32 v11, v11
	s_nop 0
	v_cvt_pk_bf16_f32 v13, v13, v11
	v_cvt_pk_bf16_f32 v12, v12, v10
	v_cvt_pk_bf16_f32 v11, v5, v16
	v_cvt_pk_bf16_f32 v10, v14, v15
	global_store_dwordx4 v[8:9], v[10:13], off offset:256
	global_load_dwordx4 v[10:13], v[0:1], off offset:16
	s_nop 0
	global_load_dwordx4 v[14:17], v[0:1], off
	v_or_b32_e32 v8, 32, v4
	v_ashrrev_i32_e32 v9, 31, v8
	v_lshlrev_b64 v[8:9], 13, v[8:9]
	v_lshl_add_u64 v[8:9], s[24:25], 0, v[8:9]
	v_lshl_add_u64 v[8:9], v[8:9], 0, v[6:7]
	v_or_b32_e32 v4, 48, v4
	s_waitcnt vmcnt(1)
	v_fmac_f32_e32 v13, 0x3c800000, v123
	s_waitcnt vmcnt(0)
	v_fmamk_f32 v5, v124, 0x3c800000, v14
	v_mul_f32_e32 v5, 0xbfb8aa3b, v5
	v_exp_f32_e32 v14, v5
	v_fmamk_f32 v5, v120, 0x3c800000, v10
	v_mul_f32_e32 v5, 0xbfb8aa3b, v5
	v_exp_f32_e32 v18, v5
	v_fmamk_f32 v5, v125, 0x3c800000, v15
	v_mul_f32_e32 v5, 0xbfb8aa3b, v5
	v_exp_f32_e32 v20, v5
	v_fmamk_f32 v5, v121, 0x3c800000, v11
	v_mul_f32_e32 v5, 0xbfb8aa3b, v5
	v_exp_f32_e32 v10, v5
	v_fmamk_f32 v5, v126, 0x3c800000, v16
	v_mul_f32_e32 v5, 0xbfb8aa3b, v5
	v_exp_f32_e32 v15, v5
	v_fmamk_f32 v5, v122, 0x3c800000, v12
	v_mul_f32_e32 v5, 0xbfb8aa3b, v5
	v_fmac_f32_e32 v17, 0x3c800000, v127
	v_exp_f32_e32 v19, v5
	v_mul_f32_e32 v5, 0xbfb8aa3b, v17
	v_exp_f32_e32 v21, v5
	v_mul_f32_e32 v5, 0xbfb8aa3b, v13
	v_pk_add_f32 v[12:13], v[14:15], 1.0 op_sel_hi:[1,0]
	v_exp_f32_e32 v11, v5
	s_nop 0
	v_pk_add_f32 v[10:11], v[10:11], 1.0 op_sel_hi:[1,0]
	v_rcp_f32_e32 v5, v13
	v_rcp_f32_e32 v14, v12
	v_pk_add_f32 v[12:13], v[20:21], 1.0 op_sel_hi:[1,0]
	s_nop 0
	v_rcp_f32_e32 v15, v12
	v_rcp_f32_e32 v16, v13
	v_pk_add_f32 v[12:13], v[18:19], 1.0 op_sel_hi:[1,0]
	s_nop 0
	v_rcp_f32_e32 v13, v13
	v_rcp_f32_e32 v12, v12
	v_rcp_f32_e32 v10, v10
	v_rcp_f32_e32 v11, v11
	s_nop 0
	v_cvt_pk_bf16_f32 v13, v13, v11
	v_cvt_pk_bf16_f32 v12, v12, v10
	v_cvt_pk_bf16_f32 v11, v5, v16
	v_cvt_pk_bf16_f32 v10, v14, v15
	global_store_dwordx4 v[8:9], v[10:13], off
	global_load_dwordx4 v[10:13], v[0:1], off offset:528
	s_nop 0
	global_load_dwordx4 v[14:17], v[0:1], off offset:512
	s_waitcnt vmcnt(1)
	v_fmac_f32_e32 v13, 0x3c800000, v115
	s_waitcnt vmcnt(0)
	v_fmamk_f32 v5, v116, 0x3c800000, v14
	v_mul_f32_e32 v5, 0xbfb8aa3b, v5
	v_exp_f32_e32 v14, v5
	v_fmamk_f32 v5, v112, 0x3c800000, v10
	v_mul_f32_e32 v5, 0xbfb8aa3b, v5
	v_exp_f32_e32 v18, v5
	v_fmamk_f32 v5, v117, 0x3c800000, v15
	v_mul_f32_e32 v5, 0xbfb8aa3b, v5
	v_exp_f32_e32 v20, v5
	v_fmamk_f32 v5, v113, 0x3c800000, v11
	v_mul_f32_e32 v5, 0xbfb8aa3b, v5
	v_exp_f32_e32 v10, v5
	v_fmamk_f32 v5, v118, 0x3c800000, v16
	v_mul_f32_e32 v5, 0xbfb8aa3b, v5
	v_exp_f32_e32 v15, v5
	v_fmamk_f32 v5, v114, 0x3c800000, v12
	v_mul_f32_e32 v5, 0xbfb8aa3b, v5
	v_fmac_f32_e32 v17, 0x3c800000, v119
	v_exp_f32_e32 v19, v5
	v_mul_f32_e32 v5, 0xbfb8aa3b, v17
	v_exp_f32_e32 v21, v5
	v_mul_f32_e32 v5, 0xbfb8aa3b, v13
	v_pk_add_f32 v[12:13], v[14:15], 1.0 op_sel_hi:[1,0]
	v_exp_f32_e32 v11, v5
	s_nop 0
	v_pk_add_f32 v[10:11], v[10:11], 1.0 op_sel_hi:[1,0]
	v_rcp_f32_e32 v5, v13
	v_rcp_f32_e32 v14, v12
	v_pk_add_f32 v[12:13], v[20:21], 1.0 op_sel_hi:[1,0]
	s_nop 0
	v_rcp_f32_e32 v15, v12
	v_rcp_f32_e32 v16, v13
	v_pk_add_f32 v[12:13], v[18:19], 1.0 op_sel_hi:[1,0]
	s_nop 0
	v_rcp_f32_e32 v13, v13
	v_rcp_f32_e32 v12, v12
	v_rcp_f32_e32 v10, v10
	v_div_scale_f32 v17, s[8:9], v11, v11, 1.0
	v_rcp_f32_e32 v18, v17
	s_nop 0
	v_fma_f32 v19, -v17, v18, 1.0
	v_fmac_f32_e32 v18, v19, v18
	v_div_scale_f32 v19, vcc, 1.0, v11, 1.0
	v_mul_f32_e32 v20, v19, v18
	v_fma_f32 v21, -v17, v20, v19
	v_rcp_f32_e32 v11, v11
	s_nop 0
	v_cvt_pk_bf16_f32 v13, v13, v11
	v_cvt_pk_bf16_f32 v12, v12, v10
	v_cvt_pk_bf16_f32 v11, v5, v16
	v_cvt_pk_bf16_f32 v10, v14, v15
	global_store_dwordx4 v[8:9], v[10:13], off offset:256
	global_load_dwordx4 v[8:11], v[0:1], off offset:16
	s_nop 0
	global_load_dwordx4 v[12:15], v[0:1], off
	v_ashrrev_i32_e32 v5, 31, v4
	v_lshlrev_b64 v[4:5], 13, v[4:5]
	v_lshl_add_u64 v[4:5], s[24:25], 0, v[4:5]
	v_lshl_add_u64 v[4:5], v[4:5], 0, v[6:7]
	s_waitcnt vmcnt(1)
	v_fmamk_f32 v8, v104, 0x3c800000, v8
	v_mul_f32_e32 v8, 0xbfb8aa3b, v8
	v_exp_f32_e32 v16, v8
	s_waitcnt vmcnt(0)
; __device__ __forceinline__ unsigned pk2(float lo, float hi) { return f2bf(lo) | (f2bf(hi) << 16); }
;     __device__ __forceinline__ void operator()(const f32x4 (&acc)[2][2][4][2], const pg8::Unit& u, int wr, int wc, int fr, int fq) const {
;     ...
;                     } else if constexpr (MODE == 1) {
;                         const f32x4 b0 = *(const f32x4*)(vec + col), b1 = *(const f32x4*)(vec + col + 4);
;                         float r[8];
; #pragma unroll
;                         for (int i = 0; i < 4; ++i) { r[i] = 1.f / (1.f + __expf(-(v0[i] + b0[i]))); r[4 + i] = 1.f / (1.f + __expf(-(v1[i] + b1[i]))); }
;                         u32x4 w; w.x = pk2(r[0], r[1]); w.y = pk2(r[2], r[3]); w.z = pk2(r[4], r[5]); w.w = pk2(r[6], r[7]);
;                         *(u32x4*)(ob + row * 4096 + col) = w;
	v_fmamk_f32 v8, v109, 0x3c800000, v13
	v_mul_f32_e32 v8, 0xbfb8aa3b, v8
	v_fmamk_f32 v12, v108, 0x3c800000, v12
	v_exp_f32_e32 v18, v8
	v_fmamk_f32 v8, v105, 0x3c800000, v9
	v_fmamk_f32 v9, v110, 0x3c800000, v14
	v_mul_f32_e32 v12, 0xbfb8aa3b, v12
	v_mul_f32_e32 v9, 0xbfb8aa3b, v9
	v_exp_f32_e32 v12, v12
	v_exp_f32_e32 v13, v9
	v_fmamk_f32 v9, v106, 0x3c800000, v10
	v_mul_f32_e32 v9, 0xbfb8aa3b, v9
	v_fmac_f32_e32 v15, 0x3c800000, v111
	v_exp_f32_e32 v17, v9
	v_mul_f32_e32 v9, 0xbfb8aa3b, v15
	v_fmac_f32_e32 v11, 0x3c800000, v107
	v_exp_f32_e32 v19, v9
	v_mul_f32_e32 v9, 0xbfb8aa3b, v11
	v_pk_add_f32 v[10:11], v[12:13], 1.0 op_sel_hi:[1,0]
	v_mul_f32_e32 v8, 0xbfb8aa3b, v8
	v_exp_f32_e32 v8, v8
	v_exp_f32_e32 v9, v9
	v_rcp_f32_e32 v12, v11
	v_pk_add_f32 v[8:9], v[8:9], 1.0 op_sel_hi:[1,0]
	v_rcp_f32_e32 v13, v10
	v_pk_add_f32 v[10:11], v[18:19], 1.0 op_sel_hi:[1,0]
	s_nop 0
	v_rcp_f32_e32 v14, v10
	v_rcp_f32_e32 v15, v11
	v_pk_add_f32 v[10:11], v[16:17], 1.0 op_sel_hi:[1,0]
	s_nop 0
	v_rcp_f32_e32 v11, v11
	v_rcp_f32_e32 v10, v10
	v_rcp_f32_e32 v8, v8
	v_div_scale_f32 v16, s[8:9], v9, v9, 1.0
	v_rcp_f32_e32 v17, v16
	s_nop 0
	v_fma_f32 v18, -v16, v17, 1.0
	v_fmac_f32_e32 v17, v18, v17
	v_div_scale_f32 v18, vcc, 1.0, v9, 1.0
	v_mul_f32_e32 v19, v18, v17
	v_fma_f32 v20, -v16, v19, v18
	v_fmac_f32_e32 v19, v20, v17
	v_rcp_f32_e32 v9, v9
	s_nop 0
	v_cvt_pk_bf16_f32 v11, v11, v9
	v_cvt_pk_bf16_f32 v10, v10, v8
	v_cvt_pk_bf16_f32 v9, v12, v15
	v_cvt_pk_bf16_f32 v8, v13, v14
	global_store_dwordx4 v[4:5], v[8:11], off
	global_load_dwordx4 v[6:9], v[0:1], off offset:528
	s_nop 0
	global_load_dwordx4 v[10:13], v[0:1], off offset:512
	s_waitcnt vmcnt(1)
	v_fmamk_f32 v6, v96, 0x3c800000, v6
	v_mul_f32_e32 v6, 0xbfb8aa3b, v6
	v_exp_f32_e32 v14, v6
	s_waitcnt vmcnt(0)
	v_fmamk_f32 v6, v101, 0x3c800000, v11
	v_mul_f32_e32 v6, 0xbfb8aa3b, v6
	v_fmamk_f32 v10, v100, 0x3c800000, v10
	v_exp_f32_e32 v16, v6
	v_fmamk_f32 v6, v97, 0x3c800000, v7
	v_fmamk_f32 v7, v102, 0x3c800000, v12
	v_mul_f32_e32 v10, 0xbfb8aa3b, v10
	v_mul_f32_e32 v7, 0xbfb8aa3b, v7
	v_exp_f32_e32 v10, v10
	v_exp_f32_e32 v11, v7
	v_fmamk_f32 v7, v98, 0x3c800000, v8
	v_mul_f32_e32 v7, 0xbfb8aa3b, v7
	v_fmac_f32_e32 v13, 0x3c800000, v103
	v_exp_f32_e32 v15, v7
	v_mul_f32_e32 v7, 0xbfb8aa3b, v13
	v_fmac_f32_e32 v9, 0x3c800000, v99
	v_exp_f32_e32 v17, v7
	v_mul_f32_e32 v7, 0xbfb8aa3b, v9
	v_pk_add_f32 v[8:9], v[10:11], 1.0 op_sel_hi:[1,0]
	v_mul_f32_e32 v6, 0xbfb8aa3b, v6
	v_exp_f32_e32 v6, v6
	v_exp_f32_e32 v7, v7
	v_rcp_f32_e32 v10, v9
	v_pk_add_f32 v[6:7], v[6:7], 1.0 op_sel_hi:[1,0]
	v_rcp_f32_e32 v11, v8
	v_pk_add_f32 v[8:9], v[16:17], 1.0 op_sel_hi:[1,0]
	s_nop 0
	v_rcp_f32_e32 v12, v8
	v_rcp_f32_e32 v13, v9
	v_pk_add_f32 v[8:9], v[14:15], 1.0 op_sel_hi:[1,0]
	s_nop 0
	v_rcp_f32_e32 v9, v9
	v_rcp_f32_e32 v8, v8
	v_rcp_f32_e32 v6, v6
	v_rcp_f32_e32 v7, v7
	s_nop 0
	v_cvt_pk_bf16_f32 v9, v9, v7
	v_cvt_pk_bf16_f32 v8, v8, v6
	v_cvt_pk_bf16_f32 v7, v10, v13
	v_cvt_pk_bf16_f32 v6, v11, v12
	global_store_dwordx4 v[4:5], v[6:9], off offset:256
	global_load_dwordx4 v[4:7], v[0:1], off offset:16
	s_nop 0
	global_load_dwordx4 v[8:11], v[0:1], off
	s_waitcnt vmcnt(1)
	v_fmamk_f32 v4, v88, 0x3c800000, v4
	v_mul_f32_e32 v4, 0xbfb8aa3b, v4
	v_exp_f32_e32 v12, v4
	s_waitcnt vmcnt(0)
	v_fmamk_f32 v4, v93, 0x3c800000, v9
	v_mul_f32_e32 v4, 0xbfb8aa3b, v4
	v_fmamk_f32 v8, v92, 0x3c800000, v8
	v_exp_f32_e32 v14, v4
	v_fmamk_f32 v4, v89, 0x3c800000, v5
	v_fmamk_f32 v5, v94, 0x3c800000, v10
	v_mul_f32_e32 v8, 0xbfb8aa3b, v8
	v_mul_f32_e32 v5, 0xbfb8aa3b, v5
	v_exp_f32_e32 v8, v8
	v_exp_f32_e32 v9, v5
	v_fmamk_f32 v5, v90, 0x3c800000, v6
	v_mul_f32_e32 v5, 0xbfb8aa3b, v5
	v_fmac_f32_e32 v11, 0x3c800000, v95
	v_exp_f32_e32 v13, v5
	v_mul_f32_e32 v5, 0xbfb8aa3b, v11
	v_fmac_f32_e32 v7, 0x3c800000, v91
	v_exp_f32_e32 v15, v5
	v_mul_f32_e32 v5, 0xbfb8aa3b, v7
	v_pk_add_f32 v[6:7], v[8:9], 1.0 op_sel_hi:[1,0]
	v_mul_f32_e32 v4, 0xbfb8aa3b, v4
	v_exp_f32_e32 v4, v4
	v_exp_f32_e32 v5, v5
	v_rcp_f32_e32 v8, v7
	v_pk_add_f32 v[4:5], v[4:5], 1.0 op_sel_hi:[1,0]
	v_rcp_f32_e32 v9, v6
	v_pk_add_f32 v[6:7], v[14:15], 1.0 op_sel_hi:[1,0]
	s_nop 0
	v_rcp_f32_e32 v10, v6
	v_rcp_f32_e32 v11, v7
	v_pk_add_f32 v[6:7], v[12:13], 1.0 op_sel_hi:[1,0]
	s_nop 0
	v_rcp_f32_e32 v7, v7
	v_rcp_f32_e32 v6, v6
	v_rcp_f32_e32 v4, v4
	s_mov_b64 s[8:9], 0x100000
	v_rcp_f32_e32 v5, v5
	v_bfe_u32 v14, v11, 16, 1
	v_bfe_u32 v15, v10, 16, 1
	v_add3_u32 v10, v10, v15, s33
	v_add3_u32 v11, v11, v14, s33
	v_bfe_u32 v12, v9, 16, 1
	v_bfe_u32 v13, v8, 16, 1
	v_add3_u32 v8, v8, v13, s33
	v_add3_u32 v9, v9, v12, s33
	v_lshrrev_b32_e32 v12, 16, v9
	v_lshrrev_b32_e32 v13, 16, v8
	v_cvt_pk_bf16_f32 v9, v7, v5
	v_cvt_pk_bf16_f32 v8, v6, v4
	v_lshl_add_u64 v[4:5], v[2:3], 0, s[8:9]
	s_mov_b32 s8, 0x100000
	v_and_or_b32 v6, v10, s67, v12
	v_add_co_u32_e32 v10, vcc, s8, v2
	v_and_or_b32 v7, v11, s67, v13
	s_nop 0
	v_addc_co_u32_e32 v11, vcc, 0, v3, vcc
	global_store_dwordx4 v[10:11], v[6:9], off
	global_load_dwordx4 v[6:9], v[0:1], off offset:528
	s_nop 0
	global_load_dwordx4 v[10:13], v[0:1], off offset:512
	s_waitcnt vmcnt(1)
	v_fmamk_f32 v6, v80, 0x3c800000, v6
	v_mul_f32_e32 v6, 0xbfb8aa3b, v6
	v_exp_f32_e32 v14, v6
	s_waitcnt vmcnt(0)
; __device__ __forceinline__ unsigned pk2(float lo, float hi) { return f2bf(lo) | (f2bf(hi) << 16); }
;     __device__ __forceinline__ void operator()(const f32x4 (&acc)[2][2][4][2], const pg8::Unit& u, int wr, int wc, int fr, int fq) const {
;     ...
;                     } else if constexpr (MODE == 1) {
;                         const f32x4 b0 = *(const f32x4*)(vec + col), b1 = *(const f32x4*)(vec + col + 4);
;                         float r[8];
; #pragma unroll
;                         for (int i = 0; i < 4; ++i) { r[i] = 1.f / (1.f + __expf(-(v0[i] + b0[i]))); r[4 + i] = 1.f / (1.f + __expf(-(v1[i] + b1[i]))); }
;                         u32x4 w; w.x = pk2(r[0], r[1]); w.y = pk2(r[2], r[3]); w.z = pk2(r[4], r[5]); w.w = pk2(r[6], r[7]);
;                         *(u32x4*)(ob + row * 4096 + col) = w;
	v_fmamk_f32 v6, v85, 0x3c800000, v11
	v_mul_f32_e32 v6, 0xbfb8aa3b, v6
	v_fmamk_f32 v10, v84, 0x3c800000, v10
	v_exp_f32_e32 v16, v6
	v_fmamk_f32 v6, v81, 0x3c800000, v7
	v_fmamk_f32 v7, v86, 0x3c800000, v12
	v_mul_f32_e32 v10, 0xbfb8aa3b, v10
	v_mul_f32_e32 v7, 0xbfb8aa3b, v7
	v_exp_f32_e32 v10, v10
	v_exp_f32_e32 v11, v7
	v_fmamk_f32 v7, v82, 0x3c800000, v8
	v_mul_f32_e32 v7, 0xbfb8aa3b, v7
	v_fmac_f32_e32 v13, 0x3c800000, v87
	v_exp_f32_e32 v15, v7
	v_mul_f32_e32 v7, 0xbfb8aa3b, v13
	v_fmac_f32_e32 v9, 0x3c800000, v83
	v_exp_f32_e32 v17, v7
	v_mul_f32_e32 v7, 0xbfb8aa3b, v9
	v_pk_add_f32 v[8:9], v[10:11], 1.0 op_sel_hi:[1,0]
	v_mul_f32_e32 v6, 0xbfb8aa3b, v6
	v_exp_f32_e32 v6, v6
	v_exp_f32_e32 v7, v7
	v_rcp_f32_e32 v10, v9
	v_pk_add_f32 v[6:7], v[6:7], 1.0 op_sel_hi:[1,0]
	v_rcp_f32_e32 v11, v8
	v_pk_add_f32 v[8:9], v[16:17], 1.0 op_sel_hi:[1,0]
	s_nop 0
	v_rcp_f32_e32 v12, v8
	v_rcp_f32_e32 v13, v9
	v_pk_add_f32 v[8:9], v[14:15], 1.0 op_sel_hi:[1,0]
	s_nop 0
	v_rcp_f32_e32 v9, v9
	v_rcp_f32_e32 v8, v8
	v_rcp_f32_e32 v6, v6
	v_rcp_f32_e32 v7, v7
	s_nop 0
	v_cvt_pk_bf16_f32 v9, v9, v7
	v_cvt_pk_bf16_f32 v8, v8, v6
	v_cvt_pk_bf16_f32 v7, v10, v13
	v_cvt_pk_bf16_f32 v6, v11, v12
	global_store_dwordx4 v[4:5], v[6:9], off offset:256
	global_load_dwordx4 v[4:7], v[0:1], off offset:16
	s_nop 0
	global_load_dwordx4 v[8:11], v[0:1], off
	s_waitcnt vmcnt(1)
	v_fmamk_f32 v4, v72, 0x3c800000, v4
	v_mul_f32_e32 v4, 0xbfb8aa3b, v4
	v_exp_f32_e32 v12, v4
	s_waitcnt vmcnt(0)
	v_fmamk_f32 v4, v77, 0x3c800000, v9
	v_mul_f32_e32 v4, 0xbfb8aa3b, v4
	v_fmamk_f32 v8, v76, 0x3c800000, v8
	v_exp_f32_e32 v14, v4
	v_fmamk_f32 v4, v73, 0x3c800000, v5
	v_fmamk_f32 v5, v78, 0x3c800000, v10
	v_mul_f32_e32 v8, 0xbfb8aa3b, v8
	v_mul_f32_e32 v5, 0xbfb8aa3b, v5
	v_exp_f32_e32 v8, v8
	v_exp_f32_e32 v9, v5
	v_fmamk_f32 v5, v74, 0x3c800000, v6
	v_mul_f32_e32 v5, 0xbfb8aa3b, v5
	v_fmac_f32_e32 v11, 0x3c800000, v79
	v_exp_f32_e32 v13, v5
	v_mul_f32_e32 v5, 0xbfb8aa3b, v11
	v_fmac_f32_e32 v7, 0x3c800000, v75
	v_exp_f32_e32 v15, v5
	v_mul_f32_e32 v5, 0xbfb8aa3b, v7
	v_pk_add_f32 v[6:7], v[8:9], 1.0 op_sel_hi:[1,0]
	v_mul_f32_e32 v4, 0xbfb8aa3b, v4
	v_exp_f32_e32 v4, v4
	v_exp_f32_e32 v5, v5
	v_rcp_f32_e32 v8, v7
	v_pk_add_f32 v[4:5], v[4:5], 1.0 op_sel_hi:[1,0]
	v_rcp_f32_e32 v9, v6
	v_pk_add_f32 v[6:7], v[14:15], 1.0 op_sel_hi:[1,0]
	s_nop 0
	v_rcp_f32_e32 v10, v6
	v_rcp_f32_e32 v11, v7
	v_pk_add_f32 v[6:7], v[12:13], 1.0 op_sel_hi:[1,0]
	s_nop 0
	v_rcp_f32_e32 v7, v7
	v_rcp_f32_e32 v6, v6
	v_rcp_f32_e32 v4, v4
	s_mov_b64 s[8:9], 0x120000
	v_rcp_f32_e32 v5, v5
	v_bfe_u32 v14, v11, 16, 1
	v_bfe_u32 v15, v10, 16, 1
	v_add3_u32 v10, v10, v15, s33
	v_add3_u32 v11, v11, v14, s33
	v_bfe_u32 v12, v9, 16, 1
	v_bfe_u32 v13, v8, 16, 1
	v_add3_u32 v8, v8, v13, s33
	v_add3_u32 v9, v9, v12, s33
	v_lshrrev_b32_e32 v12, 16, v9
	v_lshrrev_b32_e32 v13, 16, v8
	v_cvt_pk_bf16_f32 v9, v7, v5
	v_cvt_pk_bf16_f32 v8, v6, v4
	v_lshl_add_u64 v[4:5], v[2:3], 0, s[8:9]
	s_mov_b32 s8, 0x120000
	v_and_or_b32 v6, v10, s67, v12
	v_add_co_u32_e32 v10, vcc, s8, v2
	v_and_or_b32 v7, v11, s67, v13
	s_nop 0
	v_addc_co_u32_e32 v11, vcc, 0, v3, vcc
	global_store_dwordx4 v[10:11], v[6:9], off
	global_load_dwordx4 v[6:9], v[0:1], off offset:528
	s_nop 0
	global_load_dwordx4 v[10:13], v[0:1], off offset:512
	s_waitcnt vmcnt(1)
	v_fmamk_f32 v6, v64, 0x3c800000, v6
	v_mul_f32_e32 v6, 0xbfb8aa3b, v6
	v_exp_f32_e32 v14, v6
	s_waitcnt vmcnt(0)
	v_fmamk_f32 v6, v69, 0x3c800000, v11
	v_mul_f32_e32 v6, 0xbfb8aa3b, v6
	v_fmamk_f32 v10, v68, 0x3c800000, v10
	v_exp_f32_e32 v16, v6
	v_fmamk_f32 v6, v65, 0x3c800000, v7
	v_fmamk_f32 v7, v70, 0x3c800000, v12
	v_mul_f32_e32 v10, 0xbfb8aa3b, v10
	v_mul_f32_e32 v7, 0xbfb8aa3b, v7
	v_exp_f32_e32 v10, v10
	v_exp_f32_e32 v11, v7
	v_fmamk_f32 v7, v66, 0x3c800000, v8
	v_mul_f32_e32 v7, 0xbfb8aa3b, v7
	v_fmac_f32_e32 v13, 0x3c800000, v71
	v_exp_f32_e32 v15, v7
	v_mul_f32_e32 v7, 0xbfb8aa3b, v13
	v_fmac_f32_e32 v9, 0x3c800000, v67
	v_exp_f32_e32 v17, v7
	v_mul_f32_e32 v7, 0xbfb8aa3b, v9
	v_pk_add_f32 v[8:9], v[10:11], 1.0 op_sel_hi:[1,0]
	v_mul_f32_e32 v6, 0xbfb8aa3b, v6
	v_exp_f32_e32 v6, v6
	v_exp_f32_e32 v7, v7
	v_rcp_f32_e32 v10, v9
	v_pk_add_f32 v[6:7], v[6:7], 1.0 op_sel_hi:[1,0]
	v_rcp_f32_e32 v11, v8
	v_pk_add_f32 v[8:9], v[16:17], 1.0 op_sel_hi:[1,0]
	s_nop 0
	v_rcp_f32_e32 v12, v8
	v_rcp_f32_e32 v13, v9
	v_pk_add_f32 v[8:9], v[14:15], 1.0 op_sel_hi:[1,0]
	s_nop 0
	v_rcp_f32_e32 v9, v9
	v_rcp_f32_e32 v8, v8
	v_rcp_f32_e32 v6, v6
	v_rcp_f32_e32 v7, v7
	s_nop 0
	v_cvt_pk_bf16_f32 v9, v9, v7
	v_cvt_pk_bf16_f32 v8, v8, v6
	v_cvt_pk_bf16_f32 v7, v10, v13
	v_cvt_pk_bf16_f32 v6, v11, v12
	global_store_dwordx4 v[4:5], v[6:9], off offset:256
	global_load_dwordx4 v[4:7], v[0:1], off offset:16
	s_nop 0
	global_load_dwordx4 v[8:11], v[0:1], off
	s_waitcnt vmcnt(1)
	v_fmamk_f32 v4, v56, 0x3c800000, v4
	v_mul_f32_e32 v4, 0xbfb8aa3b, v4
	v_exp_f32_e32 v12, v4
	s_waitcnt vmcnt(0)
; __device__ __forceinline__ unsigned pk2(float lo, float hi) { return f2bf(lo) | (f2bf(hi) << 16); }
;     __device__ __forceinline__ void operator()(const f32x4 (&acc)[2][2][4][2], const pg8::Unit& u, int wr, int wc, int fr, int fq) const {
;     ...
;                     } else if constexpr (MODE == 1) {
;                         const f32x4 b0 = *(const f32x4*)(vec + col), b1 = *(const f32x4*)(vec + col + 4);
;                         float r[8];
; #pragma unroll
;                         for (int i = 0; i < 4; ++i) { r[i] = 1.f / (1.f + __expf(-(v0[i] + b0[i]))); r[4 + i] = 1.f / (1.f + __expf(-(v1[i] + b1[i]))); }
;                         u32x4 w; w.x = pk2(r[0], r[1]); w.y = pk2(r[2], r[3]); w.z = pk2(r[4], r[5]); w.w = pk2(r[6], r[7]);
;                         *(u32x4*)(ob + row * 4096 + col) = w;
	v_fmamk_f32 v4, v61, 0x3c800000, v9
	v_mul_f32_e32 v4, 0xbfb8aa3b, v4
	v_fmamk_f32 v8, v60, 0x3c800000, v8
	v_exp_f32_e32 v14, v4
	v_fmamk_f32 v4, v57, 0x3c800000, v5
	v_fmamk_f32 v5, v62, 0x3c800000, v10
	v_mul_f32_e32 v8, 0xbfb8aa3b, v8
	v_mul_f32_e32 v5, 0xbfb8aa3b, v5
	v_exp_f32_e32 v8, v8
	v_exp_f32_e32 v9, v5
	v_fmamk_f32 v5, v58, 0x3c800000, v6
	v_mul_f32_e32 v5, 0xbfb8aa3b, v5
	v_fmac_f32_e32 v11, 0x3c800000, v63
	v_exp_f32_e32 v13, v5
	v_mul_f32_e32 v5, 0xbfb8aa3b, v11
	v_fmac_f32_e32 v7, 0x3c800000, v59
	v_exp_f32_e32 v15, v5
	v_mul_f32_e32 v5, 0xbfb8aa3b, v7
	v_pk_add_f32 v[6:7], v[8:9], 1.0 op_sel_hi:[1,0]
	v_mul_f32_e32 v4, 0xbfb8aa3b, v4
	v_exp_f32_e32 v4, v4
	v_exp_f32_e32 v5, v5
	v_rcp_f32_e32 v8, v7
	v_pk_add_f32 v[4:5], v[4:5], 1.0 op_sel_hi:[1,0]
	v_rcp_f32_e32 v9, v6
	v_pk_add_f32 v[6:7], v[14:15], 1.0 op_sel_hi:[1,0]
	s_nop 0
	v_rcp_f32_e32 v10, v6
	v_rcp_f32_e32 v11, v7
	v_pk_add_f32 v[6:7], v[12:13], 1.0 op_sel_hi:[1,0]
	s_nop 0
	v_rcp_f32_e32 v7, v7
	v_rcp_f32_e32 v6, v6
	v_rcp_f32_e32 v4, v4
	s_mov_b64 s[8:9], 0x140000
	v_rcp_f32_e32 v5, v5
	v_bfe_u32 v14, v11, 16, 1
	v_bfe_u32 v15, v10, 16, 1
	v_add3_u32 v10, v10, v15, s33
	v_add3_u32 v11, v11, v14, s33
	v_bfe_u32 v12, v9, 16, 1
	v_bfe_u32 v13, v8, 16, 1
	v_add3_u32 v8, v8, v13, s33
	v_add3_u32 v9, v9, v12, s33
	v_lshrrev_b32_e32 v12, 16, v9
	v_lshrrev_b32_e32 v13, 16, v8
	v_cvt_pk_bf16_f32 v9, v7, v5
	v_cvt_pk_bf16_f32 v8, v6, v4
	v_lshl_add_u64 v[4:5], v[2:3], 0, s[8:9]
	s_mov_b32 s8, 0x140000
	v_and_or_b32 v6, v10, s67, v12
	v_add_co_u32_e32 v10, vcc, s8, v2
	v_and_or_b32 v7, v11, s67, v13
	s_nop 0
	v_addc_co_u32_e32 v11, vcc, 0, v3, vcc
	global_store_dwordx4 v[10:11], v[6:9], off
	global_load_dwordx4 v[6:9], v[0:1], off offset:528
	s_nop 0
	global_load_dwordx4 v[10:13], v[0:1], off offset:512
	s_waitcnt vmcnt(1)
	v_fmamk_f32 v6, v48, 0x3c800000, v6
	v_mul_f32_e32 v6, 0xbfb8aa3b, v6
	v_exp_f32_e32 v14, v6
	s_waitcnt vmcnt(0)
	v_fmamk_f32 v6, v53, 0x3c800000, v11
	v_mul_f32_e32 v6, 0xbfb8aa3b, v6
	v_fmamk_f32 v10, v52, 0x3c800000, v10
	v_exp_f32_e32 v16, v6
	v_fmamk_f32 v6, v49, 0x3c800000, v7
	v_fmamk_f32 v7, v54, 0x3c800000, v12
	v_mul_f32_e32 v10, 0xbfb8aa3b, v10
	v_mul_f32_e32 v7, 0xbfb8aa3b, v7
	v_exp_f32_e32 v10, v10
	v_exp_f32_e32 v11, v7
	v_fmamk_f32 v7, v50, 0x3c800000, v8
	v_mul_f32_e32 v7, 0xbfb8aa3b, v7
	v_fmac_f32_e32 v13, 0x3c800000, v55
	v_exp_f32_e32 v15, v7
	v_mul_f32_e32 v7, 0xbfb8aa3b, v13
	v_fmac_f32_e32 v9, 0x3c800000, v51
	v_exp_f32_e32 v17, v7
	v_mul_f32_e32 v7, 0xbfb8aa3b, v9
	v_pk_add_f32 v[8:9], v[10:11], 1.0 op_sel_hi:[1,0]
	v_mul_f32_e32 v6, 0xbfb8aa3b, v6
	v_exp_f32_e32 v6, v6
	v_exp_f32_e32 v7, v7
	v_rcp_f32_e32 v10, v9
	v_pk_add_f32 v[6:7], v[6:7], 1.0 op_sel_hi:[1,0]
	v_rcp_f32_e32 v11, v8
	v_pk_add_f32 v[8:9], v[16:17], 1.0 op_sel_hi:[1,0]
	s_nop 0
	v_rcp_f32_e32 v12, v8
	v_rcp_f32_e32 v13, v9
	v_pk_add_f32 v[8:9], v[14:15], 1.0 op_sel_hi:[1,0]
	s_nop 0
	v_rcp_f32_e32 v9, v9
	v_rcp_f32_e32 v8, v8
	v_rcp_f32_e32 v6, v6
	v_div_scale_f32 v14, s[8:9], v7, v7, 1.0
	v_rcp_f32_e32 v15, v14
	s_nop 0
	v_fma_f32 v16, -v14, v15, 1.0
	v_fmac_f32_e32 v15, v16, v15
	v_div_scale_f32 v16, vcc, 1.0, v7, 1.0
	v_mul_f32_e32 v17, v16, v15
	v_fma_f32 v18, -v14, v17, v16
	v_fmac_f32_e32 v17, v18, v15
	v_rcp_f32_e32 v7, v7
	s_nop 0
	v_cvt_pk_bf16_f32 v9, v9, v7
	v_cvt_pk_bf16_f32 v8, v8, v6
	v_cvt_pk_bf16_f32 v7, v10, v13
	v_cvt_pk_bf16_f32 v6, v11, v12
	global_store_dwordx4 v[4:5], v[6:9], off offset:256
	global_load_dwordx4 v[4:7], v[0:1], off offset:16
	s_nop 0
	global_load_dwordx4 v[8:11], v[0:1], off
	s_waitcnt vmcnt(1)
	v_fmamk_f32 v4, v40, 0x3c800000, v4
	v_mul_f32_e32 v4, 0xbfb8aa3b, v4
	v_exp_f32_e32 v12, v4
	s_waitcnt vmcnt(0)
; __device__ __forceinline__ unsigned pk2(float lo, float hi) { return f2bf(lo) | (f2bf(hi) << 16); }
;     __device__ __forceinline__ void operator()(const f32x4 (&acc)[2][2][4][2], const pg8::Unit& u, int wr, int wc, int fr, int fq) const {
;     ...
;                     } else if constexpr (MODE == 1) {
;                         const f32x4 b0 = *(const f32x4*)(vec + col), b1 = *(const f32x4*)(vec + col + 4);
;                         float r[8];
; #pragma unroll
;                         for (int i = 0; i < 4; ++i) { r[i] = 1.f / (1.f + __expf(-(v0[i] + b0[i]))); r[4 + i] = 1.f / (1.f + __expf(-(v1[i] + b1[i]))); }
;                         u32x4 w; w.x = pk2(r[0], r[1]); w.y = pk2(r[2], r[3]); w.z = pk2(r[4], r[5]); w.w = pk2(r[6], r[7]);
;                         *(u32x4*)(ob + row * 4096 + col) = w;
	v_fmamk_f32 v4, v45, 0x3c800000, v9
	v_mul_f32_e32 v4, 0xbfb8aa3b, v4
	v_fmamk_f32 v8, v44, 0x3c800000, v8
	v_exp_f32_e32 v14, v4
	v_fmamk_f32 v4, v41, 0x3c800000, v5
	v_fmamk_f32 v5, v46, 0x3c800000, v10
	v_mul_f32_e32 v8, 0xbfb8aa3b, v8
	v_mul_f32_e32 v5, 0xbfb8aa3b, v5
	v_exp_f32_e32 v8, v8
	v_exp_f32_e32 v9, v5
	v_fmamk_f32 v5, v42, 0x3c800000, v6
	v_mul_f32_e32 v5, 0xbfb8aa3b, v5
	v_fmac_f32_e32 v11, 0x3c800000, v47
	v_exp_f32_e32 v13, v5
	v_mul_f32_e32 v5, 0xbfb8aa3b, v11
	v_fmac_f32_e32 v7, 0x3c800000, v43
	v_exp_f32_e32 v15, v5
	v_mul_f32_e32 v5, 0xbfb8aa3b, v7
	v_pk_add_f32 v[6:7], v[8:9], 1.0 op_sel_hi:[1,0]
	v_mul_f32_e32 v4, 0xbfb8aa3b, v4
	v_exp_f32_e32 v4, v4
	v_exp_f32_e32 v5, v5
	v_rcp_f32_e32 v8, v7
	v_pk_add_f32 v[4:5], v[4:5], 1.0 op_sel_hi:[1,0]
	v_rcp_f32_e32 v9, v6
	v_pk_add_f32 v[6:7], v[14:15], 1.0 op_sel_hi:[1,0]
	s_nop 0
	v_rcp_f32_e32 v10, v6
	v_rcp_f32_e32 v11, v7
	v_pk_add_f32 v[6:7], v[12:13], 1.0 op_sel_hi:[1,0]
	s_nop 0
	v_rcp_f32_e32 v7, v7
	v_rcp_f32_e32 v6, v6
	v_rcp_f32_e32 v4, v4
	v_div_scale_f32 v12, s[8:9], v5, v5, 1.0
	v_rcp_f32_e32 v13, v12
	s_mov_b64 s[8:9], 0x160000
	v_fma_f32 v14, -v12, v13, 1.0
	v_fmac_f32_e32 v13, v14, v13
	v_div_scale_f32 v14, vcc, 1.0, v5, 1.0
	v_mul_f32_e32 v15, v14, v13
	v_fma_f32 v16, -v12, v15, v14
	v_rcp_f32_e32 v5, v5
	v_bfe_u32 v14, v11, 16, 1
	v_bfe_u32 v15, v10, 16, 1
	v_add3_u32 v10, v10, v15, s33
	v_add3_u32 v11, v11, v14, s33
	v_bfe_u32 v12, v9, 16, 1
	v_bfe_u32 v13, v8, 16, 1
	v_add3_u32 v8, v8, v13, s33
	v_add3_u32 v9, v9, v12, s33
	v_lshrrev_b32_e32 v12, 16, v9
	v_lshrrev_b32_e32 v13, 16, v8
	v_cvt_pk_bf16_f32 v9, v7, v5
	v_cvt_pk_bf16_f32 v8, v6, v4
	v_lshl_add_u64 v[4:5], v[2:3], 0, s[8:9]
	s_mov_b32 s8, 0x160000
	v_add_co_u32_e32 v2, vcc, s8, v2
	v_and_or_b32 v7, v11, s67, v13
	v_and_or_b32 v6, v10, s67, v12
	v_addc_co_u32_e32 v3, vcc, 0, v3, vcc
	global_store_dwordx4 v[2:3], v[6:9], off
	global_load_dwordx4 v[6:9], v[0:1], off offset:528
	s_nop 0
	global_load_dwordx4 v[0:3], v[0:1], off offset:512
	s_waitcnt vmcnt(1)
	v_fmac_f32_e32 v9, 0x3c800000, v35
	s_waitcnt vmcnt(0)
	v_fmamk_f32 v0, v36, 0x3c800000, v0
	v_mul_f32_e32 v0, 0xbfb8aa3b, v0
	v_exp_f32_e32 v10, v0
	v_fmamk_f32 v0, v32, 0x3c800000, v6
	v_mul_f32_e32 v0, 0xbfb8aa3b, v0
	v_exp_f32_e32 v6, v0
	v_fmamk_f32 v0, v37, 0x3c800000, v1
	v_fmamk_f32 v1, v38, 0x3c800000, v2
	v_mul_f32_e32 v1, 0xbfb8aa3b, v1
	v_exp_f32_e32 v11, v1
	v_fmamk_f32 v1, v34, 0x3c800000, v8
	v_mul_f32_e32 v0, 0xbfb8aa3b, v0
	v_mul_f32_e32 v1, 0xbfb8aa3b, v1
	v_fmac_f32_e32 v3, 0x3c800000, v39
	v_exp_f32_e32 v12, v0
	v_fmamk_f32 v0, v33, 0x3c800000, v7
	v_exp_f32_e32 v7, v1
	v_mul_f32_e32 v1, 0xbfb8aa3b, v3
	v_pk_add_f32 v[2:3], v[10:11], 1.0 op_sel_hi:[1,0]
	v_exp_f32_e32 v13, v1
	v_mul_f32_e32 v1, 0xbfb8aa3b, v9
	v_mul_f32_e32 v0, 0xbfb8aa3b, v0
	v_exp_f32_e32 v0, v0
	v_exp_f32_e32 v1, v1
	v_rcp_f32_e32 v8, v3
	v_pk_add_f32 v[0:1], v[0:1], 1.0 op_sel_hi:[1,0]
	v_rcp_f32_e32 v9, v2
	v_pk_add_f32 v[2:3], v[12:13], 1.0 op_sel_hi:[1,0]
	s_nop 0
	v_rcp_f32_e32 v10, v2
	v_rcp_f32_e32 v11, v3
	v_pk_add_f32 v[2:3], v[6:7], 1.0 op_sel_hi:[1,0]
	s_nop 0
	v_rcp_f32_e32 v3, v3
	v_rcp_f32_e32 v2, v2
	v_rcp_f32_e32 v0, v0
	v_div_scale_f32 v6, s[8:9], v1, v1, 1.0
	v_rcp_f32_e32 v7, v6
	s_nop 0
	v_fma_f32 v12, -v6, v7, 1.0
	v_fmac_f32_e32 v7, v12, v7
	v_div_scale_f32 v12, vcc, 1.0, v1, 1.0
	v_mul_f32_e32 v13, v12, v7
	v_fma_f32 v14, -v6, v13, v12
	v_fmac_f32_e32 v13, v14, v7
	v_fma_f32 v6, -v6, v13, v12
	v_div_fmas_f32 v6, v6, v7, v13
	v_rcp_f32_e32 v1, v1
	s_nop 0
	v_cvt_pk_bf16_f32 v3, v3, v1
	v_cvt_pk_bf16_f32 v2, v2, v0
	v_cvt_pk_bf16_f32 v1, v8, v11
	v_cvt_pk_bf16_f32 v0, v9, v10
	s_andn2_b64 vcc, exec, s[38:39]
	global_store_dwordx4 v[4:5], v[0:3], off offset:256
	s_cbranch_vccnz .LBB0_1114
	s_andn2_b64 vcc, exec, s[0:1]
	s_cbranch_vccnz .LBB0_1113
	s_barrier
	s_branch .LBB0_1113

; template <bool F8>
; __device__ __forceinline__ void norm_row(const float* xrow, const float* sh, const float* sc, bf16_t* hrow, unsigned char* h8row, int lane) {
;     f32x4 v[8]; float ss = 0.f;
; #pragma unroll
;     for (int j = 0; j < 8; ++j) { v[j] = ((const f32x4*)xrow)[lane + 64 * j]; ss += (v[j].x * v[j].x + v[j].y * v[j].y) + (v[j].z * v[j].z + v[j].w * v[j].w); }
;     ss = wave_sum(ss); const float r = 1.f / sqrtf(ss * (1.f / DM) + EPS);
; __global__ void __launch_bounds__(NTHREADS, 2) mega(Args a) {
;     ...
;                 for (int rep = 0; rep < REP_N; ++rep) for (int t = gw; t < SEQ; t += NGW) norm_row<true>(xin + (size_t)t * DM, md, md + DM, H + (size_t)t * DM, H8 + (size_t)t * DM, lane);
.LBB0_1159:
	global_load_dwordx4 v[28:31], v[62:63], off offset:-4096
	global_load_dwordx4 v[24:27], v[62:63], off offset:-3072
	global_load_dwordx4 v[20:23], v[62:63], off offset:-2048
	global_load_dwordx4 v[16:19], v[62:63], off offset:-1024
	global_load_dwordx4 v[12:15], v[62:63], off
	global_load_dwordx4 v[8:11], v[62:63], off offset:1024
	global_load_dwordx4 v[4:7], v[62:63], off offset:2048
	global_load_dwordx4 v[0:3], v[62:63], off offset:3072
	v_lshl_add_u64 v[64:65], s[90:91], 0, v[60:61]
	s_mov_b32 s0, 0xe300000
	v_add_co_u32_e32 v64, vcc, s0, v64
	v_lshl_add_u64 v[66:67], s[90:91], 0, v[58:59]
	s_nop 0
	v_addc_co_u32_e32 v65, vcc, 0, v65, vcc
	s_mov_b32 s0, 0x3cf00000
	v_add_co_u32_e32 v66, vcc, s0, v66
	v_mov_b32_e32 v80, 0
	s_nop 0
	v_addc_co_u32_e32 v67, vcc, 0, v67, vcc
	s_add_i32 s4, s4, s66
	v_lshl_add_u64 v[58:59], v[58:59], 0, s[6:7]
	v_lshl_add_u64 v[60:61], v[60:61], 0, s[8:9]
	v_lshl_add_u64 v[62:63], v[62:63], 0, s[10:11]
	s_cmpk_gt_i32 s4, 0x3fff
	s_waitcnt vmcnt(7)
	v_mul_f32_e32 v68, v29, v29
	v_mul_f32_e32 v72, v31, v31
	s_waitcnt vmcnt(6)
	v_mul_f32_e32 v73, v25, v25
	v_mul_f32_e32 v74, v27, v27
	s_waitcnt vmcnt(5)
	v_mul_f32_e32 v75, v21, v21
	v_mul_f32_e32 v76, v23, v23
	v_fmac_f32_e32 v68, v28, v28
	v_fmac_f32_e32 v72, v30, v30
	v_fmac_f32_e32 v73, v24, v24
	v_fmac_f32_e32 v74, v26, v26
	s_waitcnt vmcnt(4)
	v_mul_f32_e32 v77, v17, v17
	v_mul_f32_e32 v78, v19, v19
	v_fmac_f32_e32 v75, v20, v20
	v_fmac_f32_e32 v76, v22, v22
	v_add_f32_e32 v68, v68, v72
	v_add_f32_e32 v72, v73, v74
	s_waitcnt vmcnt(3)
	v_mul_f32_e32 v79, v13, v13
	v_mul_f32_e32 v81, v15, v15
	v_fmac_f32_e32 v77, v16, v16
	v_fmac_f32_e32 v78, v18, v18
	v_add_f32_e32 v73, v75, v76
	v_add_f32_e32 v68, v68, v72
	s_waitcnt vmcnt(2)
	v_mul_f32_e32 v82, v9, v9
	v_mul_f32_e32 v83, v11, v11
	v_fmac_f32_e32 v79, v12, v12
	v_fmac_f32_e32 v81, v14, v14
	v_add_f32_e32 v74, v77, v78
	v_add_f32_e32 v68, v68, v73
	s_waitcnt vmcnt(1)
	v_mul_f32_e32 v84, v5, v5
	v_mul_f32_e32 v85, v7, v7
	v_fmac_f32_e32 v82, v8, v8
	v_fmac_f32_e32 v83, v10, v10
	v_add_f32_e32 v75, v79, v81
	v_add_f32_e32 v68, v68, v74
	s_waitcnt vmcnt(0)
	v_mul_f32_e32 v86, v1, v1
	v_mul_f32_e32 v87, v3, v3
	v_fmac_f32_e32 v84, v4, v4
	v_fmac_f32_e32 v85, v6, v6
	v_add_f32_e32 v76, v82, v83
	v_add_f32_e32 v68, v68, v75
	v_fmac_f32_e32 v86, v0, v0
	v_fmac_f32_e32 v87, v2, v2
	v_add_f32_e32 v77, v84, v85
	v_add_f32_e32 v68, v68, v76
	v_add_f32_e32 v78, v86, v87
	v_add_f32_e32 v68, v68, v77
	v_add_f32_e32 v68, v68, v78
	s_nop 1
	v_add_f32_dpp v68, v68, v68 row_ror:8 row_mask:0xf bank_mask:0xf bound_ctrl:1
	s_nop 1
	v_add_f32_dpp v68, v68, v68 row_ror:4 row_mask:0xf bank_mask:0xf bound_ctrl:1
	s_nop 1
	v_add_f32_dpp v68, v68, v68 quad_perm:[2,3,0,1] row_mask:0xf bank_mask:0xf bound_ctrl:1
	s_nop 1
	v_add_f32_dpp v68, v68, v68 quad_perm:[1,0,3,2] row_mask:0xf bank_mask:0xf bound_ctrl:1
	v_mov_b32_e32 v72, v68
	s_nop 1
	v_permlane16_swap_b32_e32 v68, v72
	s_nop 0
	v_add_f32_e32 v68, v68, v72
	v_mov_b32_e32 v81, v68
	s_nop 1
	v_permlane32_swap_b32_e32 v68, v81
	global_load_dwordx4 v[72:75], v[32:33], off
	global_load_dwordx4 v[76:79], v[34:35], off
	v_add_f32_e32 v68, v68, v81
	v_fmamk_f32 v68, v68, 0x3a000000, v205
	v_mul_f32_e32 v81, 0x4f800000, v68
	v_cmp_gt_f32_e32 vcc, s5, v68
	s_waitcnt vmcnt(1)
	v_pk_add_f32 v[72:73], v[72:73], 1.0 op_sel_hi:[1,0]
	v_cndmask_b32_e32 v68, v68, v81, vcc
	v_sqrt_f32_e32 v81, v68
	v_pk_add_f32 v[74:75], v[74:75], 1.0 op_sel_hi:[1,0]
	v_add_u32_e32 v82, -1, v81
	v_add_u32_e32 v83, 1, v81
	v_fma_f32 v84, -v82, v81, v68
	v_fma_f32 v85, -v83, v81, v68
	v_cmp_ge_f32_e64 s[0:1], 0, v84
	s_nop 1
	v_cndmask_b32_e64 v81, v81, v82, s[0:1]
	v_cmp_lt_f32_e64 s[0:1], 0, v85
	s_nop 1
	v_cndmask_b32_e64 v81, v81, v83, s[0:1]
	v_mul_f32_e32 v82, 0x37800000, v81
	v_cndmask_b32_e32 v81, v81, v82, vcc
	v_cmp_class_f32_e32 vcc, v68, v206
	s_nop 1
	v_cndmask_b32_e32 v68, v81, v68, vcc
	v_div_scale_f32 v81, s[0:1], v68, v68, 1.0
	v_rcp_f32_e32 v83, v81
	v_div_scale_f32 v82, vcc, 1.0, v68, 1.0
	v_fma_f32 v84, -v81, v83, 1.0
	v_fmac_f32_e32 v83, v84, v83
	v_mul_f32_e32 v84, v82, v83
	v_fma_f32 v85, -v81, v84, v82
	v_fmac_f32_e32 v84, v85, v83
	v_fma_f32 v81, -v81, v84, v82
	v_div_fmas_f32 v81, v81, v83, v84
	v_div_fixup_f32 v68, v81, v68, 1.0
	v_pk_mul_f32 v[28:29], v[28:29], v[68:69] op_sel_hi:[1,0]
	v_pk_mul_f32 v[30:31], v[30:31], v[68:69] op_sel_hi:[1,0]
	s_waitcnt vmcnt(0)
; __device__ __forceinline__ unsigned pk2(float lo, float hi) { return f2bf(lo) | (f2bf(hi) << 16); }
; template <bool F8>
; __device__ __forceinline__ void norm_row(const float* xrow, const float* sh, const float* sc, bf16_t* hrow, unsigned char* h8row, int lane) {
;     ...
;     for (int j = 0; j < 8; ++j) { const f32x4 s4 = ((const f32x4*)sc)[lane + 64 * j], h4 = ((const f32x4*)sh)[lane + 64 * j];
;         const f32x4 y = v[j] * r * (s4 + 1.f) + h4; u32x2 o; o.x = pk2(y.x, y.y); o.y = pk2(y.z, y.w); ((u32x2*)hrow)[lane + 64 * j] = o;
;         if constexpr (F8) { int t0 = __builtin_amdgcn_cvt_pk_fp8_f32(y.x, y.y, 0, false); t0 = __builtin_amdgcn_cvt_pk_fp8_f32(y.z, y.w, t0, true); ((unsigned*)h8row)[lane + 64 * j] = (unsigned)t0; } }
	v_pk_fma_f32 v[28:29], v[72:73], v[28:29], v[76:77]
	v_pk_fma_f32 v[30:31], v[74:75], v[30:31], v[78:79]
	v_cvt_pk_fp8_f32 v80, v28, v29
	v_cvt_pk_bf16_f32 v28, v28, v29
	v_cvt_pk_fp8_f32 v80, v30, v31 op_sel:[0,0,1]
	v_cvt_pk_bf16_f32 v29, v30, v31
	global_store_dwordx2 v[64:65], v[28:29], off
	global_store_dword v[66:67], v80, off
	global_load_dwordx4 v[28:31], v[36:37], off
	s_nop 0
	global_load_dwordx4 v[72:75], v[34:35], off offset:1024
	v_pk_mul_f32 v[24:25], v[24:25], v[68:69] op_sel_hi:[1,0]
	v_mov_b32_e32 v76, 0
	v_pk_mul_f32 v[26:27], v[26:27], v[68:69] op_sel_hi:[1,0]
	v_pk_mul_f32 v[20:21], v[20:21], v[68:69] op_sel_hi:[1,0]
	v_pk_mul_f32 v[22:23], v[22:23], v[68:69] op_sel_hi:[1,0]
	v_pk_mul_f32 v[16:17], v[16:17], v[68:69] op_sel_hi:[1,0]
	v_pk_mul_f32 v[18:19], v[18:19], v[68:69] op_sel_hi:[1,0]
	v_pk_mul_f32 v[12:13], v[12:13], v[68:69] op_sel_hi:[1,0]
	v_pk_mul_f32 v[14:15], v[14:15], v[68:69] op_sel_hi:[1,0]
	v_pk_mul_f32 v[8:9], v[8:9], v[68:69] op_sel_hi:[1,0]
	v_pk_mul_f32 v[10:11], v[10:11], v[68:69] op_sel_hi:[1,0]
	v_pk_mul_f32 v[4:5], v[4:5], v[68:69] op_sel_hi:[1,0]
	v_pk_mul_f32 v[6:7], v[6:7], v[68:69] op_sel_hi:[1,0]
	v_pk_mul_f32 v[0:1], v[0:1], v[68:69] op_sel_hi:[1,0]
	v_pk_mul_f32 v[2:3], v[2:3], v[68:69] op_sel_hi:[1,0]
	s_waitcnt vmcnt(1)
	v_pk_add_f32 v[28:29], v[28:29], 1.0 op_sel_hi:[1,0]
	s_waitcnt vmcnt(0)
	v_pk_fma_f32 v[24:25], v[28:29], v[24:25], v[72:73]
	v_pk_add_f32 v[30:31], v[30:31], 1.0 op_sel_hi:[1,0]
	v_cvt_pk_fp8_f32 v76, v24, v25
	v_pk_fma_f32 v[26:27], v[30:31], v[26:27], v[74:75]
	v_cvt_pk_bf16_f32 v24, v24, v25
	v_cvt_pk_fp8_f32 v76, v26, v27 op_sel:[0,0,1]
	v_cvt_pk_bf16_f32 v25, v26, v27
	global_store_dwordx2 v[64:65], v[24:25], off offset:512
	global_store_dword v[66:67], v76, off offset:256
	global_load_dwordx4 v[24:27], v[38:39], off
	s_nop 0
	global_load_dwordx4 v[28:31], v[34:35], off offset:2048
	v_mov_b32_e32 v72, 0
	s_waitcnt vmcnt(1)
	v_pk_add_f32 v[24:25], v[24:25], 1.0 op_sel_hi:[1,0]
	s_waitcnt vmcnt(0)
	v_pk_fma_f32 v[20:21], v[20:21], v[24:25], v[28:29]
	v_pk_add_f32 v[26:27], v[26:27], 1.0 op_sel_hi:[1,0]
	v_cvt_pk_fp8_f32 v72, v20, v21
	v_pk_fma_f32 v[22:23], v[22:23], v[26:27], v[30:31]
	v_cvt_pk_bf16_f32 v20, v20, v21
	v_cvt_pk_fp8_f32 v72, v22, v23 op_sel:[0,0,1]
	v_cvt_pk_bf16_f32 v21, v22, v23
	global_store_dwordx2 v[64:65], v[20:21], off offset:1024
	global_store_dword v[66:67], v72, off offset:512
	global_load_dwordx4 v[20:23], v[40:41], off
	s_nop 0
	global_load_dwordx4 v[24:27], v[34:35], off offset:3072
	v_mov_b32_e32 v28, 0
	s_waitcnt vmcnt(1)
	v_pk_add_f32 v[20:21], v[20:21], 1.0 op_sel_hi:[1,0]
	s_waitcnt vmcnt(0)
	v_pk_fma_f32 v[16:17], v[16:17], v[20:21], v[24:25]
	v_pk_add_f32 v[22:23], v[22:23], 1.0 op_sel_hi:[1,0]
	v_cvt_pk_fp8_f32 v28, v16, v17
	v_pk_fma_f32 v[18:19], v[18:19], v[22:23], v[26:27]
	v_cvt_pk_bf16_f32 v16, v16, v17
	v_cvt_pk_fp8_f32 v28, v18, v19 op_sel:[0,0,1]
	v_cvt_pk_bf16_f32 v17, v18, v19
	global_store_dwordx2 v[64:65], v[16:17], off offset:1536
	global_store_dword v[66:67], v28, off offset:768
	global_load_dwordx4 v[16:19], v[42:43], off
	s_nop 0
	global_load_dwordx4 v[20:23], v[44:45], off
	v_mov_b32_e32 v24, 0
	s_waitcnt vmcnt(1)
	v_pk_add_f32 v[16:17], v[16:17], 1.0 op_sel_hi:[1,0]
	s_waitcnt vmcnt(0)
	v_pk_fma_f32 v[12:13], v[12:13], v[16:17], v[20:21]
	v_pk_add_f32 v[18:19], v[18:19], 1.0 op_sel_hi:[1,0]
	v_cvt_pk_fp8_f32 v24, v12, v13
	v_pk_fma_f32 v[14:15], v[14:15], v[18:19], v[22:23]
	v_cvt_pk_bf16_f32 v12, v12, v13
	v_cvt_pk_fp8_f32 v24, v14, v15 op_sel:[0,0,1]
	v_cvt_pk_bf16_f32 v13, v14, v15
	global_store_dwordx2 v[64:65], v[12:13], off offset:2048
	global_store_dword v[66:67], v24, off offset:1024
	global_load_dwordx4 v[12:15], v[46:47], off
	s_nop 0
	global_load_dwordx4 v[16:19], v[48:49], off
	v_mov_b32_e32 v20, 0
	s_waitcnt vmcnt(1)
	v_pk_add_f32 v[12:13], v[12:13], 1.0 op_sel_hi:[1,0]
	s_waitcnt vmcnt(0)
	v_pk_fma_f32 v[8:9], v[8:9], v[12:13], v[16:17]
	v_pk_add_f32 v[14:15], v[14:15], 1.0 op_sel_hi:[1,0]
	v_cvt_pk_fp8_f32 v20, v8, v9
	v_pk_fma_f32 v[10:11], v[10:11], v[14:15], v[18:19]
	v_cvt_pk_bf16_f32 v8, v8, v9
	v_cvt_pk_fp8_f32 v20, v10, v11 op_sel:[0,0,1]
	v_cvt_pk_bf16_f32 v9, v10, v11
	global_store_dwordx2 v[64:65], v[8:9], off offset:2560
	global_store_dword v[66:67], v20, off offset:1280
	global_load_dwordx4 v[8:11], v[50:51], off
	s_nop 0
	global_load_dwordx4 v[12:15], v[52:53], off
	v_mov_b32_e32 v16, 0
	s_waitcnt vmcnt(1)
	v_pk_add_f32 v[8:9], v[8:9], 1.0 op_sel_hi:[1,0]
	s_waitcnt vmcnt(0)
	v_pk_fma_f32 v[4:5], v[4:5], v[8:9], v[12:13]
	v_pk_add_f32 v[10:11], v[10:11], 1.0 op_sel_hi:[1,0]
	v_cvt_pk_fp8_f32 v16, v4, v5
	v_pk_fma_f32 v[6:7], v[6:7], v[10:11], v[14:15]
	v_cvt_pk_bf16_f32 v4, v4, v5
	v_cvt_pk_fp8_f32 v16, v6, v7 op_sel:[0,0,1]
	v_cvt_pk_bf16_f32 v5, v6, v7
	global_store_dwordx2 v[64:65], v[4:5], off offset:3072
	global_store_dword v[66:67], v16, off offset:1536
	global_load_dwordx4 v[4:7], v[54:55], off
	s_nop 0
	global_load_dwordx4 v[8:11], v[56:57], off
	v_mov_b32_e32 v12, 0
	s_waitcnt vmcnt(1)
	v_pk_add_f32 v[4:5], v[4:5], 1.0 op_sel_hi:[1,0]
	s_waitcnt vmcnt(0)
	v_pk_fma_f32 v[0:1], v[0:1], v[4:5], v[8:9]
	v_pk_add_f32 v[6:7], v[6:7], 1.0 op_sel_hi:[1,0]
	v_cvt_pk_fp8_f32 v12, v0, v1
	v_pk_fma_f32 v[2:3], v[2:3], v[6:7], v[10:11]
	v_cvt_pk_bf16_f32 v0, v0, v1
	v_cvt_pk_fp8_f32 v12, v2, v3 op_sel:[0,0,1]
	v_cvt_pk_bf16_f32 v1, v2, v3
	global_store_dwordx2 v[64:65], v[0:1], off offset:3584
	global_store_dword v[66:67], v12, off offset:1792
	s_cbranch_scc0 .LBB0_1159
